# v29_staticprio
# speedup vs baseline: 1.0130x; 1.0130x over previous
; __device__ __forceinline__ void xcd_barrier(const XcdBarrier& b) {
;     asm volatile("s_waitcnt vmcnt(0)" ::: "memory");
;     __syncthreads();
;     if (threadIdx.x == 0) {
;         unsigned* bar = b.bar;
;         __builtin_amdgcn_s_waitcnt(0);
;         unsigned nloc = b.st[0], nx = b.st[1];
;         if (nloc == 0u) { xcd_barrier_complete(bar, b.x, nloc, nx); b.st[0] = nloc; b.st[1] = nx; }
.LBB0_42:
	s_cmp_gt_i32 s97, 1
	s_cselect_b64 s[4:5], -1, 0
	s_and_b64 s[6:7], s[28:29], s[4:5]
	s_andn2_b64 vcc, exec, s[6:7]
	s_cbranch_vccnz .LBB0_96
	s_waitcnt vmcnt(0)
	s_setprio 0
	s_barrier
	s_and_saveexec_b64 s[6:7], s[88:89]
	s_cbranch_execz .LBB0_95
	s_add_i32 s3, 0, 0x25fc0
	v_mov_b32_e32 v0, s3
	s_waitcnt vmcnt(0) expcnt(0) lgkmcnt(0)
	ds_read_b32 v2, v0
	s_add_i32 s3, 0, 0x25fc4
	v_mov_b32_e32 v0, s3
	ds_read_b32 v0, v0
	s_waitcnt lgkmcnt(1)
	v_cmp_ne_u32_e32 vcc, 0, v2
	s_cbranch_vccnz .LBB0_59
	s_add_u32 s10, s58, 0x1000
	s_load_dwordx2 s[8:9], s[0:1], 0xe8
	s_load_dword s3, s[0:1], 0xf0
	s_addc_u32 s11, s59, 0
	s_add_u32 s14, s58, 0x1100
	s_addc_u32 s15, s59, 0
	s_add_u32 s16, s58, 0x1200
	s_addc_u32 s17, s59, 0
	s_waitcnt lgkmcnt(0)
	s_mul_i32 s3, s9, s3
	s_add_u32 s18, s58, 0x1300
	s_mul_i32 s3, s3, s8
	s_addc_u32 s19, s59, 0
	s_mov_b32 s8, 1
	v_mov_b32_e32 v16, 0
	s_branch .LBB0_47

; #define PG8_STAGE(bufoff, gbase, voff) do { const __amdgpu_buffer_rsrc_t _rs = __builtin_amdgcn_make_buffer_rsrc((void*)(gbase), 0, 0x7fffffff, 0x00020000); _Pragma("unroll") for (int _i = 0; _i < 2; ++_i) \
;         __builtin_amdgcn_raw_ptr_buffer_load_lds(_rs, (LAS unsigned*)(lds + (bufoff) + ldsw + _i * 8192), 16, (int)(voff)[_i], 0, 0, 0); } while (0)
; #define PG8_BAR __builtin_amdgcn_s_barrier()
; template <class Epi, class Sched, bool F8 = false>
; __device__ __forceinline__ void gemm_phase(LAS unsigned char* lds, const int lda, const int ldb, const Sched& S, const Epi& E) {
;     ...
;     for (int i = 0; i < 2; ++i) { int R, C; stage_rc(tid * 16 + i * 8192, R, C); const int Rb = Epi::PERM ? ((R & ~31) + perm32(R & 31)) : R;
;         voffA[i] = (unsigned)(R * lda + C * 2); voffB[i] = (unsigned)(Rb * 128 + C * 2); }
;     const size_t kstep = (size_t)(BK * 2), kstepB = 32768;
;     const size_t hstepA = (size_t)HALF * lda, hstepB = 16384; (void)ldb;
;     const unsigned ldsw = (unsigned)wid * 1024u;
;     const int aoff = lds_byte(wr * 64 + fr, fq * 8), boff = lds_byte(wc * 32 + fr, fq * 8);
;     ...
;     PG8_STAGE(PG8_SB(0, 0), cB, voffB); PG8_STAGE(PG8_SB(0, 1), cB + hstepB, voffB); PG8_STAGE(PG8_SA(0, 0), cA, voffA); PG8_STAGE(PG8_SA(0, 1), cA + hstepA, voffA);
;     if (wr == 1) PG8_BAR;
.LBB0_104:
	v_bfe_i32 v3, v0, 27, 1
	v_lshlrev_b32_e32 v1, 4, v0
	v_lshrrev_b32_e32 v3, 22, v3
	v_add_u32_e32 v3, v1, v3
	v_and_b32_e32 v3, 0xfffffc00, v3
	v_sub_u32_e32 v3, v1, v3
	v_ashrrev_i32_e32 v2, 31, v0
	v_lshrrev_b32_e32 v4, 4, v3
	v_lshrrev_b32_e32 v2, 26, v2
	v_bitop3_b32 v3, v4, v3, 32 bitop3:0x6c
	v_add_u32_e32 v2, v0, v2
	v_ashrrev_i32_e32 v5, 31, v3
	v_ashrrev_i32_e32 v2, 6, v2
	v_lshrrev_b32_e32 v5, 26, v5
	v_lshlrev_b32_e32 v4, 3, v2
	v_add_u32_e32 v5, v3, v5
	v_and_b32_e32 v4, -16, v4
	v_ashrrev_i32_e32 v6, 6, v5
	v_and_b32_e32 v5, 0xc0, v5
	v_add_u32_e32 v4, v6, v4
	v_sub_u32_e32 v3, v3, v5
	v_mov_b32_e32 v5, 1
	v_lshlrev_b32_e32 v2, 5, v2
	v_ashrrev_i16_sdwa v3, v5, sext(v3) dst_sel:DWORD dst_unused:UNUSED_PAD src0_sel:DWORD src1_sel:BYTE_0
	v_lshlrev_b32_e32 v7, 1, v4
	v_lshrrev_b32_e32 v8, 2, v4
	v_and_b32_e32 v6, 3, v6
	s_mov_b32 s3, 0x1ffffe0
	v_and_b32_e32 v2, 32, v2
	v_bfe_i32 v3, v3, 0, 16
	v_and_b32_e32 v7, 24, v7
	v_and_b32_e32 v8, 4, v8
	v_and_or_b32 v6, v4, s3, v6
	v_or3_b32 v6, v6, v8, v7
	v_add_lshl_u32 v2, v2, v3, 1
	v_add_u32_e32 v1, 0x2000, v1
	v_lshl_add_u32 v136, v4, 13, v2
	v_lshl_add_u32 v137, v6, 7, v2
	v_ashrrev_i32_e32 v2, 31, v1
	v_lshrrev_b32_e32 v2, 22, v2
	v_add_u32_e32 v2, v1, v2
	v_ashrrev_i32_e32 v2, 10, v2
	v_mul_i32_i24_e32 v3, 0x400, v2
	v_sub_u32_e32 v1, v1, v3
	v_lshrrev_b32_e32 v3, 4, v1
	v_bitop3_b32 v1, v3, v1, 32 bitop3:0x6c
	v_ashrrev_i32_e32 v4, 31, v1
	v_lshrrev_b32_e32 v4, 26, v4
	v_lshlrev_b32_e32 v3, 3, v2
	v_add_u32_e32 v4, v1, v4
	v_and_b32_e32 v3, -16, v3
	v_ashrrev_i32_e32 v6, 6, v4
	v_add_u32_e32 v3, v6, v3
	v_and_b32_e32 v4, 0xc0, v4
	v_and_b32_e32 v6, 3, v6
	s_ashr_i32 s5, s24, 6
	v_sub_u32_e32 v1, v1, v4
	v_and_or_b32 v6, v3, s3, v6
	s_lshl_b32 s3, s5, 10
	v_lshlrev_b32_e32 v2, 5, v2
	v_ashrrev_i16_sdwa v1, v5, sext(v1) dst_sel:DWORD dst_unused:UNUSED_PAD src0_sel:DWORD src1_sel:BYTE_0
	v_lshlrev_b32_e32 v4, 1, v3
	v_lshrrev_b32_e32 v5, 2, v3
	s_add_i32 s3, s3, 0
	v_and_b32_e32 v2, 32, v2
	v_bfe_i32 v1, v1, 0, 16
	v_and_b32_e32 v4, 24, v4
	v_and_b32_e32 v5, 4, v5
	s_add_i32 s8, s3, 0x10000
	v_or3_b32 v4, v6, v5, v4
	v_add_lshl_u32 v1, v2, v1, 1
	s_and_b32 s17, s23, 0xffff
	s_mov_b32 s19, 0x20000
	s_brev_b32 s18, -2
	s_mov_b32 s16, s22
	s_mov_b32 m0, s8
	s_add_i32 s9, s3, 0x12000
	s_ashr_i32 s4, s24, 8
	v_lshl_add_u32 v139, v4, 7, v1
	buffer_load_dwordx4 v137, s[16:19], 0 offen lds
	s_mov_b32 m0, s9
	v_lshl_add_u32 v138, v3, 13, v1
	buffer_load_dwordx4 v139, s[16:19], 0 offen lds
	s_add_u32 s16, s22, 0x4000
	s_addc_u32 s7, s23, 0
	s_add_i32 s76, s3, 0x14000
	s_and_b32 s17, s7, 0xffff
	s_mov_b32 m0, s76
	s_add_i32 s79, s3, 0x16000
	buffer_load_dwordx4 v137, s[16:19], 0 offen lds
	s_mov_b32 m0, s79
	s_add_i32 s80, s3, 0x2000
	buffer_load_dwordx4 v139, s[16:19], 0 offen lds
	s_and_b32 s17, s21, 0xffff
	s_mov_b32 s16, s20
	s_mov_b32 m0, s3
	s_mov_b32 s83, 0
	buffer_load_dwordx4 v136, s[16:19], 0 offen lds
	s_mov_b32 m0, s80
	s_movk_i32 s84, 0x6000
	buffer_load_dwordx4 v138, s[16:19], 0 offen lds
	s_add_u32 s16, s20, 0x100000
	s_addc_u32 s7, s21, 0
	s_add_i32 s81, s3, 0x4000
	s_and_b32 s17, s7, 0xffff
	s_mov_b32 m0, s81
	s_add_i32 s82, s3, 0x6000
	buffer_load_dwordx4 v136, s[16:19], 0 offen lds
	s_mov_b32 m0, s82
	s_cmp_eq_u32 s4, 1
	buffer_load_dwordx4 v138, s[16:19], 0 offen lds
	s_cselect_b64 s[36:37], -1, 0
	s_cmp_lg_u32 s4, 1
	s_cbranch_scc1 .LBB0_106
	s_setprio 1
	s_barrier

; #define PG8_STAGE(bufoff, gbase, voff) do { const __amdgpu_buffer_rsrc_t _rs = __builtin_amdgcn_make_buffer_rsrc((void*)(gbase), 0, 0x7fffffff, 0x00020000); _Pragma("unroll") for (int _i = 0; _i < 2; ++_i) \
;         __builtin_amdgcn_raw_ptr_buffer_load_lds(_rs, (LAS unsigned*)(lds + (bufoff) + ldsw + _i * 8192), 16, (int)(voff)[_i], 0, 0, 0); } while (0)
; #define PG8_WAIT_V(n) asm volatile("s_waitcnt vmcnt(" #n ")" ::: "memory")
; #define PG8_WAIT_L(n) asm volatile("s_waitcnt lgkmcnt(" #n ")" ::: "memory")
; #define PG8_BAR __builtin_amdgcn_s_barrier()
; #define PG8_SCHED __builtin_amdgcn_sched_barrier(0)
; template <class Epi, class Sched, bool F8 = false>
; __device__ __forceinline__ void gemm_phase(LAS unsigned char* lds, const int lda, const int ldb, const Sched& S, const Epi& E) {
;     ...
;             PG8_LDB(B0, 0, 0); PG8_LDB(B1, 0, 1); PG8_SCHED; PG8_LDA(At, 0, 0); PG8_STAGE(PG8_SA(1, 1), a1 + hstepA, voffA);
;             PG8_WAIT_V(8); PG8_WAIT_L(0); PG8_BAR; PG8_MMA(0, 0, At, B0); PG8_MMA(0, 1, At, B1); PG8_BAR; PG8_SCHED;
;             PG8_LDA(At, 0, 1); PG8_STAGE(PG8_SB(0, 0), b2, voffB); PG8_STAGE(PG8_SB(0, 1), b2 + hstepB, voffB); PG8_STAGE(PG8_SA(0, 0), a2, voffA);
;             PG8_WAIT_V(8); PG8_WAIT_L(0); PG8_BAR; PG8_MMA(1, 0, At, B0); PG8_MMA(1, 1, At, B1); PG8_BAR; PG8_SCHED;
.LBB0_116:
	ds_read_b128 v[132:135], v140
	ds_read_b128 v[146:149], v140 offset:1024
	ds_read_b128 v[150:153], v140 offset:2048
	ds_read_b128 v[154:157], v140 offset:3072
	ds_read_b128 v[158:161], v141
	ds_read_b128 v[162:165], v141 offset:1024
	ds_read_b128 v[166:169], v141 offset:2048
	ds_read_b128 v[174:177], v141 offset:3072
	s_add_u32 s16, s63, 0xfff00080
	s_addc_u32 s17, s67, -1
	s_cmp_eq_u32 s69, 60
	s_cselect_b32 s28, s70, s16
	s_cselect_b32 s23, s71, s17
	s_cselect_b32 s22, s73, s62
	s_cselect_b32 s24, s72, s7
	s_add_u32 s20, s28, 0x80
	s_addc_u32 s21, s23, 0
	s_and_b32 s17, s67, 0xffff
	s_mov_b32 s16, s63
	s_mov_b32 m0, s93
	ds_read_b128 v[178:181], v142
	ds_read_b128 v[182:185], v142 offset:1024
	ds_read_b128 v[186:189], v142 offset:2048
	ds_read_b128 v[190:193], v142 offset:3072
	ds_read_b128 v[194:197], v142 offset:4096
	ds_read_b128 v[198:201], v142 offset:5120
	ds_read_b128 v[202:205], v142 offset:6144
	ds_read_b128 v[206:209], v142 offset:7168
	buffer_load_dwordx4 v136, s[16:19], 0 offen lds
	s_mov_b32 m0, s94
	s_nop 0
	buffer_load_dwordx4 v138, s[16:19], 0 offen lds
	s_waitcnt vmcnt(8)
	s_waitcnt lgkmcnt(0)
	s_barrier
	v_mfma_f32_16x16x32_bf16 v[124:127], v[132:135], v[178:181], v[124:127]
	v_mfma_f32_16x16x32_bf16 v[120:123], v[150:153], v[178:181], v[120:123]
	v_mfma_f32_16x16x32_bf16 v[108:111], v[132:135], v[186:189], v[108:111]
	v_mfma_f32_16x16x32_bf16 v[104:107], v[150:153], v[186:189], v[104:107]
	v_mfma_f32_16x16x32_bf16 v[92:95], v[132:135], v[194:197], v[92:95]
	v_mfma_f32_16x16x32_bf16 v[88:91], v[150:153], v[194:197], v[88:91]
	v_mfma_f32_16x16x32_bf16 v[76:79], v[132:135], v[202:205], v[76:79]
	v_mfma_f32_16x16x32_bf16 v[72:75], v[150:153], v[202:205], v[72:75]
	v_mfma_f32_16x16x32_bf16 v[124:127], v[146:149], v[182:185], v[124:127]
	v_mfma_f32_16x16x32_bf16 v[120:123], v[154:157], v[182:185], v[120:123]
	v_mfma_f32_16x16x32_bf16 v[108:111], v[146:149], v[190:193], v[108:111]
	v_mfma_f32_16x16x32_bf16 v[104:107], v[154:157], v[190:193], v[104:107]
	v_mfma_f32_16x16x32_bf16 v[92:95], v[146:149], v[198:201], v[92:95]
	v_mfma_f32_16x16x32_bf16 v[88:91], v[154:157], v[198:201], v[88:91]
	v_mfma_f32_16x16x32_bf16 v[76:79], v[146:149], v[206:209], v[76:79]
	v_mfma_f32_16x16x32_bf16 v[72:75], v[154:157], v[206:209], v[72:75]
	v_mfma_f32_16x16x32_bf16 v[116:119], v[158:161], v[178:181], v[116:119]
	v_mfma_f32_16x16x32_bf16 v[112:115], v[166:169], v[178:181], v[112:115]
	v_mfma_f32_16x16x32_bf16 v[100:103], v[158:161], v[186:189], v[100:103]
	v_mfma_f32_16x16x32_bf16 v[96:99], v[166:169], v[186:189], v[96:99]
	v_mfma_f32_16x16x32_bf16 v[84:87], v[158:161], v[194:197], v[84:87]
	v_mfma_f32_16x16x32_bf16 v[80:83], v[166:169], v[194:197], v[80:83]
	v_mfma_f32_16x16x32_bf16 v[68:71], v[158:161], v[202:205], v[68:71]
	v_mfma_f32_16x16x32_bf16 v[64:67], v[166:169], v[202:205], v[64:67]
	v_mfma_f32_16x16x32_bf16 v[116:119], v[162:165], v[182:185], v[116:119]
	v_mfma_f32_16x16x32_bf16 v[112:115], v[174:177], v[182:185], v[112:115]
	v_mfma_f32_16x16x32_bf16 v[100:103], v[162:165], v[190:193], v[100:103]
	v_mfma_f32_16x16x32_bf16 v[96:99], v[174:177], v[190:193], v[96:99]
	v_mfma_f32_16x16x32_bf16 v[84:87], v[162:165], v[198:201], v[84:87]
	v_mfma_f32_16x16x32_bf16 v[80:83], v[174:177], v[198:201], v[80:83]
	v_mfma_f32_16x16x32_bf16 v[68:71], v[162:165], v[206:209], v[68:71]
	v_mfma_f32_16x16x32_bf16 v[64:67], v[174:177], v[206:209], v[64:67]
	s_barrier
	s_and_b32 s25, s22, 0xffff
	s_mov_b32 m0, s8
	s_mov_b32 s26, s18
	s_mov_b32 s27, s19
	s_add_u32 s16, s24, 0x4000
	ds_read_b128 v[178:181], v142 offset:16384
	ds_read_b128 v[182:185], v142 offset:17408
	ds_read_b128 v[186:189], v142 offset:18432
	ds_read_b128 v[190:193], v142 offset:19456
	ds_read_b128 v[194:197], v142 offset:20480
	ds_read_b128 v[198:201], v142 offset:21504
	ds_read_b128 v[202:205], v142 offset:22528
	ds_read_b128 v[206:209], v142 offset:23552
	buffer_load_dwordx4 v137, s[24:27], 0 offen lds
	s_mov_b32 m0, s9
	s_addc_u32 s17, s22, 0
	buffer_load_dwordx4 v139, s[24:27], 0 offen lds
	s_and_b32 s17, s17, 0xffff
	s_mov_b32 m0, s76
	s_and_b32 s29, s23, 0xffff
	buffer_load_dwordx4 v137, s[16:19], 0 offen lds
	s_mov_b32 m0, s79
	s_mov_b32 s30, s18
	buffer_load_dwordx4 v139, s[16:19], 0 offen lds
	s_mov_b32 s31, s19
	s_mov_b32 m0, s3
	s_nop 0
	buffer_load_dwordx4 v136, s[28:31], 0 offen lds
	s_mov_b32 m0, s80
	s_nop 0
	buffer_load_dwordx4 v138, s[28:31], 0 offen lds
	s_waitcnt vmcnt(8)
	s_waitcnt lgkmcnt(0)
	s_barrier
	v_mfma_f32_16x16x32_bf16 v[60:63], v[132:135], v[178:181], v[60:63]
	v_mfma_f32_16x16x32_bf16 v[56:59], v[150:153], v[178:181], v[56:59]
	v_mfma_f32_16x16x32_bf16 v[44:47], v[132:135], v[186:189], v[44:47]
	v_mfma_f32_16x16x32_bf16 v[40:43], v[150:153], v[186:189], v[40:43]
	v_mfma_f32_16x16x32_bf16 v[28:31], v[132:135], v[194:197], v[28:31]
	v_mfma_f32_16x16x32_bf16 v[24:27], v[150:153], v[194:197], v[24:27]
	v_mfma_f32_16x16x32_bf16 v[12:15], v[132:135], v[202:205], v[12:15]
	v_mfma_f32_16x16x32_bf16 v[8:11], v[150:153], v[202:205], v[8:11]
	v_mfma_f32_16x16x32_bf16 v[60:63], v[146:149], v[182:185], v[60:63]
	v_mfma_f32_16x16x32_bf16 v[56:59], v[154:157], v[182:185], v[56:59]
	v_mfma_f32_16x16x32_bf16 v[44:47], v[146:149], v[190:193], v[44:47]
	v_mfma_f32_16x16x32_bf16 v[40:43], v[154:157], v[190:193], v[40:43]
	v_mfma_f32_16x16x32_bf16 v[28:31], v[146:149], v[198:201], v[28:31]
	v_mfma_f32_16x16x32_bf16 v[24:27], v[154:157], v[198:201], v[24:27]
	v_mfma_f32_16x16x32_bf16 v[12:15], v[146:149], v[206:209], v[12:15]
	v_mfma_f32_16x16x32_bf16 v[8:11], v[154:157], v[206:209], v[8:11]
	v_mfma_f32_16x16x32_bf16 v[52:55], v[158:161], v[178:181], v[52:55]
	v_mfma_f32_16x16x32_bf16 v[48:51], v[166:169], v[178:181], v[48:51]
	v_mfma_f32_16x16x32_bf16 v[36:39], v[158:161], v[186:189], v[36:39]
	v_mfma_f32_16x16x32_bf16 v[32:35], v[166:169], v[186:189], v[32:35]
	v_mfma_f32_16x16x32_bf16 v[20:23], v[158:161], v[194:197], v[20:23]
	v_mfma_f32_16x16x32_bf16 v[16:19], v[166:169], v[194:197], v[16:19]
	v_mfma_f32_16x16x32_bf16 v[4:7], v[158:161], v[202:205], v[4:7]
	v_mfma_f32_16x16x32_bf16 v[0:3], v[166:169], v[202:205], v[0:3]
	v_mfma_f32_16x16x32_bf16 v[52:55], v[162:165], v[182:185], v[52:55]
	v_mfma_f32_16x16x32_bf16 v[48:51], v[174:177], v[182:185], v[48:51]
	v_mfma_f32_16x16x32_bf16 v[36:39], v[162:165], v[190:193], v[36:39]
	v_mfma_f32_16x16x32_bf16 v[32:35], v[174:177], v[190:193], v[32:35]
	v_mfma_f32_16x16x32_bf16 v[20:23], v[162:165], v[198:201], v[20:23]
	v_mfma_f32_16x16x32_bf16 v[16:19], v[174:177], v[198:201], v[16:19]
	v_mfma_f32_16x16x32_bf16 v[4:7], v[162:165], v[206:209], v[4:7]
	v_mfma_f32_16x16x32_bf16 v[0:3], v[174:177], v[206:209], v[0:3]
	s_barrier
; #define PG8_STAGE(bufoff, gbase, voff) do { const __amdgpu_buffer_rsrc_t _rs = __builtin_amdgcn_make_buffer_rsrc((void*)(gbase), 0, 0x7fffffff, 0x00020000); _Pragma("unroll") for (int _i = 0; _i < 2; ++_i) \
;         __builtin_amdgcn_raw_ptr_buffer_load_lds(_rs, (LAS unsigned*)(lds + (bufoff) + ldsw + _i * 8192), 16, (int)(voff)[_i], 0, 0, 0); } while (0)
; #define PG8_WAIT_V(n) asm volatile("s_waitcnt vmcnt(" #n ")" ::: "memory")
; #define PG8_WAIT_L(n) asm volatile("s_waitcnt lgkmcnt(" #n ")" ::: "memory")
; #define PG8_BAR __builtin_amdgcn_s_barrier()
; #define PG8_SCHED __builtin_amdgcn_sched_barrier(0)
; template <class Epi, class Sched, bool F8 = false>
; __device__ __forceinline__ void gemm_phase(LAS unsigned char* lds, const int lda, const int ldb, const Sched& S, const Epi& E) {
;     ...
;             PG8_LDB(B0, 1, 0); PG8_LDB(B1, 1, 1); PG8_SCHED; PG8_LDA(At, 1, 0); PG8_STAGE(PG8_SA(0, 1), a2 + hstepA, voffA);
;             PG8_WAIT_V(8); PG8_WAIT_L(0); PG8_BAR; PG8_MMA(0, 0, At, B0); PG8_MMA(0, 1, At, B1); PG8_BAR; PG8_SCHED;
;             PG8_LDA(At, 1, 1); PG8_STAGE(PG8_SB(1, 0), b3, voffB); PG8_STAGE(PG8_SB(1, 1), b3 + hstepB, voffB); PG8_STAGE(PG8_SA(1, 0), a3, voffA);
;             PG8_WAIT_V(8); PG8_WAIT_L(0); PG8_BAR; PG8_MMA(1, 0, At, B0); PG8_MMA(1, 1, At, B1); PG8_BAR; PG8_SCHED;
;     ...
;         }
;         if (wr == 0) PG8_BAR;
	ds_read_b128 v[132:135], v143
	ds_read_b128 v[146:149], v143 offset:1024
	ds_read_b128 v[150:153], v143 offset:2048
	ds_read_b128 v[154:157], v143 offset:3072
	ds_read_b128 v[158:161], v144
	ds_read_b128 v[162:165], v144 offset:1024
	ds_read_b128 v[166:169], v144 offset:2048
	ds_read_b128 v[174:177], v144 offset:3072
	s_add_u32 s16, s28, 0x100000
	s_addc_u32 s17, s23, 0
	s_and_b32 s17, s17, 0xffff
	s_mov_b32 m0, s81
	ds_read_b128 v[178:181], v142 offset:32768
	ds_read_b128 v[182:185], v142 offset:33792
	ds_read_b128 v[186:189], v142 offset:34816
	ds_read_b128 v[190:193], v142 offset:35840
	ds_read_b128 v[194:197], v142 offset:36864
	ds_read_b128 v[198:201], v142 offset:37888
	ds_read_b128 v[202:205], v142 offset:38912
	ds_read_b128 v[206:209], v142 offset:39936
	buffer_load_dwordx4 v136, s[16:19], 0 offen lds
	s_mov_b32 m0, s82
	s_nop 0
	buffer_load_dwordx4 v138, s[16:19], 0 offen lds
	s_waitcnt vmcnt(8)
	s_waitcnt lgkmcnt(0)
	s_barrier
	v_mfma_f32_16x16x32_bf16 v[124:127], v[132:135], v[178:181], v[124:127]
	v_mfma_f32_16x16x32_bf16 v[120:123], v[150:153], v[178:181], v[120:123]
	v_mfma_f32_16x16x32_bf16 v[108:111], v[132:135], v[186:189], v[108:111]
	v_mfma_f32_16x16x32_bf16 v[104:107], v[150:153], v[186:189], v[104:107]
	v_mfma_f32_16x16x32_bf16 v[92:95], v[132:135], v[194:197], v[92:95]
	v_mfma_f32_16x16x32_bf16 v[88:91], v[150:153], v[194:197], v[88:91]
	v_mfma_f32_16x16x32_bf16 v[76:79], v[132:135], v[202:205], v[76:79]
	v_mfma_f32_16x16x32_bf16 v[72:75], v[150:153], v[202:205], v[72:75]
	v_mfma_f32_16x16x32_bf16 v[124:127], v[146:149], v[182:185], v[124:127]
	v_mfma_f32_16x16x32_bf16 v[120:123], v[154:157], v[182:185], v[120:123]
	v_mfma_f32_16x16x32_bf16 v[108:111], v[146:149], v[190:193], v[108:111]
	v_mfma_f32_16x16x32_bf16 v[104:107], v[154:157], v[190:193], v[104:107]
	v_mfma_f32_16x16x32_bf16 v[92:95], v[146:149], v[198:201], v[92:95]
	v_mfma_f32_16x16x32_bf16 v[88:91], v[154:157], v[198:201], v[88:91]
	v_mfma_f32_16x16x32_bf16 v[76:79], v[146:149], v[206:209], v[76:79]
	v_mfma_f32_16x16x32_bf16 v[72:75], v[154:157], v[206:209], v[72:75]
	v_mfma_f32_16x16x32_bf16 v[116:119], v[158:161], v[178:181], v[116:119]
	v_mfma_f32_16x16x32_bf16 v[112:115], v[166:169], v[178:181], v[112:115]
	v_mfma_f32_16x16x32_bf16 v[100:103], v[158:161], v[186:189], v[100:103]
	v_mfma_f32_16x16x32_bf16 v[96:99], v[166:169], v[186:189], v[96:99]
	v_mfma_f32_16x16x32_bf16 v[84:87], v[158:161], v[194:197], v[84:87]
	v_mfma_f32_16x16x32_bf16 v[80:83], v[166:169], v[194:197], v[80:83]
	v_mfma_f32_16x16x32_bf16 v[68:71], v[158:161], v[202:205], v[68:71]
	v_mfma_f32_16x16x32_bf16 v[64:67], v[166:169], v[202:205], v[64:67]
	v_mfma_f32_16x16x32_bf16 v[116:119], v[162:165], v[182:185], v[116:119]
	v_mfma_f32_16x16x32_bf16 v[112:115], v[174:177], v[182:185], v[112:115]
	v_mfma_f32_16x16x32_bf16 v[100:103], v[162:165], v[190:193], v[100:103]
	v_mfma_f32_16x16x32_bf16 v[96:99], v[174:177], v[190:193], v[96:99]
	v_mfma_f32_16x16x32_bf16 v[84:87], v[162:165], v[198:201], v[84:87]
	v_mfma_f32_16x16x32_bf16 v[80:83], v[174:177], v[198:201], v[80:83]
	v_mfma_f32_16x16x32_bf16 v[68:71], v[162:165], v[206:209], v[68:71]
	v_mfma_f32_16x16x32_bf16 v[64:67], v[174:177], v[206:209], v[64:67]
	s_barrier
	s_add_u32 s16, s24, 0x8000
	s_addc_u32 s17, s22, 0
	s_mov_b32 m0, s87
	s_and_b32 s17, s17, 0xffff
	ds_read_b128 v[178:181], v142 offset:49152
	ds_read_b128 v[182:185], v142 offset:50176
	ds_read_b128 v[186:189], v142 offset:51200
	ds_read_b128 v[190:193], v142 offset:52224
	ds_read_b128 v[194:197], v142 offset:53248
	ds_read_b128 v[198:201], v142 offset:54272
	ds_read_b128 v[202:205], v142 offset:55296
	ds_read_b128 v[206:209], v142 offset:56320
	buffer_load_dwordx4 v137, s[16:19], 0 offen lds
	s_mov_b32 m0, s88
	s_mov_b32 s23, s19
	buffer_load_dwordx4 v139, s[16:19], 0 offen lds
	s_add_u32 s16, s24, 0xc000
	s_addc_u32 s17, s22, 0
	s_and_b32 s17, s17, 0xffff
	s_mov_b32 m0, s91
	s_and_b32 s21, s21, 0xffff
	buffer_load_dwordx4 v137, s[16:19], 0 offen lds
	s_mov_b32 m0, s92
	s_mov_b32 s22, s18
	buffer_load_dwordx4 v139, s[16:19], 0 offen lds
	s_mov_b32 m0, s89
	s_nop 0
	buffer_load_dwordx4 v136, s[20:23], 0 offen lds
	s_mov_b32 m0, s90
	s_nop 0
	buffer_load_dwordx4 v138, s[20:23], 0 offen lds
	s_waitcnt vmcnt(8)
	s_waitcnt lgkmcnt(0)
	s_barrier
	v_mfma_f32_16x16x32_bf16 v[60:63], v[132:135], v[178:181], v[60:63]
	v_mfma_f32_16x16x32_bf16 v[56:59], v[150:153], v[178:181], v[56:59]
	v_mfma_f32_16x16x32_bf16 v[44:47], v[132:135], v[186:189], v[44:47]
	v_mfma_f32_16x16x32_bf16 v[40:43], v[150:153], v[186:189], v[40:43]
	v_mfma_f32_16x16x32_bf16 v[28:31], v[132:135], v[194:197], v[28:31]
	v_mfma_f32_16x16x32_bf16 v[24:27], v[150:153], v[194:197], v[24:27]
	v_mfma_f32_16x16x32_bf16 v[12:15], v[132:135], v[202:205], v[12:15]
	v_mfma_f32_16x16x32_bf16 v[8:11], v[150:153], v[202:205], v[8:11]
	v_mfma_f32_16x16x32_bf16 v[60:63], v[146:149], v[182:185], v[60:63]
	v_mfma_f32_16x16x32_bf16 v[56:59], v[154:157], v[182:185], v[56:59]
	v_mfma_f32_16x16x32_bf16 v[44:47], v[146:149], v[190:193], v[44:47]
	v_mfma_f32_16x16x32_bf16 v[40:43], v[154:157], v[190:193], v[40:43]
	v_mfma_f32_16x16x32_bf16 v[28:31], v[146:149], v[198:201], v[28:31]
	v_mfma_f32_16x16x32_bf16 v[24:27], v[154:157], v[198:201], v[24:27]
	v_mfma_f32_16x16x32_bf16 v[12:15], v[146:149], v[206:209], v[12:15]
	v_mfma_f32_16x16x32_bf16 v[8:11], v[154:157], v[206:209], v[8:11]
	v_mfma_f32_16x16x32_bf16 v[52:55], v[158:161], v[178:181], v[52:55]
	v_mfma_f32_16x16x32_bf16 v[48:51], v[166:169], v[178:181], v[48:51]
	v_mfma_f32_16x16x32_bf16 v[36:39], v[158:161], v[186:189], v[36:39]
	v_mfma_f32_16x16x32_bf16 v[32:35], v[166:169], v[186:189], v[32:35]
	v_mfma_f32_16x16x32_bf16 v[20:23], v[158:161], v[194:197], v[20:23]
	v_mfma_f32_16x16x32_bf16 v[16:19], v[166:169], v[194:197], v[16:19]
	v_mfma_f32_16x16x32_bf16 v[4:7], v[158:161], v[202:205], v[4:7]
	v_mfma_f32_16x16x32_bf16 v[0:3], v[166:169], v[202:205], v[0:3]
	v_mfma_f32_16x16x32_bf16 v[52:55], v[162:165], v[182:185], v[52:55]
	v_mfma_f32_16x16x32_bf16 v[48:51], v[174:177], v[182:185], v[48:51]
	v_mfma_f32_16x16x32_bf16 v[36:39], v[162:165], v[190:193], v[36:39]
	v_mfma_f32_16x16x32_bf16 v[32:35], v[174:177], v[190:193], v[32:35]
	v_mfma_f32_16x16x32_bf16 v[20:23], v[162:165], v[198:201], v[20:23]
	v_mfma_f32_16x16x32_bf16 v[16:19], v[174:177], v[198:201], v[16:19]
	v_mfma_f32_16x16x32_bf16 v[4:7], v[162:165], v[206:209], v[4:7]
	v_mfma_f32_16x16x32_bf16 v[0:3], v[174:177], v[206:209], v[0:3]
	s_barrier
	s_add_i32 s69, s69, 2
	s_add_u32 s7, s7, 0x10000
	s_addc_u32 s62, s62, 0
	s_add_u32 s63, s63, 0x100
	s_addc_u32 s67, s67, 0
	s_cmp_gt_u32 s69, 61
	s_cbranch_scc0 .LBB0_116
	s_and_b64 vcc, exec, s[38:39]
	s_cbranch_vccz .LBB0_119
	s_barrier

; #define PG8_WAIT_V(n) asm volatile("s_waitcnt vmcnt(" #n ")" ::: "memory")
; #define PG8_BAR __builtin_amdgcn_s_barrier()
; template <class Epi, class Sched, bool F8 = false>
; __device__ __forceinline__ void gemm_phase(LAS unsigned char* lds, const int lda, const int ldb, const Sched& S, const Epi& E) {
;     ...
;     PG8_WAIT_V(0);
;     PG8_BAR;
.LBB0_154:
	s_load_dwordx2 s[96:97], s[0:1], 0xe0
	s_waitcnt vmcnt(0)
	v_readlane_b32 s88, v255, 7
	v_readlane_b32 s95, v255, 6
	v_readlane_b32 s89, v255, 8
	s_setprio 0
	s_barrier

; #define PG8_STAGE(bufoff, gbase, voff) do { const __amdgpu_buffer_rsrc_t _rs = __builtin_amdgcn_make_buffer_rsrc((void*)(gbase), 0, 0x7fffffff, 0x00020000); _Pragma("unroll") for (int _i = 0; _i < 2; ++_i) \
;         __builtin_amdgcn_raw_ptr_buffer_load_lds(_rs, (LAS unsigned*)(lds + (bufoff) + ldsw + _i * 8192), 16, (int)(voff)[_i], 0, 0, 0); } while (0)
; #define PG8_BAR __builtin_amdgcn_s_barrier()
; template <class Epi, class Sched, bool F8 = false>
; __device__ __forceinline__ void gemm_phase(LAS unsigned char* lds, const int lda, const int ldb, const Sched& S, const Epi& E) {
;     ...
;     for (int i = 0; i < 2; ++i) { int R, C; stage_rc(tid * 16 + i * 8192, R, C); const int Rb = Epi::PERM ? ((R & ~31) + perm32(R & 31)) : R;
;         voffA[i] = (unsigned)(R * lda + C * 2); voffB[i] = (unsigned)(Rb * 128 + C * 2); }
;     const size_t kstep = (size_t)(BK * 2), kstepB = 32768;
;     const size_t hstepA = (size_t)HALF * lda, hstepB = 16384; (void)ldb;
;     const unsigned ldsw = (unsigned)wid * 1024u;
;     const int aoff = lds_byte(wr * 64 + fr, fq * 8), boff = lds_byte(wc * 32 + fr, fq * 8);
;     ...
;     PG8_STAGE(PG8_SB(0, 0), cB, voffB); PG8_STAGE(PG8_SB(0, 1), cB + hstepB, voffB); PG8_STAGE(PG8_SA(0, 0), cA, voffA); PG8_STAGE(PG8_SA(0, 1), cA + hstepA, voffA);
;     if (wr == 1) PG8_BAR;
.LBB0_162:
	v_bfe_i32 v3, v0, 27, 1
	v_lshlrev_b32_e32 v1, 4, v0
	v_lshrrev_b32_e32 v3, 22, v3
	v_add_u32_e32 v3, v1, v3
	v_and_b32_e32 v3, 0xfffffc00, v3
	v_sub_u32_e32 v3, v1, v3
	v_ashrrev_i32_e32 v2, 31, v0
	v_lshrrev_b32_e32 v4, 4, v3
	v_lshrrev_b32_e32 v2, 26, v2
	v_bitop3_b32 v3, v4, v3, 32 bitop3:0x6c
	v_add_u32_e32 v2, v0, v2
	v_ashrrev_i32_e32 v5, 31, v3
	v_ashrrev_i32_e32 v2, 6, v2
	v_lshrrev_b32_e32 v5, 26, v5
	v_lshlrev_b32_e32 v4, 3, v2
	v_add_u32_e32 v5, v3, v5
	v_and_b32_e32 v4, -16, v4
	v_ashrrev_i32_e32 v6, 6, v5
	v_and_b32_e32 v5, 0xc0, v5
	v_add_u32_e32 v4, v6, v4
	v_sub_u32_e32 v3, v3, v5
	v_mov_b32_e32 v5, 1
	v_lshlrev_b32_e32 v2, 5, v2
	v_ashrrev_i16_sdwa v3, v5, sext(v3) dst_sel:DWORD dst_unused:UNUSED_PAD src0_sel:DWORD src1_sel:BYTE_0
	v_lshlrev_b32_e32 v7, 1, v4
	v_lshrrev_b32_e32 v8, 2, v4
	v_and_b32_e32 v6, 3, v6
	s_mov_b32 s5, 0x1ffffe0
	v_and_b32_e32 v2, 32, v2
	v_bfe_i32 v3, v3, 0, 16
	v_and_b32_e32 v7, 24, v7
	v_and_b32_e32 v8, 4, v8
	v_and_or_b32 v6, v4, s5, v6
	v_or3_b32 v6, v6, v8, v7
	v_add_lshl_u32 v2, v2, v3, 1
	v_add_u32_e32 v1, 0x2000, v1
	v_lshl_add_u32 v136, v4, 12, v2
	v_lshl_add_u32 v137, v6, 7, v2
	v_ashrrev_i32_e32 v2, 31, v1
	v_lshrrev_b32_e32 v2, 22, v2
	v_add_u32_e32 v2, v1, v2
	v_ashrrev_i32_e32 v2, 10, v2
	v_mul_i32_i24_e32 v3, 0x400, v2
	v_sub_u32_e32 v1, v1, v3
	v_lshrrev_b32_e32 v3, 4, v1
	v_bitop3_b32 v1, v3, v1, 32 bitop3:0x6c
	v_ashrrev_i32_e32 v4, 31, v1
	v_lshrrev_b32_e32 v4, 26, v4
	v_lshlrev_b32_e32 v3, 3, v2
	v_add_u32_e32 v4, v1, v4
	v_and_b32_e32 v3, -16, v3
	v_ashrrev_i32_e32 v6, 6, v4
	v_add_u32_e32 v3, v6, v3
	v_and_b32_e32 v6, 3, v6
	v_and_b32_e32 v4, 0xc0, v4
	v_and_or_b32 v6, v3, s5, v6
	s_ashr_i32 s5, s3, 6
	v_sub_u32_e32 v1, v1, v4
	s_lshl_b32 s7, s5, 10
	v_lshlrev_b32_e32 v2, 5, v2
	v_ashrrev_i16_sdwa v1, v5, sext(v1) dst_sel:DWORD dst_unused:UNUSED_PAD src0_sel:DWORD src1_sel:BYTE_0
	v_lshlrev_b32_e32 v4, 1, v3
	v_lshrrev_b32_e32 v5, 2, v3
	s_add_i32 s76, s7, 0
	v_and_b32_e32 v2, 32, v2
	v_bfe_i32 v1, v1, 0, 16
	v_and_b32_e32 v4, 24, v4
	v_and_b32_e32 v5, 4, v5
	s_add_i32 s79, s76, 0x10000
	v_or3_b32 v4, v6, v5, v4
	v_add_lshl_u32 v1, v2, v1, 1
	s_and_b32 s17, s23, 0xffff
	s_mov_b32 s19, 0x20000
	s_brev_b32 s18, -2
	s_mov_b32 s16, s22
	s_mov_b32 m0, s79
	s_add_i32 s80, s76, 0x12000
	s_ashr_i32 s4, s3, 8
	v_lshl_add_u32 v139, v4, 7, v1
	buffer_load_dwordx4 v137, s[16:19], 0 offen lds
	s_mov_b32 m0, s80
	v_lshl_add_u32 v138, v3, 12, v1
	buffer_load_dwordx4 v139, s[16:19], 0 offen lds
	s_add_u32 s16, s22, 0x4000
	s_addc_u32 s7, s23, 0
	s_add_i32 s81, s76, 0x14000
	s_and_b32 s17, s7, 0xffff
	s_mov_b32 m0, s81
	s_add_i32 s82, s76, 0x16000
	buffer_load_dwordx4 v137, s[16:19], 0 offen lds
	s_mov_b32 m0, s82
	s_add_i32 s83, s76, 0x2000
	buffer_load_dwordx4 v139, s[16:19], 0 offen lds
	s_and_b32 s17, s21, 0xffff
	s_mov_b32 s16, s20
	s_mov_b32 m0, s76
	s_mov_b32 s86, 0
	buffer_load_dwordx4 v136, s[16:19], 0 offen lds
	s_mov_b32 m0, s83
	s_movk_i32 s87, 0x6000
	buffer_load_dwordx4 v138, s[16:19], 0 offen lds
	s_add_u32 s16, s20, 0x80000
	s_addc_u32 s7, s21, 0
	s_add_i32 s84, s76, 0x4000
	s_and_b32 s17, s7, 0xffff
	s_mov_b32 m0, s84
	s_add_i32 s85, s76, 0x6000
	buffer_load_dwordx4 v136, s[16:19], 0 offen lds
	s_mov_b32 m0, s85
	s_cmp_eq_u32 s4, 1
	buffer_load_dwordx4 v138, s[16:19], 0 offen lds
	s_cselect_b64 s[36:37], -1, 0
	s_cmp_lg_u32 s4, 1
	s_cbranch_scc1 .LBB0_164
	s_setprio 1
	s_barrier

; #define PG8_STAGE(bufoff, gbase, voff) do { const __amdgpu_buffer_rsrc_t _rs = __builtin_amdgcn_make_buffer_rsrc((void*)(gbase), 0, 0x7fffffff, 0x00020000); _Pragma("unroll") for (int _i = 0; _i < 2; ++_i) \
;         __builtin_amdgcn_raw_ptr_buffer_load_lds(_rs, (LAS unsigned*)(lds + (bufoff) + ldsw + _i * 8192), 16, (int)(voff)[_i], 0, 0, 0); } while (0)
; #define PG8_WAIT_V(n) asm volatile("s_waitcnt vmcnt(" #n ")" ::: "memory")
; #define PG8_WAIT_L(n) asm volatile("s_waitcnt lgkmcnt(" #n ")" ::: "memory")
; #define PG8_BAR __builtin_amdgcn_s_barrier()
; #define PG8_SCHED __builtin_amdgcn_sched_barrier(0)
; template <class Epi, class Sched, bool F8 = false>
; __device__ __forceinline__ void gemm_phase(LAS unsigned char* lds, const int lda, const int ldb, const Sched& S, const Epi& E) {
;     ...
;             PG8_LDB(B0, 0, 0); PG8_LDB(B1, 0, 1); PG8_SCHED; PG8_LDA(At, 0, 0); PG8_STAGE(PG8_SA(1, 1), a1 + hstepA, voffA);
;             PG8_WAIT_V(8); PG8_WAIT_L(0); PG8_BAR; PG8_MMA(0, 0, At, B0); PG8_MMA(0, 1, At, B1); PG8_BAR; PG8_SCHED;
;             PG8_LDA(At, 0, 1); PG8_STAGE(PG8_SB(0, 0), b2, voffB); PG8_STAGE(PG8_SB(0, 1), b2 + hstepB, voffB); PG8_STAGE(PG8_SA(0, 0), a2, voffA);
;             PG8_WAIT_V(8); PG8_WAIT_L(0); PG8_BAR; PG8_MMA(1, 0, At, B0); PG8_MMA(1, 1, At, B1); PG8_BAR; PG8_SCHED;
.LBB0_174:
	ds_read_b128 v[146:149], v140
	ds_read_b128 v[150:153], v140 offset:1024
	ds_read_b128 v[154:157], v140 offset:2048
	ds_read_b128 v[158:161], v140 offset:3072
	ds_read_b128 v[162:165], v141
	ds_read_b128 v[166:169], v141 offset:1024
	ds_read_b128 v[174:177], v141 offset:2048
	ds_read_b128 v[178:181], v141 offset:3072
	s_add_u32 s16, s63, 0xfff80080
	s_addc_u32 s17, s67, -1
	s_cmp_eq_u32 s69, 28
	s_cselect_b32 s28, s70, s16
	s_cselect_b32 s23, s71, s17
	s_cselect_b32 s22, s73, s62
	s_cselect_b32 s24, s72, s7
	s_add_u32 s20, s28, 0x80
	s_addc_u32 s21, s23, 0
	s_and_b32 s17, s67, 0xffff
	s_mov_b32 s16, s63
	s_mov_b32 m0, s96
	ds_read_b128 v[182:185], v142
	ds_read_b128 v[186:189], v142 offset:1024
	ds_read_b128 v[190:193], v142 offset:2048
	ds_read_b128 v[194:197], v142 offset:3072
	ds_read_b128 v[198:201], v142 offset:4096
	ds_read_b128 v[202:205], v142 offset:5120
	ds_read_b128 v[206:209], v142 offset:6144
	ds_read_b128 v[210:213], v142 offset:7168
	buffer_load_dwordx4 v136, s[16:19], 0 offen lds
	s_mov_b32 m0, s97
	s_nop 0
	buffer_load_dwordx4 v138, s[16:19], 0 offen lds
	s_waitcnt vmcnt(8)
	s_waitcnt lgkmcnt(0)
	s_barrier
	v_mfma_scale_f32_16x16x128_f8f6f4 v[124:127], v[146:153], v[182:189], v[124:127], v143, v143 op_sel_hi:[0,0,0]
	v_mfma_scale_f32_16x16x128_f8f6f4 v[120:123], v[154:161], v[182:189], v[120:123], v143, v143 op_sel_hi:[0,0,0]
	v_mfma_scale_f32_16x16x128_f8f6f4 v[108:111], v[146:153], v[190:197], v[108:111], v143, v143 op_sel_hi:[0,0,0]
	v_mfma_scale_f32_16x16x128_f8f6f4 v[104:107], v[154:161], v[190:197], v[104:107], v143, v143 op_sel_hi:[0,0,0]
	v_mfma_scale_f32_16x16x128_f8f6f4 v[132:135], v[146:153], v[198:205], v[92:95], v143, v143 op_sel_hi:[0,0,0]
	v_mfma_scale_f32_16x16x128_f8f6f4 v[214:217], v[154:161], v[198:205], v[88:91], v143, v143 op_sel_hi:[0,0,0]
	v_mfma_scale_f32_16x16x128_f8f6f4 v[218:221], v[146:153], v[206:213], v[76:79], v143, v143 op_sel_hi:[0,0,0]
	v_mfma_scale_f32_16x16x128_f8f6f4 v[222:225], v[154:161], v[206:213], v[72:75], v143, v143 op_sel_hi:[0,0,0]
	v_mfma_scale_f32_16x16x128_f8f6f4 v[116:119], v[162:169], v[182:189], v[116:119], v143, v143 op_sel_hi:[0,0,0]
	v_mfma_scale_f32_16x16x128_f8f6f4 v[112:115], v[174:181], v[182:189], v[112:115], v143, v143 op_sel_hi:[0,0,0]
	v_mfma_scale_f32_16x16x128_f8f6f4 v[100:103], v[162:169], v[190:197], v[100:103], v143, v143 op_sel_hi:[0,0,0]
	v_mfma_scale_f32_16x16x128_f8f6f4 v[96:99], v[174:181], v[190:197], v[96:99], v143, v143 op_sel_hi:[0,0,0]
	v_mfma_scale_f32_16x16x128_f8f6f4 v[182:185], v[162:169], v[198:205], v[84:87], v143, v143 op_sel_hi:[0,0,0]
	v_mfma_scale_f32_16x16x128_f8f6f4 v[186:189], v[174:181], v[198:205], v[80:83], v143, v143 op_sel_hi:[0,0,0]
	v_mfma_scale_f32_16x16x128_f8f6f4 v[190:193], v[162:169], v[206:213], v[68:71], v143, v143 op_sel_hi:[0,0,0]
	v_mfma_scale_f32_16x16x128_f8f6f4 v[194:197], v[174:181], v[206:213], v[64:67], v143, v143 op_sel_hi:[0,0,0]
	s_barrier
	s_and_b32 s25, s22, 0xffff
	s_mov_b32 m0, s79
	s_mov_b32 s26, s18
	s_mov_b32 s27, s19
	s_add_u32 s16, s24, 0x4000
	ds_read_b128 v[64:67], v142 offset:16384
	ds_read_b128 v[68:71], v142 offset:17408
	ds_read_b128 v[72:75], v142 offset:18432
	ds_read_b128 v[76:79], v142 offset:19456
	ds_read_b128 v[80:83], v142 offset:20480
	ds_read_b128 v[84:87], v142 offset:21504
	ds_read_b128 v[88:91], v142 offset:22528
	ds_read_b128 v[92:95], v142 offset:23552
	buffer_load_dwordx4 v137, s[24:27], 0 offen lds
	s_mov_b32 m0, s80
	s_addc_u32 s17, s22, 0
	buffer_load_dwordx4 v139, s[24:27], 0 offen lds
	s_and_b32 s17, s17, 0xffff
	s_mov_b32 m0, s81
	s_and_b32 s29, s23, 0xffff
	buffer_load_dwordx4 v137, s[16:19], 0 offen lds
	s_mov_b32 m0, s82
	s_mov_b32 s30, s18
	buffer_load_dwordx4 v139, s[16:19], 0 offen lds
	s_mov_b32 s31, s19
	s_mov_b32 m0, s76
	s_nop 0
	buffer_load_dwordx4 v136, s[28:31], 0 offen lds
	s_mov_b32 m0, s83
	s_nop 0
	buffer_load_dwordx4 v138, s[28:31], 0 offen lds
	s_waitcnt vmcnt(8)
	s_waitcnt lgkmcnt(0)
	s_barrier
	v_mfma_scale_f32_16x16x128_f8f6f4 v[60:63], v[146:153], v[64:71], v[60:63], v143, v143 op_sel_hi:[0,0,0]
	v_mfma_scale_f32_16x16x128_f8f6f4 v[56:59], v[154:161], v[64:71], v[56:59], v143, v143 op_sel_hi:[0,0,0]
	v_mfma_scale_f32_16x16x128_f8f6f4 v[198:201], v[146:153], v[72:79], v[44:47], v143, v143 op_sel_hi:[0,0,0]
	v_mfma_scale_f32_16x16x128_f8f6f4 v[202:205], v[154:161], v[72:79], v[40:43], v143, v143 op_sel_hi:[0,0,0]
	v_mfma_scale_f32_16x16x128_f8f6f4 v[206:209], v[146:153], v[80:87], v[28:31], v143, v143 op_sel_hi:[0,0,0]
	v_mfma_scale_f32_16x16x128_f8f6f4 v[210:213], v[154:161], v[80:87], v[24:27], v143, v143 op_sel_hi:[0,0,0]
	v_mfma_scale_f32_16x16x128_f8f6f4 v[226:229], v[146:153], v[88:95], v[12:15], v143, v143 op_sel_hi:[0,0,0]
	v_mfma_scale_f32_16x16x128_f8f6f4 v[230:233], v[154:161], v[88:95], v[8:11], v143, v143 op_sel_hi:[0,0,0]
	v_mfma_scale_f32_16x16x128_f8f6f4 v[52:55], v[162:169], v[64:71], v[52:55], v143, v143 op_sel_hi:[0,0,0]
	v_mfma_scale_f32_16x16x128_f8f6f4 v[48:51], v[174:181], v[64:71], v[48:51], v143, v143 op_sel_hi:[0,0,0]
	v_mfma_scale_f32_16x16x128_f8f6f4 v[234:237], v[162:169], v[72:79], v[36:39], v143, v143 op_sel_hi:[0,0,0]
	v_mfma_scale_f32_16x16x128_f8f6f4 v[238:241], v[174:181], v[72:79], v[32:35], v143, v143 op_sel_hi:[0,0,0]
	v_mfma_scale_f32_16x16x128_f8f6f4 v[242:245], v[162:169], v[80:87], v[20:23], v143, v143 op_sel_hi:[0,0,0]
	v_mfma_scale_f32_16x16x128_f8f6f4 v[246:249], v[174:181], v[80:87], v[16:19], v143, v143 op_sel_hi:[0,0,0]
	v_mfma_scale_f32_16x16x128_f8f6f4 v[250:253], v[162:169], v[88:95], v[4:7], v143, v143 op_sel_hi:[0,0,0]
	v_mfma_scale_f32_16x16x128_f8f6f4 v[170:173], v[174:181], v[88:95], v[0:3], v143, v143 op_sel_hi:[0,0,0]
	s_barrier
; #define PG8_STAGE(bufoff, gbase, voff) do { const __amdgpu_buffer_rsrc_t _rs = __builtin_amdgcn_make_buffer_rsrc((void*)(gbase), 0, 0x7fffffff, 0x00020000); _Pragma("unroll") for (int _i = 0; _i < 2; ++_i) \
;         __builtin_amdgcn_raw_ptr_buffer_load_lds(_rs, (LAS unsigned*)(lds + (bufoff) + ldsw + _i * 8192), 16, (int)(voff)[_i], 0, 0, 0); } while (0)
; #define PG8_WAIT_V(n) asm volatile("s_waitcnt vmcnt(" #n ")" ::: "memory")
; #define PG8_WAIT_L(n) asm volatile("s_waitcnt lgkmcnt(" #n ")" ::: "memory")
; #define PG8_BAR __builtin_amdgcn_s_barrier()
; #define PG8_SCHED __builtin_amdgcn_sched_barrier(0)
; template <class Epi, class Sched, bool F8 = false>
; __device__ __forceinline__ void gemm_phase(LAS unsigned char* lds, const int lda, const int ldb, const Sched& S, const Epi& E) {
;     ...
;             PG8_LDB(B0, 1, 0); PG8_LDB(B1, 1, 1); PG8_SCHED; PG8_LDA(At, 1, 0); PG8_STAGE(PG8_SA(0, 1), a2 + hstepA, voffA);
;             PG8_WAIT_V(8); PG8_WAIT_L(0); PG8_BAR; PG8_MMA(0, 0, At, B0); PG8_MMA(0, 1, At, B1); PG8_BAR; PG8_SCHED;
;             PG8_LDA(At, 1, 1); PG8_STAGE(PG8_SB(1, 0), b3, voffB); PG8_STAGE(PG8_SB(1, 1), b3 + hstepB, voffB); PG8_STAGE(PG8_SA(1, 0), a3, voffA);
;             PG8_WAIT_V(8); PG8_WAIT_L(0); PG8_BAR; PG8_MMA(1, 0, At, B0); PG8_MMA(1, 1, At, B1); PG8_BAR; PG8_SCHED;
	s_nop 4
	ds_read_b128 v[0:3], v144
	ds_read_b128 v[4:7], v144 offset:1024
	ds_read_b128 v[16:19], v144 offset:2048
	ds_read_b128 v[20:23], v144 offset:3072
	ds_read_b128 v[146:149], v145
	ds_read_b128 v[150:153], v145 offset:1024
	ds_read_b128 v[154:157], v145 offset:2048
	ds_read_b128 v[158:161], v145 offset:3072
	s_add_u32 s16, s28, 0x80000
	s_addc_u32 s17, s23, 0
	s_and_b32 s17, s17, 0xffff
	s_mov_b32 m0, s84
	ds_read_b128 v[8:11], v142 offset:32768
	ds_read_b128 v[12:15], v142 offset:33792
	ds_read_b128 v[24:27], v142 offset:34816
	ds_read_b128 v[28:31], v142 offset:35840
	ds_read_b128 v[32:35], v142 offset:36864
	ds_read_b128 v[36:39], v142 offset:37888
	ds_read_b128 v[40:43], v142 offset:38912
	ds_read_b128 v[44:47], v142 offset:39936
	buffer_load_dwordx4 v136, s[16:19], 0 offen lds
	s_mov_b32 m0, s85
	s_nop 0
	buffer_load_dwordx4 v138, s[16:19], 0 offen lds
	s_waitcnt vmcnt(8)
	s_waitcnt lgkmcnt(0)
	s_barrier
	v_mfma_scale_f32_16x16x128_f8f6f4 v[124:127], v[0:7], v[8:15], v[124:127], v143, v143 op_sel_hi:[0,0,0]
	v_mfma_scale_f32_16x16x128_f8f6f4 v[120:123], v[16:23], v[8:15], v[120:123], v143, v143 op_sel_hi:[0,0,0]
	v_mfma_scale_f32_16x16x128_f8f6f4 v[108:111], v[0:7], v[24:31], v[108:111], v143, v143 op_sel_hi:[0,0,0]
	v_mfma_scale_f32_16x16x128_f8f6f4 v[104:107], v[16:23], v[24:31], v[104:107], v143, v143 op_sel_hi:[0,0,0]
	v_mfma_scale_f32_16x16x128_f8f6f4 v[92:95], v[0:7], v[32:39], v[132:135], v143, v143 op_sel_hi:[0,0,0]
	v_mfma_scale_f32_16x16x128_f8f6f4 v[88:91], v[16:23], v[32:39], v[214:217], v143, v143 op_sel_hi:[0,0,0]
	v_mfma_scale_f32_16x16x128_f8f6f4 v[76:79], v[0:7], v[40:47], v[218:221], v143, v143 op_sel_hi:[0,0,0]
	v_mfma_scale_f32_16x16x128_f8f6f4 v[72:75], v[16:23], v[40:47], v[222:225], v143, v143 op_sel_hi:[0,0,0]
	v_mfma_scale_f32_16x16x128_f8f6f4 v[116:119], v[146:153], v[8:15], v[116:119], v143, v143 op_sel_hi:[0,0,0]
	v_mfma_scale_f32_16x16x128_f8f6f4 v[112:115], v[154:161], v[8:15], v[112:115], v143, v143 op_sel_hi:[0,0,0]
	v_mfma_scale_f32_16x16x128_f8f6f4 v[100:103], v[146:153], v[24:31], v[100:103], v143, v143 op_sel_hi:[0,0,0]
	v_mfma_scale_f32_16x16x128_f8f6f4 v[96:99], v[154:161], v[24:31], v[96:99], v143, v143 op_sel_hi:[0,0,0]
	v_mfma_scale_f32_16x16x128_f8f6f4 v[84:87], v[146:153], v[32:39], v[182:185], v143, v143 op_sel_hi:[0,0,0]
	v_mfma_scale_f32_16x16x128_f8f6f4 v[80:83], v[154:161], v[32:39], v[186:189], v143, v143 op_sel_hi:[0,0,0]
	v_mfma_scale_f32_16x16x128_f8f6f4 v[68:71], v[146:153], v[40:47], v[190:193], v143, v143 op_sel_hi:[0,0,0]
	v_mfma_scale_f32_16x16x128_f8f6f4 v[64:67], v[154:161], v[40:47], v[194:197], v143, v143 op_sel_hi:[0,0,0]
	s_barrier
	s_add_u32 s16, s24, 0x8000
	s_addc_u32 s17, s22, 0
	s_mov_b32 m0, s90
	s_and_b32 s17, s17, 0xffff
	ds_read_b128 v[32:35], v142 offset:49152
	ds_read_b128 v[36:39], v142 offset:50176
	ds_read_b128 v[162:165], v142 offset:51200
	ds_read_b128 v[166:169], v142 offset:52224
	ds_read_b128 v[174:177], v142 offset:53248
	ds_read_b128 v[178:181], v142 offset:54272
	ds_read_b128 v[182:185], v142 offset:55296
	ds_read_b128 v[186:189], v142 offset:56320
	buffer_load_dwordx4 v137, s[16:19], 0 offen lds
	s_mov_b32 m0, s91
	s_mov_b32 s23, s19
	buffer_load_dwordx4 v139, s[16:19], 0 offen lds
	s_add_u32 s16, s24, 0xc000
	s_addc_u32 s17, s22, 0
	s_and_b32 s17, s17, 0xffff
	s_mov_b32 m0, s94
	s_and_b32 s21, s21, 0xffff
	buffer_load_dwordx4 v137, s[16:19], 0 offen lds
	s_mov_b32 m0, s95
	s_mov_b32 s22, s18
	buffer_load_dwordx4 v139, s[16:19], 0 offen lds
	s_mov_b32 m0, s92
	s_nop 0
	buffer_load_dwordx4 v136, s[20:23], 0 offen lds
	s_mov_b32 m0, s93
	s_nop 0
	buffer_load_dwordx4 v138, s[20:23], 0 offen lds
	s_waitcnt vmcnt(8)
	s_waitcnt lgkmcnt(0)
	s_barrier
	v_mfma_scale_f32_16x16x128_f8f6f4 v[60:63], v[0:7], v[32:39], v[60:63], v143, v143 op_sel_hi:[0,0,0]
	v_mfma_scale_f32_16x16x128_f8f6f4 v[56:59], v[16:23], v[32:39], v[56:59], v143, v143 op_sel_hi:[0,0,0]
	v_mfma_scale_f32_16x16x128_f8f6f4 v[44:47], v[0:7], v[162:169], v[198:201], v143, v143 op_sel_hi:[0,0,0]
	v_mfma_scale_f32_16x16x128_f8f6f4 v[40:43], v[16:23], v[162:169], v[202:205], v143, v143 op_sel_hi:[0,0,0]
	v_mfma_scale_f32_16x16x128_f8f6f4 v[28:31], v[0:7], v[174:181], v[206:209], v143, v143 op_sel_hi:[0,0,0]
	v_mfma_scale_f32_16x16x128_f8f6f4 v[24:27], v[16:23], v[174:181], v[210:213], v143, v143 op_sel_hi:[0,0,0]
	v_mfma_scale_f32_16x16x128_f8f6f4 v[12:15], v[0:7], v[182:189], v[226:229], v143, v143 op_sel_hi:[0,0,0]
	v_mfma_scale_f32_16x16x128_f8f6f4 v[8:11], v[16:23], v[182:189], v[230:233], v143, v143 op_sel_hi:[0,0,0]
	v_mfma_scale_f32_16x16x128_f8f6f4 v[52:55], v[146:153], v[32:39], v[52:55], v143, v143 op_sel_hi:[0,0,0]
	v_mfma_scale_f32_16x16x128_f8f6f4 v[48:51], v[154:161], v[32:39], v[48:51], v143, v143 op_sel_hi:[0,0,0]
	v_mfma_scale_f32_16x16x128_f8f6f4 v[36:39], v[146:153], v[162:169], v[234:237], v143, v143 op_sel_hi:[0,0,0]
	v_mfma_scale_f32_16x16x128_f8f6f4 v[32:35], v[154:161], v[162:169], v[238:241], v143, v143 op_sel_hi:[0,0,0]
	v_mfma_scale_f32_16x16x128_f8f6f4 v[20:23], v[146:153], v[174:181], v[242:245], v143, v143 op_sel_hi:[0,0,0]
	v_mfma_scale_f32_16x16x128_f8f6f4 v[16:19], v[154:161], v[174:181], v[246:249], v143, v143 op_sel_hi:[0,0,0]
	v_mfma_scale_f32_16x16x128_f8f6f4 v[4:7], v[146:153], v[182:189], v[250:253], v143, v143 op_sel_hi:[0,0,0]
	v_mfma_scale_f32_16x16x128_f8f6f4 v[0:3], v[154:161], v[182:189], v[170:173], v143, v143 op_sel_hi:[0,0,0]
	s_barrier
	s_add_i32 s69, s69, 2
	s_add_u32 s7, s7, 0x10000
	s_addc_u32 s62, s62, 0
	s_add_u32 s63, s63, 0x100
	s_addc_u32 s67, s67, 0
	s_cmp_gt_u32 s69, 29
	s_cbranch_scc0 .LBB0_174
	s_and_b64 vcc, exec, s[38:39]
	s_cbranch_vccz .LBB0_177
	s_barrier

; #define PG8_STAGE(bufoff, gbase, voff) do { const __amdgpu_buffer_rsrc_t _rs = __builtin_amdgcn_make_buffer_rsrc((void*)(gbase), 0, 0x7fffffff, 0x00020000); _Pragma("unroll") for (int _i = 0; _i < 2; ++_i) \
;         __builtin_amdgcn_raw_ptr_buffer_load_lds(_rs, (LAS unsigned*)(lds + (bufoff) + ldsw + _i * 8192), 16, (int)(voff)[_i], 0, 0, 0); } while (0)
; #define PG8_BAR __builtin_amdgcn_s_barrier()
; template <class Epi, class Sched, bool F8 = false>
; __device__ __forceinline__ void gemm_phase(LAS unsigned char* lds, const int lda, const int ldb, const Sched& S, const Epi& E) {
;     ...
;     for (int i = 0; i < 2; ++i) { int R, C; stage_rc(tid * 16 + i * 8192, R, C); const int Rb = Epi::PERM ? ((R & ~31) + perm32(R & 31)) : R;
;         voffA[i] = (unsigned)(R * lda + C * 2); voffB[i] = (unsigned)(Rb * 128 + C * 2); }
;     ...
;     PG8_STAGE(PG8_SB(0, 0), cB, voffB); PG8_STAGE(PG8_SB(0, 1), cB + hstepB, voffB); PG8_STAGE(PG8_SA(0, 0), cA, voffA); PG8_STAGE(PG8_SA(0, 1), cA + hstepA, voffA);
;     if (wr == 1) PG8_BAR;
.LBB0_395:
	v_bfe_i32 v3, v0, 27, 1
	v_lshlrev_b32_e32 v1, 4, v0
	v_lshrrev_b32_e32 v3, 22, v3
	v_add_u32_e32 v3, v1, v3
	v_and_b32_e32 v3, 0xfffffc00, v3
	v_sub_u32_e32 v3, v1, v3
	v_ashrrev_i32_e32 v2, 31, v0
	v_lshrrev_b32_e32 v4, 4, v3
	v_lshrrev_b32_e32 v2, 26, v2
	v_bitop3_b32 v3, v4, v3, 32 bitop3:0x6c
	v_add_u32_e32 v2, v0, v2
	v_ashrrev_i32_e32 v5, 31, v3
	v_ashrrev_i32_e32 v2, 6, v2
	v_lshrrev_b32_e32 v5, 26, v5
	v_lshlrev_b32_e32 v4, 3, v2
	v_add_u32_e32 v5, v3, v5
	v_and_b32_e32 v4, -16, v4
	v_ashrrev_i32_e32 v6, 6, v5
	v_and_b32_e32 v5, 0xc0, v5
	v_add_u32_e32 v4, v6, v4
	v_sub_u32_e32 v3, v3, v5
	v_mov_b32_e32 v5, 1
	v_lshlrev_b32_e32 v2, 5, v2
	v_ashrrev_i16_sdwa v3, v5, sext(v3) dst_sel:DWORD dst_unused:UNUSED_PAD src0_sel:DWORD src1_sel:BYTE_0
	v_lshlrev_b32_e32 v7, 1, v4
	v_lshrrev_b32_e32 v8, 2, v4
	v_and_b32_e32 v6, 3, v6
	s_mov_b32 s5, 0x1ffffe0
	v_and_b32_e32 v2, 32, v2
	v_bfe_i32 v3, v3, 0, 16
	v_and_b32_e32 v7, 24, v7
	v_and_b32_e32 v8, 4, v8
	v_and_or_b32 v6, v4, s5, v6
	v_or3_b32 v6, v6, v8, v7
	v_add_lshl_u32 v2, v2, v3, 1
	v_add_u32_e32 v1, 0x2000, v1
	v_lshl_add_u32 v176, v4, 12, v2
	v_lshl_add_u32 v177, v6, 7, v2
	v_ashrrev_i32_e32 v2, 31, v1
	v_lshrrev_b32_e32 v2, 22, v2
	v_add_u32_e32 v2, v1, v2
	v_ashrrev_i32_e32 v2, 10, v2
	v_mul_i32_i24_e32 v3, 0x400, v2
	v_sub_u32_e32 v1, v1, v3
	v_lshrrev_b32_e32 v3, 4, v1
	v_bitop3_b32 v1, v3, v1, 32 bitop3:0x6c
	v_ashrrev_i32_e32 v4, 31, v1
	s_ashr_i32 s37, s35, 6
	s_ashr_i32 s36, s35, 8
	v_lshrrev_b32_e32 v4, 26, v4
	s_waitcnt lgkmcnt(0)
	s_lshl_b32 s20, s37, 10
	v_lshlrev_b32_e32 v3, 3, v2
	v_add_u32_e32 v4, v1, v4
	s_add_u32 s0, s58, s0
	v_and_b32_e32 v3, -16, v3
	v_ashrrev_i32_e32 v6, 6, v4
	v_and_b32_e32 v4, 0xc0, v4
	s_addc_u32 s1, s59, s1
	v_add_u32_e32 v3, v6, v3
	v_sub_u32_e32 v1, v1, v4
	s_add_u32 s18, s0, s4
	v_lshlrev_b32_e32 v2, 5, v2
	v_ashrrev_i16_sdwa v1, v5, sext(v1) dst_sel:DWORD dst_unused:UNUSED_PAD src0_sel:DWORD src1_sel:BYTE_0
	v_lshlrev_b32_e32 v4, 1, v3
	v_lshrrev_b32_e32 v5, 2, v3
	v_and_b32_e32 v6, 3, v6
	s_addc_u32 s19, s1, 0
	s_add_i32 s74, s20, 0
	v_and_b32_e32 v2, 32, v2
	v_bfe_i32 v1, v1, 0, 16
	v_and_b32_e32 v4, 24, v4
	v_and_b32_e32 v5, 4, v5
	v_and_or_b32 v6, v3, s5, v6
	s_add_i32 s75, s74, 0x10000
	v_or3_b32 v4, v6, v5, v4
	v_add_lshl_u32 v1, v2, v1, 1
	s_and_b32 s5, s19, 0xffff
	s_mov_b32 s7, 0x20000
	s_brev_b32 s6, -2
	s_mov_b32 s4, s18
	s_mov_b32 m0, s75
	s_add_i32 s77, s74, 0x12000
	v_lshl_add_u32 v179, v4, 7, v1
	buffer_load_dwordx4 v177, s[4:7], 0 offen lds
	s_mov_b32 m0, s77
	v_lshl_add_u32 v178, v3, 12, v1
	buffer_load_dwordx4 v179, s[4:7], 0 offen lds
	s_add_u32 s4, s18, 0x4000
	s_addc_u32 s0, s19, 0
	s_add_i32 s78, s74, 0x14000
	s_and_b32 s5, s0, 0xffff
	s_mov_b32 m0, s78
	s_add_i32 s79, s74, 0x16000
	buffer_load_dwordx4 v177, s[4:7], 0 offen lds
	s_mov_b32 m0, s79
	s_add_i32 s80, s74, 0x2000
	buffer_load_dwordx4 v179, s[4:7], 0 offen lds
	s_and_b32 s5, s17, 0xffff
	s_mov_b32 s4, s16
	s_mov_b32 m0, s74
	s_mov_b32 s83, 0
	buffer_load_dwordx4 v176, s[4:7], 0 offen lds
	s_mov_b32 m0, s80
	s_nop 0
	buffer_load_dwordx4 v178, s[4:7], 0 offen lds
	s_add_u32 s4, s16, 0x80000
	s_addc_u32 s0, s17, 0
	s_add_i32 s81, s74, 0x4000
	s_and_b32 s5, s0, 0xffff
	s_mov_b32 m0, s81
	s_add_i32 s82, s74, 0x6000
	buffer_load_dwordx4 v176, s[4:7], 0 offen lds
	s_mov_b32 m0, s82
	s_cmp_eq_u32 s36, 1
	buffer_load_dwordx4 v178, s[4:7], 0 offen lds
	s_cselect_b64 s[20:21], -1, 0
	s_cmp_lg_u32 s36, 1
	s_cbranch_scc1 .LBB0_397
	s_setprio 1
	s_barrier

; #define PG8_STAGE(bufoff, gbase, voff) do { const __amdgpu_buffer_rsrc_t _rs = __builtin_amdgcn_make_buffer_rsrc((void*)(gbase), 0, 0x7fffffff, 0x00020000); _Pragma("unroll") for (int _i = 0; _i < 2; ++_i) \
;         __builtin_amdgcn_raw_ptr_buffer_load_lds(_rs, (LAS unsigned*)(lds + (bufoff) + ldsw + _i * 8192), 16, (int)(voff)[_i], 0, 0, 0); } while (0)
; #define PG8_WAIT_V(n) asm volatile("s_waitcnt vmcnt(" #n ")" ::: "memory")
; #define PG8_WAIT_L(n) asm volatile("s_waitcnt lgkmcnt(" #n ")" ::: "memory")
; #define PG8_BAR __builtin_amdgcn_s_barrier()
; #define PG8_SCHED __builtin_amdgcn_sched_barrier(0)
; template <class Epi, class Sched, bool F8 = false>
; __device__ __forceinline__ void gemm_phase(LAS unsigned char* lds, const int lda, const int ldb, const Sched& S, const Epi& E) {
;     ...
;             const char* a1 = cA + (size_t)(t + 1) * kstep;
;             const char* a2 = last ? nA : cA + (size_t)(t + 2) * kstep; const char* b2 = last ? nB : cB + (size_t)(t + 2) * kstepB;
;             const char* a3 = a2 + kstep; const char* b3 = b2 + kstepB;
;     ...
;             PG8_LDB(B0, 0, 0); PG8_LDB(B1, 0, 1); PG8_SCHED; PG8_LDA(At, 0, 0); PG8_STAGE(PG8_SA(1, 1), a1 + hstepA, voffA);
;             PG8_WAIT_V(8); PG8_WAIT_L(0); PG8_BAR; PG8_MMA(0, 0, At, B0); PG8_MMA(0, 1, At, B1); PG8_BAR; PG8_SCHED;
;             PG8_LDA(At, 0, 1); PG8_STAGE(PG8_SB(0, 0), b2, voffB); PG8_STAGE(PG8_SB(0, 1), b2 + hstepB, voffB); PG8_STAGE(PG8_SA(0, 0), a2, voffA);
;             PG8_WAIT_V(8); PG8_WAIT_L(0); PG8_BAR; PG8_MMA(1, 0, At, B0); PG8_MMA(1, 1, At, B1); PG8_BAR; PG8_SCHED;
.LBB0_408:
	ds_read_b128 v[104:107], v180
	ds_read_b128 v[108:111], v180 offset:1024
	ds_read_b128 v[136:139], v180 offset:2048
	ds_read_b128 v[140:143], v180 offset:3072
	ds_read_b128 v[148:151], v181
	ds_read_b128 v[152:155], v181 offset:1024
	ds_read_b128 v[156:159], v181 offset:2048
	ds_read_b128 v[160:163], v181 offset:3072
	s_add_i32 s64, s4, 2
	s_add_u32 s5, vcc_hi, 0xfff80080
	s_addc_u32 s16, s35, -1
	s_cmp_eq_u32 s62, s4
	s_cselect_b32 s40, s70, s5
	s_cselect_b32 s19, s71, s16
	s_cselect_b32 s18, s73, vcc_lo
	s_cselect_b32 s36, s72, s63
	s_add_u32 s16, s40, 0x80
	s_addc_u32 s17, s19, 0
	s_and_b32 s5, s35, 0xffff
	s_mov_b32 s4, vcc_hi
	s_mov_b32 m0, s92
	ds_read_b128 v[164:167], v182
	ds_read_b128 v[168:171], v182 offset:1024
	ds_read_b128 v[172:175], v182 offset:2048
	ds_read_b128 v[186:189], v182 offset:3072
	ds_read_b128 v[190:193], v182 offset:4096
	ds_read_b128 v[194:197], v182 offset:5120
	ds_read_b128 v[198:201], v182 offset:6144
	ds_read_b128 v[202:205], v182 offset:7168
	buffer_load_dwordx4 v176, s[4:7], 0 offen lds
	s_mov_b32 m0, s93
	s_nop 0
	buffer_load_dwordx4 v178, s[4:7], 0 offen lds
	s_waitcnt vmcnt(8)
	s_waitcnt lgkmcnt(0)
	s_barrier
	v_mfma_f32_16x16x32_bf16 v[132:135], v[104:107], v[164:167], v[132:135]
	v_mfma_f32_16x16x32_bf16 v[128:131], v[136:139], v[164:167], v[128:131]
	v_mfma_f32_16x16x32_bf16 v[124:127], v[104:107], v[172:175], v[124:127]
	v_mfma_f32_16x16x32_bf16 v[120:123], v[136:139], v[172:175], v[120:123]
	v_mfma_f32_16x16x32_bf16 v[116:119], v[104:107], v[190:193], v[116:119]
	v_mfma_f32_16x16x32_bf16 v[112:115], v[136:139], v[190:193], v[112:115]
	v_mfma_f32_16x16x32_bf16 v[100:103], v[104:107], v[198:201], v[100:103]
	v_mfma_f32_16x16x32_bf16 v[96:99], v[136:139], v[198:201], v[96:99]
	v_mfma_f32_16x16x32_bf16 v[132:135], v[108:111], v[168:171], v[132:135]
	v_mfma_f32_16x16x32_bf16 v[128:131], v[140:143], v[168:171], v[128:131]
	v_mfma_f32_16x16x32_bf16 v[124:127], v[108:111], v[186:189], v[124:127]
	v_mfma_f32_16x16x32_bf16 v[120:123], v[140:143], v[186:189], v[120:123]
	v_mfma_f32_16x16x32_bf16 v[116:119], v[108:111], v[194:197], v[116:119]
	v_mfma_f32_16x16x32_bf16 v[112:115], v[140:143], v[194:197], v[112:115]
	v_mfma_f32_16x16x32_bf16 v[100:103], v[108:111], v[202:205], v[100:103]
	v_mfma_f32_16x16x32_bf16 v[96:99], v[140:143], v[202:205], v[96:99]
	v_mfma_f32_16x16x32_bf16 v[60:63], v[148:151], v[164:167], v[60:63]
	v_mfma_f32_16x16x32_bf16 v[56:59], v[156:159], v[164:167], v[56:59]
	v_mfma_f32_16x16x32_bf16 v[52:55], v[148:151], v[172:175], v[52:55]
	v_mfma_f32_16x16x32_bf16 v[48:51], v[156:159], v[172:175], v[48:51]
	v_mfma_f32_16x16x32_bf16 v[44:47], v[148:151], v[190:193], v[44:47]
	v_mfma_f32_16x16x32_bf16 v[40:43], v[156:159], v[190:193], v[40:43]
	v_mfma_f32_16x16x32_bf16 v[36:39], v[148:151], v[198:201], v[36:39]
	v_mfma_f32_16x16x32_bf16 v[32:35], v[156:159], v[198:201], v[32:35]
	v_mfma_f32_16x16x32_bf16 v[60:63], v[152:155], v[168:171], v[60:63]
	v_mfma_f32_16x16x32_bf16 v[56:59], v[160:163], v[168:171], v[56:59]
	v_mfma_f32_16x16x32_bf16 v[52:55], v[152:155], v[186:189], v[52:55]
	v_mfma_f32_16x16x32_bf16 v[48:51], v[160:163], v[186:189], v[48:51]
	v_mfma_f32_16x16x32_bf16 v[44:47], v[152:155], v[194:197], v[44:47]
	v_mfma_f32_16x16x32_bf16 v[40:43], v[160:163], v[194:197], v[40:43]
	v_mfma_f32_16x16x32_bf16 v[36:39], v[152:155], v[202:205], v[36:39]
	v_mfma_f32_16x16x32_bf16 v[32:35], v[160:163], v[202:205], v[32:35]
	s_barrier
	s_and_b32 s37, s18, 0xffff
	s_mov_b32 m0, s75
	s_mov_b32 s38, s6
	s_mov_b32 s39, s7
	s_add_u32 s4, s36, 0x4000
	ds_read_b128 v[164:167], v182 offset:16384
	ds_read_b128 v[168:171], v182 offset:17408
	ds_read_b128 v[172:175], v182 offset:18432
	ds_read_b128 v[186:189], v182 offset:19456
	ds_read_b128 v[190:193], v182 offset:20480
	ds_read_b128 v[194:197], v182 offset:21504
	ds_read_b128 v[198:201], v182 offset:22528
	ds_read_b128 v[202:205], v182 offset:23552
	buffer_load_dwordx4 v177, s[36:39], 0 offen lds
	s_mov_b32 m0, s77
	s_addc_u32 s5, s18, 0
	buffer_load_dwordx4 v179, s[36:39], 0 offen lds
	s_and_b32 s5, s5, 0xffff
	s_mov_b32 m0, s78
	s_and_b32 s41, s19, 0xffff
	buffer_load_dwordx4 v177, s[4:7], 0 offen lds
	s_mov_b32 m0, s79
	s_mov_b32 s42, s6
	buffer_load_dwordx4 v179, s[4:7], 0 offen lds
	s_mov_b32 s43, s7
	s_mov_b32 m0, s74
	s_nop 0
	buffer_load_dwordx4 v176, s[40:43], 0 offen lds
	s_mov_b32 m0, s80
	s_nop 0
	buffer_load_dwordx4 v178, s[40:43], 0 offen lds
	s_waitcnt vmcnt(8)
	s_waitcnt lgkmcnt(0)
	s_barrier
	v_mfma_f32_16x16x32_bf16 v[92:95], v[104:107], v[164:167], v[92:95]
	v_mfma_f32_16x16x32_bf16 v[88:91], v[136:139], v[164:167], v[88:91]
	v_mfma_f32_16x16x32_bf16 v[84:87], v[104:107], v[172:175], v[84:87]
	v_mfma_f32_16x16x32_bf16 v[80:83], v[136:139], v[172:175], v[80:83]
	v_mfma_f32_16x16x32_bf16 v[76:79], v[104:107], v[190:193], v[76:79]
	v_mfma_f32_16x16x32_bf16 v[72:75], v[136:139], v[190:193], v[72:75]
	v_mfma_f32_16x16x32_bf16 v[68:71], v[104:107], v[198:201], v[68:71]
	v_mfma_f32_16x16x32_bf16 v[64:67], v[136:139], v[198:201], v[64:67]
	v_mfma_f32_16x16x32_bf16 v[92:95], v[108:111], v[168:171], v[92:95]
	v_mfma_f32_16x16x32_bf16 v[88:91], v[140:143], v[168:171], v[88:91]
	v_mfma_f32_16x16x32_bf16 v[84:87], v[108:111], v[186:189], v[84:87]
	v_mfma_f32_16x16x32_bf16 v[80:83], v[140:143], v[186:189], v[80:83]
	v_mfma_f32_16x16x32_bf16 v[76:79], v[108:111], v[194:197], v[76:79]
	v_mfma_f32_16x16x32_bf16 v[72:75], v[140:143], v[194:197], v[72:75]
	v_mfma_f32_16x16x32_bf16 v[68:71], v[108:111], v[202:205], v[68:71]
	v_mfma_f32_16x16x32_bf16 v[64:67], v[140:143], v[202:205], v[64:67]
	v_mfma_f32_16x16x32_bf16 v[28:31], v[148:151], v[164:167], v[28:31]
	v_mfma_f32_16x16x32_bf16 v[24:27], v[156:159], v[164:167], v[24:27]
	v_mfma_f32_16x16x32_bf16 v[20:23], v[148:151], v[172:175], v[20:23]
	v_mfma_f32_16x16x32_bf16 v[16:19], v[156:159], v[172:175], v[16:19]
	v_mfma_f32_16x16x32_bf16 v[12:15], v[148:151], v[190:193], v[12:15]
	v_mfma_f32_16x16x32_bf16 v[8:11], v[156:159], v[190:193], v[8:11]
	v_mfma_f32_16x16x32_bf16 v[4:7], v[148:151], v[198:201], v[4:7]
	v_mfma_f32_16x16x32_bf16 v[0:3], v[156:159], v[198:201], v[0:3]
	v_mfma_f32_16x16x32_bf16 v[28:31], v[152:155], v[168:171], v[28:31]
	v_mfma_f32_16x16x32_bf16 v[24:27], v[160:163], v[168:171], v[24:27]
	v_mfma_f32_16x16x32_bf16 v[20:23], v[152:155], v[186:189], v[20:23]
	v_mfma_f32_16x16x32_bf16 v[16:19], v[160:163], v[186:189], v[16:19]
	v_mfma_f32_16x16x32_bf16 v[12:15], v[152:155], v[194:197], v[12:15]
	v_mfma_f32_16x16x32_bf16 v[8:11], v[160:163], v[194:197], v[8:11]
	v_mfma_f32_16x16x32_bf16 v[4:7], v[152:155], v[202:205], v[4:7]
	v_mfma_f32_16x16x32_bf16 v[0:3], v[160:163], v[202:205], v[0:3]
	s_barrier
; #define PG8_STAGE(bufoff, gbase, voff) do { const __amdgpu_buffer_rsrc_t _rs = __builtin_amdgcn_make_buffer_rsrc((void*)(gbase), 0, 0x7fffffff, 0x00020000); _Pragma("unroll") for (int _i = 0; _i < 2; ++_i) \
;         __builtin_amdgcn_raw_ptr_buffer_load_lds(_rs, (LAS unsigned*)(lds + (bufoff) + ldsw + _i * 8192), 16, (int)(voff)[_i], 0, 0, 0); } while (0)
; #define PG8_WAIT_V(n) asm volatile("s_waitcnt vmcnt(" #n ")" ::: "memory")
; #define PG8_WAIT_L(n) asm volatile("s_waitcnt lgkmcnt(" #n ")" ::: "memory")
; #define PG8_BAR __builtin_amdgcn_s_barrier()
; #define PG8_SCHED __builtin_amdgcn_sched_barrier(0)
; template <class Epi, class Sched, bool F8 = false>
; __device__ __forceinline__ void gemm_phase(LAS unsigned char* lds, const int lda, const int ldb, const Sched& S, const Epi& E) {
;     ...
;             PG8_LDB(B0, 1, 0); PG8_LDB(B1, 1, 1); PG8_SCHED; PG8_LDA(At, 1, 0); PG8_STAGE(PG8_SA(0, 1), a2 + hstepA, voffA);
;             PG8_WAIT_V(8); PG8_WAIT_L(0); PG8_BAR; PG8_MMA(0, 0, At, B0); PG8_MMA(0, 1, At, B1); PG8_BAR; PG8_SCHED;
;             PG8_LDA(At, 1, 1); PG8_STAGE(PG8_SB(1, 0), b3, voffB); PG8_STAGE(PG8_SB(1, 1), b3 + hstepB, voffB); PG8_STAGE(PG8_SA(1, 0), a3, voffA);
;             PG8_WAIT_V(8); PG8_WAIT_L(0); PG8_BAR; PG8_MMA(1, 0, At, B0); PG8_MMA(1, 1, At, B1); PG8_BAR; PG8_SCHED;
	ds_read_b128 v[104:107], v183
	ds_read_b128 v[108:111], v183 offset:1024
	ds_read_b128 v[136:139], v183 offset:2048
	ds_read_b128 v[140:143], v183 offset:3072
	ds_read_b128 v[148:151], v184
	ds_read_b128 v[152:155], v184 offset:1024
	ds_read_b128 v[156:159], v184 offset:2048
	ds_read_b128 v[160:163], v184 offset:3072
	s_add_u32 s4, s40, 0x80000
	s_addc_u32 s5, s19, 0
	s_and_b32 s5, s5, 0xffff
	s_mov_b32 m0, s81
	ds_read_b128 v[164:167], v182 offset:32768
	ds_read_b128 v[168:171], v182 offset:33792
	ds_read_b128 v[172:175], v182 offset:34816
	ds_read_b128 v[186:189], v182 offset:35840
	ds_read_b128 v[190:193], v182 offset:36864
	ds_read_b128 v[194:197], v182 offset:37888
	ds_read_b128 v[198:201], v182 offset:38912
	ds_read_b128 v[202:205], v182 offset:39936
	buffer_load_dwordx4 v176, s[4:7], 0 offen lds
	s_mov_b32 m0, s82
	s_nop 0
	buffer_load_dwordx4 v178, s[4:7], 0 offen lds
	s_waitcnt vmcnt(8)
	s_waitcnt lgkmcnt(0)
	s_barrier
	v_mfma_f32_16x16x32_bf16 v[132:135], v[104:107], v[164:167], v[132:135]
	v_mfma_f32_16x16x32_bf16 v[128:131], v[136:139], v[164:167], v[128:131]
	v_mfma_f32_16x16x32_bf16 v[124:127], v[104:107], v[172:175], v[124:127]
	v_mfma_f32_16x16x32_bf16 v[120:123], v[136:139], v[172:175], v[120:123]
	v_mfma_f32_16x16x32_bf16 v[116:119], v[104:107], v[190:193], v[116:119]
	v_mfma_f32_16x16x32_bf16 v[112:115], v[136:139], v[190:193], v[112:115]
	v_mfma_f32_16x16x32_bf16 v[100:103], v[104:107], v[198:201], v[100:103]
	v_mfma_f32_16x16x32_bf16 v[96:99], v[136:139], v[198:201], v[96:99]
	v_mfma_f32_16x16x32_bf16 v[132:135], v[108:111], v[168:171], v[132:135]
	v_mfma_f32_16x16x32_bf16 v[128:131], v[140:143], v[168:171], v[128:131]
	v_mfma_f32_16x16x32_bf16 v[124:127], v[108:111], v[186:189], v[124:127]
	v_mfma_f32_16x16x32_bf16 v[120:123], v[140:143], v[186:189], v[120:123]
	v_mfma_f32_16x16x32_bf16 v[116:119], v[108:111], v[194:197], v[116:119]
	v_mfma_f32_16x16x32_bf16 v[112:115], v[140:143], v[194:197], v[112:115]
	v_mfma_f32_16x16x32_bf16 v[100:103], v[108:111], v[202:205], v[100:103]
	v_mfma_f32_16x16x32_bf16 v[96:99], v[140:143], v[202:205], v[96:99]
	v_mfma_f32_16x16x32_bf16 v[60:63], v[148:151], v[164:167], v[60:63]
	v_mfma_f32_16x16x32_bf16 v[56:59], v[156:159], v[164:167], v[56:59]
	v_mfma_f32_16x16x32_bf16 v[52:55], v[148:151], v[172:175], v[52:55]
	v_mfma_f32_16x16x32_bf16 v[48:51], v[156:159], v[172:175], v[48:51]
	v_mfma_f32_16x16x32_bf16 v[44:47], v[148:151], v[190:193], v[44:47]
	v_mfma_f32_16x16x32_bf16 v[40:43], v[156:159], v[190:193], v[40:43]
	v_mfma_f32_16x16x32_bf16 v[36:39], v[148:151], v[198:201], v[36:39]
	v_mfma_f32_16x16x32_bf16 v[32:35], v[156:159], v[198:201], v[32:35]
	v_mfma_f32_16x16x32_bf16 v[60:63], v[152:155], v[168:171], v[60:63]
	v_mfma_f32_16x16x32_bf16 v[56:59], v[160:163], v[168:171], v[56:59]
	v_mfma_f32_16x16x32_bf16 v[52:55], v[152:155], v[186:189], v[52:55]
	v_mfma_f32_16x16x32_bf16 v[48:51], v[160:163], v[186:189], v[48:51]
	v_mfma_f32_16x16x32_bf16 v[44:47], v[152:155], v[194:197], v[44:47]
	v_mfma_f32_16x16x32_bf16 v[40:43], v[160:163], v[194:197], v[40:43]
	v_mfma_f32_16x16x32_bf16 v[36:39], v[152:155], v[202:205], v[36:39]
	v_mfma_f32_16x16x32_bf16 v[32:35], v[160:163], v[202:205], v[32:35]
	s_barrier
	s_add_u32 s4, s36, 0x8000
	s_addc_u32 s5, s18, 0
	s_mov_b32 m0, s86
	s_and_b32 s5, s5, 0xffff
	ds_read_b128 v[164:167], v182 offset:49152
	ds_read_b128 v[168:171], v182 offset:50176
	ds_read_b128 v[172:175], v182 offset:51200
	ds_read_b128 v[186:189], v182 offset:52224
	ds_read_b128 v[190:193], v182 offset:53248
	ds_read_b128 v[194:197], v182 offset:54272
	ds_read_b128 v[198:201], v182 offset:55296
	ds_read_b128 v[202:205], v182 offset:56320
	buffer_load_dwordx4 v177, s[4:7], 0 offen lds
	s_mov_b32 m0, s87
	s_mov_b32 s19, s7
	buffer_load_dwordx4 v179, s[4:7], 0 offen lds
	s_add_u32 s4, s36, 0xc000
	s_addc_u32 s5, s18, 0
	s_and_b32 s5, s5, 0xffff
	s_mov_b32 m0, s90
	s_and_b32 s17, s17, 0xffff
	buffer_load_dwordx4 v177, s[4:7], 0 offen lds
	s_mov_b32 m0, s91
	s_mov_b32 s18, s6
	buffer_load_dwordx4 v179, s[4:7], 0 offen lds
	s_mov_b32 m0, s88
	s_nop 0
	buffer_load_dwordx4 v176, s[16:19], 0 offen lds
	s_mov_b32 m0, s89
	s_nop 0
	buffer_load_dwordx4 v178, s[16:19], 0 offen lds
	s_waitcnt vmcnt(8)
	s_waitcnt lgkmcnt(0)
	s_barrier
	v_mfma_f32_16x16x32_bf16 v[92:95], v[104:107], v[164:167], v[92:95]
	v_mfma_f32_16x16x32_bf16 v[88:91], v[136:139], v[164:167], v[88:91]
	v_mfma_f32_16x16x32_bf16 v[84:87], v[104:107], v[172:175], v[84:87]
	v_mfma_f32_16x16x32_bf16 v[80:83], v[136:139], v[172:175], v[80:83]
	v_mfma_f32_16x16x32_bf16 v[76:79], v[104:107], v[190:193], v[76:79]
	v_mfma_f32_16x16x32_bf16 v[72:75], v[136:139], v[190:193], v[72:75]
	v_mfma_f32_16x16x32_bf16 v[68:71], v[104:107], v[198:201], v[68:71]
	v_mfma_f32_16x16x32_bf16 v[64:67], v[136:139], v[198:201], v[64:67]
	v_mfma_f32_16x16x32_bf16 v[92:95], v[108:111], v[168:171], v[92:95]
	v_mfma_f32_16x16x32_bf16 v[88:91], v[140:143], v[168:171], v[88:91]
	v_mfma_f32_16x16x32_bf16 v[84:87], v[108:111], v[186:189], v[84:87]
	v_mfma_f32_16x16x32_bf16 v[80:83], v[140:143], v[186:189], v[80:83]
	v_mfma_f32_16x16x32_bf16 v[76:79], v[108:111], v[194:197], v[76:79]
	v_mfma_f32_16x16x32_bf16 v[72:75], v[140:143], v[194:197], v[72:75]
	v_mfma_f32_16x16x32_bf16 v[68:71], v[108:111], v[202:205], v[68:71]
	v_mfma_f32_16x16x32_bf16 v[64:67], v[140:143], v[202:205], v[64:67]
	v_mfma_f32_16x16x32_bf16 v[28:31], v[148:151], v[164:167], v[28:31]
	v_mfma_f32_16x16x32_bf16 v[24:27], v[156:159], v[164:167], v[24:27]
	v_mfma_f32_16x16x32_bf16 v[20:23], v[148:151], v[172:175], v[20:23]
	v_mfma_f32_16x16x32_bf16 v[16:19], v[156:159], v[172:175], v[16:19]
	v_mfma_f32_16x16x32_bf16 v[12:15], v[148:151], v[190:193], v[12:15]
	v_mfma_f32_16x16x32_bf16 v[8:11], v[156:159], v[190:193], v[8:11]
	v_mfma_f32_16x16x32_bf16 v[4:7], v[148:151], v[198:201], v[4:7]
	v_mfma_f32_16x16x32_bf16 v[0:3], v[156:159], v[198:201], v[0:3]
	v_mfma_f32_16x16x32_bf16 v[28:31], v[152:155], v[168:171], v[28:31]
	v_mfma_f32_16x16x32_bf16 v[24:27], v[160:163], v[168:171], v[24:27]
	v_mfma_f32_16x16x32_bf16 v[20:23], v[152:155], v[186:189], v[20:23]
	v_mfma_f32_16x16x32_bf16 v[16:19], v[160:163], v[186:189], v[16:19]
	v_mfma_f32_16x16x32_bf16 v[12:15], v[152:155], v[194:197], v[12:15]
	v_mfma_f32_16x16x32_bf16 v[8:11], v[160:163], v[194:197], v[8:11]
	v_mfma_f32_16x16x32_bf16 v[4:7], v[152:155], v[202:205], v[4:7]
	v_mfma_f32_16x16x32_bf16 v[0:3], v[160:163], v[202:205], v[0:3]
	s_barrier
	s_add_u32 s63, s63, 0x10000
	s_addc_u32 vcc_lo, vcc_lo, 0
	s_add_u32 vcc_hi, vcc_hi, 0x100
	s_addc_u32 s35, s35, 0
	s_cmp_ge_i32 s64, s9
	s_mov_b32 s4, s64
	s_cbranch_scc0 .LBB0_408
	s_and_b64 vcc, exec, s[66:67]
	s_cbranch_vccz .LBB0_411
	s_barrier

; #define PG8_WAIT_V(n) asm volatile("s_waitcnt vmcnt(" #n ")" ::: "memory")
; #define PG8_BAR __builtin_amdgcn_s_barrier()
; template <class Epi, class Sched, bool F8 = false>
; __device__ __forceinline__ void gemm_phase(LAS unsigned char* lds, const int lda, const int ldb, const Sched& S, const Epi& E) {
;     ...
;     PG8_WAIT_V(0);
;     PG8_BAR;
.LBB0_418:
	s_waitcnt vmcnt(0)
	v_readlane_b32 s96, v255, 4
	v_readlane_b32 s88, v255, 7
	v_readlane_b32 s97, v255, 5
	v_readlane_b32 s95, v255, 6
	v_readlane_b32 s89, v255, 8
	s_setprio 0
	s_barrier

; #define PG8_STAGE(bufoff, gbase, voff) do { const __amdgpu_buffer_rsrc_t _rs = __builtin_amdgcn_make_buffer_rsrc((void*)(gbase), 0, 0x7fffffff, 0x00020000); _Pragma("unroll") for (int _i = 0; _i < 2; ++_i) \
;         __builtin_amdgcn_raw_ptr_buffer_load_lds(_rs, (LAS unsigned*)(lds + (bufoff) + ldsw + _i * 8192), 16, (int)(voff)[_i], 0, 0, 0); } while (0)
; #define PG8_BAR __builtin_amdgcn_s_barrier()
; template <class Epi, class Sched, bool F8 = false>
; __device__ __forceinline__ void gemm_phase(LAS unsigned char* lds, const int lda, const int ldb, const Sched& S, const Epi& E) {
;     ...
;     for (int i = 0; i < 2; ++i) { int R, C; stage_rc(tid * 16 + i * 8192, R, C); const int Rb = Epi::PERM ? ((R & ~31) + perm32(R & 31)) : R;
;         voffA[i] = (unsigned)(R * lda + C * 2); voffB[i] = (unsigned)(Rb * 128 + C * 2); }
;     ...
;     PG8_STAGE(PG8_SB(0, 0), cB, voffB); PG8_STAGE(PG8_SB(0, 1), cB + hstepB, voffB); PG8_STAGE(PG8_SA(0, 0), cA, voffA); PG8_STAGE(PG8_SA(0, 1), cA + hstepA, voffA);
;     if (wr == 1) PG8_BAR;
.LBB0_477:
	v_bfe_i32 v3, v0, 27, 1
	v_lshlrev_b32_e32 v1, 4, v0
	v_lshrrev_b32_e32 v3, 22, v3
	v_add_u32_e32 v3, v1, v3
	v_and_b32_e32 v3, 0xfffffc00, v3
	v_sub_u32_e32 v3, v1, v3
	v_ashrrev_i32_e32 v2, 31, v0
	v_lshrrev_b32_e32 v4, 4, v3
	v_lshrrev_b32_e32 v2, 26, v2
	v_bitop3_b32 v3, v4, v3, 32 bitop3:0x6c
	v_add_u32_e32 v2, v0, v2
	v_ashrrev_i32_e32 v5, 31, v3
	v_ashrrev_i32_e32 v2, 6, v2
	v_lshrrev_b32_e32 v5, 26, v5
	v_lshlrev_b32_e32 v4, 3, v2
	v_add_u32_e32 v5, v3, v5
	v_and_b32_e32 v4, -16, v4
	v_ashrrev_i32_e32 v6, 6, v5
	v_and_b32_e32 v5, 0xc0, v5
	v_add_u32_e32 v4, v6, v4
	v_sub_u32_e32 v3, v3, v5
	v_mov_b32_e32 v5, 1
	v_lshlrev_b32_e32 v2, 5, v2
	v_ashrrev_i16_sdwa v3, v5, sext(v3) dst_sel:DWORD dst_unused:UNUSED_PAD src0_sel:DWORD src1_sel:BYTE_0
	v_lshlrev_b32_e32 v7, 1, v4
	v_lshrrev_b32_e32 v8, 2, v4
	v_and_b32_e32 v6, 3, v6
	s_mov_b32 s1, 0x1ffffe0
	v_and_b32_e32 v2, 32, v2
	v_bfe_i32 v3, v3, 0, 16
	v_and_b32_e32 v7, 24, v7
	v_and_b32_e32 v8, 4, v8
	v_and_or_b32 v6, v4, s1, v6
	v_or3_b32 v6, v6, v8, v7
	v_add_lshl_u32 v2, v2, v3, 1
	v_add_u32_e32 v1, 0x2000, v1
	v_lshl_add_u32 v148, v4, 12, v2
	v_lshl_add_u32 v149, v6, 7, v2
	v_ashrrev_i32_e32 v2, 31, v1
	v_lshrrev_b32_e32 v2, 22, v2
	v_add_u32_e32 v2, v1, v2
	v_ashrrev_i32_e32 v2, 10, v2
	v_mul_i32_i24_e32 v3, 0x400, v2
	v_sub_u32_e32 v1, v1, v3
	v_lshrrev_b32_e32 v3, 4, v1
	v_bitop3_b32 v1, v3, v1, 32 bitop3:0x6c
	v_ashrrev_i32_e32 v4, 31, v1
	v_lshrrev_b32_e32 v4, 26, v4
	v_lshlrev_b32_e32 v3, 3, v2
	v_add_u32_e32 v4, v1, v4
	v_and_b32_e32 v3, -16, v3
	v_ashrrev_i32_e32 v6, 6, v4
	v_add_u32_e32 v3, v6, v3
	v_and_b32_e32 v6, 3, v6
	v_and_b32_e32 v4, 0xc0, v4
	v_and_or_b32 v6, v3, s1, v6
	s_ashr_i32 s1, s9, 6
	v_sub_u32_e32 v1, v1, v4
	s_lshl_b32 s8, s1, 10
	v_lshlrev_b32_e32 v2, 5, v2
	v_ashrrev_i16_sdwa v1, v5, sext(v1) dst_sel:DWORD dst_unused:UNUSED_PAD src0_sel:DWORD src1_sel:BYTE_0
	v_lshlrev_b32_e32 v4, 1, v3
	v_lshrrev_b32_e32 v5, 2, v3
	s_add_i32 s67, s8, 0
	v_and_b32_e32 v2, 32, v2
	v_bfe_i32 v1, v1, 0, 16
	v_and_b32_e32 v4, 24, v4
	v_and_b32_e32 v5, 4, v5
	s_add_i32 s70, s67, 0x10000
	v_or3_b32 v4, v6, v5, v4
	v_add_lshl_u32 v1, v2, v1, 1
	s_waitcnt lgkmcnt(0)
	s_and_b32 s5, s19, 0xffff
	s_mov_b32 s7, 0x20000
	s_brev_b32 s6, -2
	s_mov_b32 s4, s18
	s_mov_b32 m0, s70
	s_add_i32 s71, s67, 0x12000
	s_ashr_i32 s0, s9, 8
	v_lshl_add_u32 v151, v4, 7, v1
	buffer_load_dwordx4 v149, s[4:7], 0 offen lds
	s_mov_b32 m0, s71
	v_lshl_add_u32 v150, v3, 12, v1
	buffer_load_dwordx4 v151, s[4:7], 0 offen lds
	s_add_u32 s4, s18, 0x4000
	s_addc_u32 s5, s19, 0
	s_add_i32 s72, s67, 0x14000
	s_and_b32 s5, s5, 0xffff
	s_mov_b32 m0, s72
	s_add_i32 s73, s67, 0x16000
	buffer_load_dwordx4 v149, s[4:7], 0 offen lds
	s_mov_b32 m0, s73
	s_add_i32 s74, s67, 0x2000
	buffer_load_dwordx4 v151, s[4:7], 0 offen lds
	s_and_b32 s5, s17, 0xffff
	s_mov_b32 s4, s16
	s_mov_b32 m0, s67
	s_mov_b32 s8, 0
	buffer_load_dwordx4 v148, s[4:7], 0 offen lds
	s_mov_b32 m0, s74
	s_movk_i32 s77, 0x4000
	buffer_load_dwordx4 v150, s[4:7], 0 offen lds
	s_add_u32 s4, s16, 0x80000
	s_addc_u32 s5, s17, 0
	s_add_i32 s75, s67, 0x4000
	s_and_b32 s5, s5, 0xffff
	s_mov_b32 m0, s75
	s_add_i32 s76, s67, 0x6000
	buffer_load_dwordx4 v148, s[4:7], 0 offen lds
	s_mov_b32 m0, s76
	s_cmp_eq_u32 s0, 1
	buffer_load_dwordx4 v150, s[4:7], 0 offen lds
	s_cselect_b64 s[14:15], -1, 0
	s_cmp_lg_u32 s0, 1
	s_movk_i32 s78, 0x6000
	s_cbranch_scc1 .LBB0_479
	s_setprio 1
	s_barrier

; #define PG8_STAGE(bufoff, gbase, voff) do { const __amdgpu_buffer_rsrc_t _rs = __builtin_amdgcn_make_buffer_rsrc((void*)(gbase), 0, 0x7fffffff, 0x00020000); _Pragma("unroll") for (int _i = 0; _i < 2; ++_i) \
;         __builtin_amdgcn_raw_ptr_buffer_load_lds(_rs, (LAS unsigned*)(lds + (bufoff) + ldsw + _i * 8192), 16, (int)(voff)[_i], 0, 0, 0); } while (0)
; #define PG8_WAIT_V(n) asm volatile("s_waitcnt vmcnt(" #n ")" ::: "memory")
; #define PG8_WAIT_L(n) asm volatile("s_waitcnt lgkmcnt(" #n ")" ::: "memory")
; #define PG8_BAR __builtin_amdgcn_s_barrier()
; #define PG8_SCHED __builtin_amdgcn_sched_barrier(0)
; template <class Epi, class Sched, bool F8 = false>
; __device__ __forceinline__ void gemm_phase(LAS unsigned char* lds, const int lda, const int ldb, const Sched& S, const Epi& E) {
;     ...
;             const char* a1 = cA + (size_t)(t + 1) * kstep;
;             const char* a2 = last ? nA : cA + (size_t)(t + 2) * kstep; const char* b2 = last ? nB : cB + (size_t)(t + 2) * kstepB;
;             const char* a3 = a2 + kstep; const char* b3 = b2 + kstepB;
;     ...
;             PG8_LDB(B0, 0, 0); PG8_LDB(B1, 0, 1); PG8_SCHED; PG8_LDA(At, 0, 0); PG8_STAGE(PG8_SA(1, 1), a1 + hstepA, voffA);
;             PG8_WAIT_V(8); PG8_WAIT_L(0); PG8_BAR; PG8_MMA(0, 0, At, B0); PG8_MMA(0, 1, At, B1); PG8_BAR; PG8_SCHED;
;             PG8_LDA(At, 0, 1); PG8_STAGE(PG8_SB(0, 0), b2, voffB); PG8_STAGE(PG8_SB(0, 1), b2 + hstepB, voffB); PG8_STAGE(PG8_SA(0, 0), a2, voffA);
;             PG8_WAIT_V(8); PG8_WAIT_L(0); PG8_BAR; PG8_MMA(1, 0, At, B0); PG8_MMA(1, 1, At, B1); PG8_BAR; PG8_SCHED;
.LBB0_485:
	v_add_u32_e32 v144, 0x10000, v152
	v_add_u32_e32 v166, 0x14000, v152
	ds_read_b128 v[132:135], v144
	ds_read_b128 v[136:139], v144 offset:1024
	ds_read_b128 v[140:143], v144 offset:2048
	ds_read_b128 v[144:147], v144 offset:3072
	ds_read_b128 v[154:157], v166
	ds_read_b128 v[158:161], v166 offset:1024
	ds_read_b128 v[162:165], v166 offset:2048
	ds_read_b128 v[166:169], v166 offset:3072
	s_add_u32 s4, s47, 0xfff80080
	s_addc_u32 s5, s62, -1
	s_cmp_eq_u32 s63, 28
	s_cselect_b32 s40, s48, s4
	s_cselect_b32 s19, s49, s5
	s_cselect_b32 s18, s51, s33
	s_cselect_b32 s36, s50, s9
	s_add_u32 s16, s40, 0x80
	s_addc_u32 s17, s19, 0
	s_and_b32 s5, s62, 0xffff
	s_mov_b32 s4, s47
	s_mov_b32 m0, s91
	ds_read_b128 v[170:173], v153
	ds_read_b128 v[174:177], v153 offset:1024
	ds_read_b128 v[178:181], v153 offset:2048
	ds_read_b128 v[182:185], v153 offset:3072
	ds_read_b128 v[186:189], v153 offset:4096
	ds_read_b128 v[190:193], v153 offset:5120
	ds_read_b128 v[194:197], v153 offset:6144
	ds_read_b128 v[198:201], v153 offset:7168
	buffer_load_dwordx4 v148, s[4:7], 0 offen lds
	s_mov_b32 m0, s92
	s_nop 0
	buffer_load_dwordx4 v150, s[4:7], 0 offen lds
	s_waitcnt vmcnt(8)
	s_waitcnt lgkmcnt(0)
	s_barrier
	v_mfma_f32_16x16x32_bf16 v[124:127], v[132:135], v[170:173], v[124:127]
	v_mfma_f32_16x16x32_bf16 v[120:123], v[140:143], v[170:173], v[120:123]
	v_mfma_f32_16x16x32_bf16 v[116:119], v[132:135], v[178:181], v[116:119]
	v_mfma_f32_16x16x32_bf16 v[112:115], v[140:143], v[178:181], v[112:115]
	v_mfma_f32_16x16x32_bf16 v[108:111], v[132:135], v[186:189], v[108:111]
	v_mfma_f32_16x16x32_bf16 v[104:107], v[140:143], v[186:189], v[104:107]
	v_mfma_f32_16x16x32_bf16 v[100:103], v[132:135], v[194:197], v[100:103]
	v_mfma_f32_16x16x32_bf16 v[96:99], v[140:143], v[194:197], v[96:99]
	v_mfma_f32_16x16x32_bf16 v[124:127], v[136:139], v[174:177], v[124:127]
	v_mfma_f32_16x16x32_bf16 v[120:123], v[144:147], v[174:177], v[120:123]
	v_mfma_f32_16x16x32_bf16 v[116:119], v[136:139], v[182:185], v[116:119]
	v_mfma_f32_16x16x32_bf16 v[112:115], v[144:147], v[182:185], v[112:115]
	v_mfma_f32_16x16x32_bf16 v[108:111], v[136:139], v[190:193], v[108:111]
	v_mfma_f32_16x16x32_bf16 v[104:107], v[144:147], v[190:193], v[104:107]
	v_mfma_f32_16x16x32_bf16 v[100:103], v[136:139], v[198:201], v[100:103]
	v_mfma_f32_16x16x32_bf16 v[96:99], v[144:147], v[198:201], v[96:99]
	v_mfma_f32_16x16x32_bf16 v[92:95], v[154:157], v[170:173], v[92:95]
	v_mfma_f32_16x16x32_bf16 v[88:91], v[162:165], v[170:173], v[88:91]
	v_mfma_f32_16x16x32_bf16 v[84:87], v[154:157], v[178:181], v[84:87]
	v_mfma_f32_16x16x32_bf16 v[80:83], v[162:165], v[178:181], v[80:83]
	v_mfma_f32_16x16x32_bf16 v[76:79], v[154:157], v[186:189], v[76:79]
	v_mfma_f32_16x16x32_bf16 v[72:75], v[162:165], v[186:189], v[72:75]
	v_mfma_f32_16x16x32_bf16 v[68:71], v[154:157], v[194:197], v[68:71]
	v_mfma_f32_16x16x32_bf16 v[64:67], v[162:165], v[194:197], v[64:67]
	v_mfma_f32_16x16x32_bf16 v[92:95], v[158:161], v[174:177], v[92:95]
	v_mfma_f32_16x16x32_bf16 v[88:91], v[166:169], v[174:177], v[88:91]
	v_mfma_f32_16x16x32_bf16 v[84:87], v[158:161], v[182:185], v[84:87]
	v_mfma_f32_16x16x32_bf16 v[80:83], v[166:169], v[182:185], v[80:83]
	v_mfma_f32_16x16x32_bf16 v[76:79], v[158:161], v[190:193], v[76:79]
	v_mfma_f32_16x16x32_bf16 v[72:75], v[166:169], v[190:193], v[72:75]
	v_mfma_f32_16x16x32_bf16 v[68:71], v[158:161], v[198:201], v[68:71]
	v_mfma_f32_16x16x32_bf16 v[64:67], v[166:169], v[198:201], v[64:67]
	s_barrier
	s_and_b32 s37, s18, 0xffff
	s_mov_b32 m0, s70
	s_mov_b32 s38, s6
	s_mov_b32 s39, s7
	s_add_u32 s4, s36, 0x4000
	ds_read_b128 v[170:173], v153 offset:16384
	ds_read_b128 v[174:177], v153 offset:17408
	ds_read_b128 v[178:181], v153 offset:18432
	ds_read_b128 v[182:185], v153 offset:19456
	ds_read_b128 v[186:189], v153 offset:20480
	ds_read_b128 v[190:193], v153 offset:21504
	ds_read_b128 v[194:197], v153 offset:22528
	ds_read_b128 v[198:201], v153 offset:23552
	buffer_load_dwordx4 v149, s[36:39], 0 offen lds
	s_mov_b32 m0, s71
	s_addc_u32 s5, s18, 0
	buffer_load_dwordx4 v151, s[36:39], 0 offen lds
	s_and_b32 s5, s5, 0xffff
	s_mov_b32 m0, s72
	s_and_b32 s41, s19, 0xffff
	buffer_load_dwordx4 v149, s[4:7], 0 offen lds
	s_mov_b32 m0, s73
	s_mov_b32 s42, s6
	buffer_load_dwordx4 v151, s[4:7], 0 offen lds
	s_mov_b32 s43, s7
	s_mov_b32 m0, s67
	s_nop 0
	buffer_load_dwordx4 v148, s[40:43], 0 offen lds
	s_mov_b32 m0, s74
	s_nop 0
	buffer_load_dwordx4 v150, s[40:43], 0 offen lds
	s_waitcnt vmcnt(8)
	s_waitcnt lgkmcnt(0)
	s_barrier
	v_mfma_f32_16x16x32_bf16 v[60:63], v[132:135], v[170:173], v[60:63]
	v_mfma_f32_16x16x32_bf16 v[56:59], v[140:143], v[170:173], v[56:59]
	v_mfma_f32_16x16x32_bf16 v[52:55], v[132:135], v[178:181], v[52:55]
	v_mfma_f32_16x16x32_bf16 v[48:51], v[140:143], v[178:181], v[48:51]
	v_mfma_f32_16x16x32_bf16 v[44:47], v[132:135], v[186:189], v[44:47]
	v_mfma_f32_16x16x32_bf16 v[40:43], v[140:143], v[186:189], v[40:43]
	v_mfma_f32_16x16x32_bf16 v[36:39], v[132:135], v[194:197], v[36:39]
	v_mfma_f32_16x16x32_bf16 v[32:35], v[140:143], v[194:197], v[32:35]
	v_mfma_f32_16x16x32_bf16 v[60:63], v[136:139], v[174:177], v[60:63]
	v_mfma_f32_16x16x32_bf16 v[56:59], v[144:147], v[174:177], v[56:59]
	v_mfma_f32_16x16x32_bf16 v[52:55], v[136:139], v[182:185], v[52:55]
	v_mfma_f32_16x16x32_bf16 v[48:51], v[144:147], v[182:185], v[48:51]
	v_mfma_f32_16x16x32_bf16 v[44:47], v[136:139], v[190:193], v[44:47]
	v_mfma_f32_16x16x32_bf16 v[40:43], v[144:147], v[190:193], v[40:43]
	v_mfma_f32_16x16x32_bf16 v[36:39], v[136:139], v[198:201], v[36:39]
	v_mfma_f32_16x16x32_bf16 v[32:35], v[144:147], v[198:201], v[32:35]
	v_mfma_f32_16x16x32_bf16 v[28:31], v[154:157], v[170:173], v[28:31]
	v_mfma_f32_16x16x32_bf16 v[24:27], v[162:165], v[170:173], v[24:27]
	v_mfma_f32_16x16x32_bf16 v[20:23], v[154:157], v[178:181], v[20:23]
	v_mfma_f32_16x16x32_bf16 v[16:19], v[162:165], v[178:181], v[16:19]
	v_mfma_f32_16x16x32_bf16 v[12:15], v[154:157], v[186:189], v[12:15]
	v_mfma_f32_16x16x32_bf16 v[8:11], v[162:165], v[186:189], v[8:11]
	v_mfma_f32_16x16x32_bf16 v[4:7], v[154:157], v[194:197], v[4:7]
	v_mfma_f32_16x16x32_bf16 v[0:3], v[162:165], v[194:197], v[0:3]
	v_mfma_f32_16x16x32_bf16 v[28:31], v[158:161], v[174:177], v[28:31]
	v_mfma_f32_16x16x32_bf16 v[24:27], v[166:169], v[174:177], v[24:27]
	v_mfma_f32_16x16x32_bf16 v[20:23], v[158:161], v[182:185], v[20:23]
	v_mfma_f32_16x16x32_bf16 v[16:19], v[166:169], v[182:185], v[16:19]
	v_mfma_f32_16x16x32_bf16 v[12:15], v[158:161], v[190:193], v[12:15]
	v_mfma_f32_16x16x32_bf16 v[8:11], v[166:169], v[190:193], v[8:11]
	v_mfma_f32_16x16x32_bf16 v[4:7], v[158:161], v[198:201], v[4:7]
	v_mfma_f32_16x16x32_bf16 v[0:3], v[166:169], v[198:201], v[0:3]
	s_barrier
; #define PG8_STAGE(bufoff, gbase, voff) do { const __amdgpu_buffer_rsrc_t _rs = __builtin_amdgcn_make_buffer_rsrc((void*)(gbase), 0, 0x7fffffff, 0x00020000); _Pragma("unroll") for (int _i = 0; _i < 2; ++_i) \
;         __builtin_amdgcn_raw_ptr_buffer_load_lds(_rs, (LAS unsigned*)(lds + (bufoff) + ldsw + _i * 8192), 16, (int)(voff)[_i], 0, 0, 0); } while (0)
; #define PG8_WAIT_V(n) asm volatile("s_waitcnt vmcnt(" #n ")" ::: "memory")
; #define PG8_WAIT_L(n) asm volatile("s_waitcnt lgkmcnt(" #n ")" ::: "memory")
; #define PG8_BAR __builtin_amdgcn_s_barrier()
; #define PG8_SCHED __builtin_amdgcn_sched_barrier(0)
; template <class Epi, class Sched, bool F8 = false>
; __device__ __forceinline__ void gemm_phase(LAS unsigned char* lds, const int lda, const int ldb, const Sched& S, const Epi& E) {
;     ...
;             PG8_LDB(B0, 1, 0); PG8_LDB(B1, 1, 1); PG8_SCHED; PG8_LDA(At, 1, 0); PG8_STAGE(PG8_SA(0, 1), a2 + hstepA, voffA);
;             PG8_WAIT_V(8); PG8_WAIT_L(0); PG8_BAR; PG8_MMA(0, 0, At, B0); PG8_MMA(0, 1, At, B1); PG8_BAR; PG8_SCHED;
;             PG8_LDA(At, 1, 1); PG8_STAGE(PG8_SB(1, 0), b3, voffB); PG8_STAGE(PG8_SB(1, 1), b3 + hstepB, voffB); PG8_STAGE(PG8_SA(1, 0), a3, voffA);
;             PG8_WAIT_V(8); PG8_WAIT_L(0); PG8_BAR; PG8_MMA(1, 0, At, B0); PG8_MMA(1, 1, At, B1); PG8_BAR; PG8_SCHED;
	v_add_u32_e32 v144, 0x18000, v152
	v_add_u32_e32 v166, 0x1c000, v152
	ds_read_b128 v[132:135], v144
	ds_read_b128 v[136:139], v144 offset:1024
	ds_read_b128 v[140:143], v144 offset:2048
	ds_read_b128 v[144:147], v144 offset:3072
	ds_read_b128 v[154:157], v166
	ds_read_b128 v[158:161], v166 offset:1024
	ds_read_b128 v[162:165], v166 offset:2048
	ds_read_b128 v[166:169], v166 offset:3072
	s_add_u32 s4, s40, 0x80000
	s_addc_u32 s5, s19, 0
	s_and_b32 s5, s5, 0xffff
	s_mov_b32 m0, s75
	ds_read_b128 v[170:173], v153 offset:32768
	ds_read_b128 v[174:177], v153 offset:33792
	ds_read_b128 v[178:181], v153 offset:34816
	ds_read_b128 v[182:185], v153 offset:35840
	ds_read_b128 v[186:189], v153 offset:36864
	ds_read_b128 v[190:193], v153 offset:37888
	ds_read_b128 v[194:197], v153 offset:38912
	ds_read_b128 v[198:201], v153 offset:39936
	buffer_load_dwordx4 v148, s[4:7], 0 offen lds
	s_mov_b32 m0, s76
	s_nop 0
	buffer_load_dwordx4 v150, s[4:7], 0 offen lds
	s_waitcnt vmcnt(8)
	s_waitcnt lgkmcnt(0)
	s_barrier
	v_mfma_f32_16x16x32_bf16 v[124:127], v[132:135], v[170:173], v[124:127]
	v_mfma_f32_16x16x32_bf16 v[120:123], v[140:143], v[170:173], v[120:123]
	v_mfma_f32_16x16x32_bf16 v[116:119], v[132:135], v[178:181], v[116:119]
	v_mfma_f32_16x16x32_bf16 v[112:115], v[140:143], v[178:181], v[112:115]
	v_mfma_f32_16x16x32_bf16 v[108:111], v[132:135], v[186:189], v[108:111]
	v_mfma_f32_16x16x32_bf16 v[104:107], v[140:143], v[186:189], v[104:107]
	v_mfma_f32_16x16x32_bf16 v[100:103], v[132:135], v[194:197], v[100:103]
	v_mfma_f32_16x16x32_bf16 v[96:99], v[140:143], v[194:197], v[96:99]
	v_mfma_f32_16x16x32_bf16 v[124:127], v[136:139], v[174:177], v[124:127]
	v_mfma_f32_16x16x32_bf16 v[120:123], v[144:147], v[174:177], v[120:123]
	v_mfma_f32_16x16x32_bf16 v[116:119], v[136:139], v[182:185], v[116:119]
	v_mfma_f32_16x16x32_bf16 v[112:115], v[144:147], v[182:185], v[112:115]
	v_mfma_f32_16x16x32_bf16 v[108:111], v[136:139], v[190:193], v[108:111]
	v_mfma_f32_16x16x32_bf16 v[104:107], v[144:147], v[190:193], v[104:107]
	v_mfma_f32_16x16x32_bf16 v[100:103], v[136:139], v[198:201], v[100:103]
	v_mfma_f32_16x16x32_bf16 v[96:99], v[144:147], v[198:201], v[96:99]
	v_mfma_f32_16x16x32_bf16 v[92:95], v[154:157], v[170:173], v[92:95]
	v_mfma_f32_16x16x32_bf16 v[88:91], v[162:165], v[170:173], v[88:91]
	v_mfma_f32_16x16x32_bf16 v[84:87], v[154:157], v[178:181], v[84:87]
	v_mfma_f32_16x16x32_bf16 v[80:83], v[162:165], v[178:181], v[80:83]
	v_mfma_f32_16x16x32_bf16 v[76:79], v[154:157], v[186:189], v[76:79]
	v_mfma_f32_16x16x32_bf16 v[72:75], v[162:165], v[186:189], v[72:75]
	v_mfma_f32_16x16x32_bf16 v[68:71], v[154:157], v[194:197], v[68:71]
	v_mfma_f32_16x16x32_bf16 v[64:67], v[162:165], v[194:197], v[64:67]
	v_mfma_f32_16x16x32_bf16 v[92:95], v[158:161], v[174:177], v[92:95]
	v_mfma_f32_16x16x32_bf16 v[88:91], v[166:169], v[174:177], v[88:91]
	v_mfma_f32_16x16x32_bf16 v[84:87], v[158:161], v[182:185], v[84:87]
	v_mfma_f32_16x16x32_bf16 v[80:83], v[166:169], v[182:185], v[80:83]
	v_mfma_f32_16x16x32_bf16 v[76:79], v[158:161], v[190:193], v[76:79]
	v_mfma_f32_16x16x32_bf16 v[72:75], v[166:169], v[190:193], v[72:75]
	v_mfma_f32_16x16x32_bf16 v[68:71], v[158:161], v[198:201], v[68:71]
	v_mfma_f32_16x16x32_bf16 v[64:67], v[166:169], v[198:201], v[64:67]
	s_barrier
	s_add_u32 s4, s36, 0x8000
	s_addc_u32 s5, s18, 0
	s_mov_b32 m0, s85
	s_and_b32 s5, s5, 0xffff
	ds_read_b128 v[170:173], v153 offset:49152
	ds_read_b128 v[174:177], v153 offset:50176
	ds_read_b128 v[178:181], v153 offset:51200
	ds_read_b128 v[182:185], v153 offset:52224
	ds_read_b128 v[186:189], v153 offset:53248
	ds_read_b128 v[190:193], v153 offset:54272
	ds_read_b128 v[194:197], v153 offset:55296
	ds_read_b128 v[198:201], v153 offset:56320
	buffer_load_dwordx4 v149, s[4:7], 0 offen lds
	s_mov_b32 m0, s86
	s_mov_b32 s19, s7
	buffer_load_dwordx4 v151, s[4:7], 0 offen lds
	s_add_u32 s4, s36, 0xc000
	s_addc_u32 s5, s18, 0
	s_and_b32 s5, s5, 0xffff
	s_mov_b32 m0, s89
	s_and_b32 s17, s17, 0xffff
	buffer_load_dwordx4 v149, s[4:7], 0 offen lds
	s_mov_b32 m0, s90
	s_mov_b32 s18, s6
	buffer_load_dwordx4 v151, s[4:7], 0 offen lds
	s_mov_b32 m0, s87
	s_nop 0
	buffer_load_dwordx4 v148, s[16:19], 0 offen lds
	s_mov_b32 m0, s88
	s_nop 0
	buffer_load_dwordx4 v150, s[16:19], 0 offen lds
	s_waitcnt vmcnt(8)
	s_waitcnt lgkmcnt(0)
	s_barrier
	v_mfma_f32_16x16x32_bf16 v[60:63], v[132:135], v[170:173], v[60:63]
	v_mfma_f32_16x16x32_bf16 v[56:59], v[140:143], v[170:173], v[56:59]
	v_mfma_f32_16x16x32_bf16 v[52:55], v[132:135], v[178:181], v[52:55]
	v_mfma_f32_16x16x32_bf16 v[48:51], v[140:143], v[178:181], v[48:51]
	v_mfma_f32_16x16x32_bf16 v[44:47], v[132:135], v[186:189], v[44:47]
	v_mfma_f32_16x16x32_bf16 v[40:43], v[140:143], v[186:189], v[40:43]
	v_mfma_f32_16x16x32_bf16 v[36:39], v[132:135], v[194:197], v[36:39]
	v_mfma_f32_16x16x32_bf16 v[32:35], v[140:143], v[194:197], v[32:35]
	v_mfma_f32_16x16x32_bf16 v[60:63], v[136:139], v[174:177], v[60:63]
	v_mfma_f32_16x16x32_bf16 v[56:59], v[144:147], v[174:177], v[56:59]
	v_mfma_f32_16x16x32_bf16 v[52:55], v[136:139], v[182:185], v[52:55]
	v_mfma_f32_16x16x32_bf16 v[48:51], v[144:147], v[182:185], v[48:51]
	v_mfma_f32_16x16x32_bf16 v[44:47], v[136:139], v[190:193], v[44:47]
	v_mfma_f32_16x16x32_bf16 v[40:43], v[144:147], v[190:193], v[40:43]
	v_mfma_f32_16x16x32_bf16 v[36:39], v[136:139], v[198:201], v[36:39]
	v_mfma_f32_16x16x32_bf16 v[32:35], v[144:147], v[198:201], v[32:35]
	v_mfma_f32_16x16x32_bf16 v[28:31], v[154:157], v[170:173], v[28:31]
	v_mfma_f32_16x16x32_bf16 v[24:27], v[162:165], v[170:173], v[24:27]
	v_mfma_f32_16x16x32_bf16 v[20:23], v[154:157], v[178:181], v[20:23]
	v_mfma_f32_16x16x32_bf16 v[16:19], v[162:165], v[178:181], v[16:19]
	v_mfma_f32_16x16x32_bf16 v[12:15], v[154:157], v[186:189], v[12:15]
	v_mfma_f32_16x16x32_bf16 v[8:11], v[162:165], v[186:189], v[8:11]
	v_mfma_f32_16x16x32_bf16 v[4:7], v[154:157], v[194:197], v[4:7]
	v_mfma_f32_16x16x32_bf16 v[0:3], v[162:165], v[194:197], v[0:3]
	v_mfma_f32_16x16x32_bf16 v[28:31], v[158:161], v[174:177], v[28:31]
	v_mfma_f32_16x16x32_bf16 v[24:27], v[166:169], v[174:177], v[24:27]
	v_mfma_f32_16x16x32_bf16 v[20:23], v[158:161], v[182:185], v[20:23]
	v_mfma_f32_16x16x32_bf16 v[16:19], v[166:169], v[182:185], v[16:19]
	v_mfma_f32_16x16x32_bf16 v[12:15], v[158:161], v[190:193], v[12:15]
	v_mfma_f32_16x16x32_bf16 v[8:11], v[166:169], v[190:193], v[8:11]
	v_mfma_f32_16x16x32_bf16 v[4:7], v[158:161], v[198:201], v[4:7]
	v_mfma_f32_16x16x32_bf16 v[0:3], v[166:169], v[198:201], v[0:3]
	s_barrier
	s_add_i32 s63, s63, 2
	s_add_u32 s9, s9, 0x10000
	s_addc_u32 s33, s33, 0
	s_add_u32 s47, s47, 0x100
	s_addc_u32 s62, s62, 0
	s_cmp_gt_u32 s63, 29
	s_cbranch_scc0 .LBB0_485
	s_and_b64 vcc, exec, s[44:45]
	s_cbranch_vccz .LBB0_488
	s_barrier

; #define PG8_STAGE(bufoff, gbase, voff) do { const __amdgpu_buffer_rsrc_t _rs = __builtin_amdgcn_make_buffer_rsrc((void*)(gbase), 0, 0x7fffffff, 0x00020000); _Pragma("unroll") for (int _i = 0; _i < 2; ++_i) \
;         __builtin_amdgcn_raw_ptr_buffer_load_lds(_rs, (LAS unsigned*)(lds + (bufoff) + ldsw + _i * 8192), 16, (int)(voff)[_i], 0, 0, 0); } while (0)
; #define PG8_BAR __builtin_amdgcn_s_barrier()
; template <class Epi, class Sched, bool F8 = false>
; __device__ __forceinline__ void gemm_phase(LAS unsigned char* lds, const int lda, const int ldb, const Sched& S, const Epi& E) {
;     ...
;     for (int i = 0; i < 2; ++i) { int R, C; stage_rc(tid * 16 + i * 8192, R, C); const int Rb = Epi::PERM ? ((R & ~31) + perm32(R & 31)) : R;
;         voffA[i] = (unsigned)(R * lda + C * 2); voffB[i] = (unsigned)(Rb * 128 + C * 2); }
;     ...
;     PG8_STAGE(PG8_SB(0, 0), cB, voffB); PG8_STAGE(PG8_SB(0, 1), cB + hstepB, voffB); PG8_STAGE(PG8_SA(0, 0), cA, voffA); PG8_STAGE(PG8_SA(0, 1), cA + hstepA, voffA);
;     if (wr == 1) PG8_BAR;
.LBB0_620:
	v_bfe_i32 v3, v0, 27, 1
	v_lshlrev_b32_e32 v1, 4, v0
	v_lshrrev_b32_e32 v3, 22, v3
	v_add_u32_e32 v3, v1, v3
	v_and_b32_e32 v3, 0xfffffc00, v3
	v_sub_u32_e32 v3, v1, v3
	v_ashrrev_i32_e32 v2, 31, v0
	v_lshrrev_b32_e32 v4, 4, v3
	v_lshrrev_b32_e32 v2, 26, v2
	v_bitop3_b32 v3, v4, v3, 32 bitop3:0x6c
	v_add_u32_e32 v2, v0, v2
	v_ashrrev_i32_e32 v5, 31, v3
	v_ashrrev_i32_e32 v2, 6, v2
	v_lshrrev_b32_e32 v5, 26, v5
	v_lshlrev_b32_e32 v4, 3, v2
	v_add_u32_e32 v5, v3, v5
	v_and_b32_e32 v4, -16, v4
	v_ashrrev_i32_e32 v6, 6, v5
	v_and_b32_e32 v5, 0xc0, v5
	v_add_u32_e32 v4, v6, v4
	v_sub_u32_e32 v3, v3, v5
	v_mov_b32_e32 v5, 1
	v_lshlrev_b32_e32 v2, 5, v2
	v_ashrrev_i16_sdwa v3, v5, sext(v3) dst_sel:DWORD dst_unused:UNUSED_PAD src0_sel:DWORD src1_sel:BYTE_0
	v_lshlrev_b32_e32 v7, 1, v4
	v_lshrrev_b32_e32 v8, 2, v4
	v_and_b32_e32 v6, 3, v6
	s_mov_b32 s1, 0x1ffffe0
	v_and_b32_e32 v2, 32, v2
	v_bfe_i32 v3, v3, 0, 16
	v_and_b32_e32 v7, 24, v7
	v_and_b32_e32 v8, 4, v8
	v_and_or_b32 v6, v4, s1, v6
	v_or3_b32 v6, v6, v8, v7
	v_add_lshl_u32 v2, v2, v3, 1
	v_add_u32_e32 v1, 0x2000, v1
	v_lshl_add_u32 v138, v4, 13, v2
	v_lshl_add_u32 v139, v6, 7, v2
	v_ashrrev_i32_e32 v2, 31, v1
	v_lshrrev_b32_e32 v2, 22, v2
	v_add_u32_e32 v2, v1, v2
	v_ashrrev_i32_e32 v2, 10, v2
	v_mul_i32_i24_e32 v3, 0x400, v2
	v_sub_u32_e32 v1, v1, v3
	v_lshrrev_b32_e32 v3, 4, v1
	v_bitop3_b32 v1, v3, v1, 32 bitop3:0x6c
	v_ashrrev_i32_e32 v4, 31, v1
	v_lshrrev_b32_e32 v4, 26, v4
	v_lshlrev_b32_e32 v3, 3, v2
	v_add_u32_e32 v4, v1, v4
	s_ashr_i32 s0, s26, 6
	v_and_b32_e32 v3, -16, v3
	v_ashrrev_i32_e32 v6, 6, v4
	v_and_b32_e32 v4, 0xc0, v4
	v_add_u32_e32 v3, v6, v3
	v_sub_u32_e32 v1, v1, v4
	s_lshl_b32 s14, s0, 10
	v_lshlrev_b32_e32 v2, 5, v2
	v_ashrrev_i16_sdwa v1, v5, sext(v1) dst_sel:DWORD dst_unused:UNUSED_PAD src0_sel:DWORD src1_sel:BYTE_0
	v_lshlrev_b32_e32 v4, 1, v3
	v_lshrrev_b32_e32 v5, 2, v3
	v_and_b32_e32 v6, 3, v6
	s_add_i32 s61, s14, 0
	v_and_b32_e32 v2, 32, v2
	v_bfe_i32 v1, v1, 0, 16
	v_and_b32_e32 v4, 24, v4
	v_and_b32_e32 v5, 4, v5
	v_and_or_b32 v6, v3, s1, v6
	s_add_i32 s73, s61, 0x10000
	v_or3_b32 v4, v6, v5, v4
	v_add_lshl_u32 v1, v2, v1, 1
	s_and_b32 s5, s19, 0xffff
	s_mov_b32 s7, 0x20000
	s_brev_b32 s6, -2
	s_mov_b32 s4, s18
	s_mov_b32 m0, s73
	s_add_i32 s74, s61, 0x12000
	v_lshl_add_u32 v141, v4, 7, v1
	s_ashr_i32 s1, s26, 8
	buffer_load_dwordx4 v139, s[4:7], 0 offen lds
	s_mov_b32 m0, s74
	v_lshl_add_u32 v140, v3, 13, v1
	buffer_load_dwordx4 v141, s[4:7], 0 offen lds
	s_add_u32 s4, s18, 0x4000
	s_addc_u32 s5, s19, 0
	s_add_i32 s75, s61, 0x14000
	s_and_b32 s5, s5, 0xffff
	s_mov_b32 m0, s75
	s_add_i32 s76, s61, 0x16000
	buffer_load_dwordx4 v139, s[4:7], 0 offen lds
	s_mov_b32 m0, s76
	s_add_i32 s77, s61, 0x2000
	buffer_load_dwordx4 v141, s[4:7], 0 offen lds
	s_and_b32 s5, s17, 0xffff
	s_mov_b32 s4, s16
	s_mov_b32 m0, s61
	s_mov_b32 s80, 0
	buffer_load_dwordx4 v138, s[4:7], 0 offen lds
	s_mov_b32 m0, s77
	s_nop 0
	buffer_load_dwordx4 v140, s[4:7], 0 offen lds
	s_add_u32 s4, s16, 0x100000
	s_addc_u32 s5, s17, 0
	s_add_i32 s78, s61, 0x4000
	s_and_b32 s5, s5, 0xffff
	s_mov_b32 m0, s78
	s_add_i32 s79, s61, 0x6000
	buffer_load_dwordx4 v138, s[4:7], 0 offen lds
	s_mov_b32 m0, s79
	s_cmp_eq_u32 s1, 1
	buffer_load_dwordx4 v140, s[4:7], 0 offen lds
	s_cselect_b64 s[14:15], -1, 0
	s_cmp_lg_u32 s1, 1
	s_cbranch_scc1 .LBB0_622
	s_setprio 1
	s_barrier

; #define PG8_STAGE(bufoff, gbase, voff) do { const __amdgpu_buffer_rsrc_t _rs = __builtin_amdgcn_make_buffer_rsrc((void*)(gbase), 0, 0x7fffffff, 0x00020000); _Pragma("unroll") for (int _i = 0; _i < 2; ++_i) \
;         __builtin_amdgcn_raw_ptr_buffer_load_lds(_rs, (LAS unsigned*)(lds + (bufoff) + ldsw + _i * 8192), 16, (int)(voff)[_i], 0, 0, 0); } while (0)
; #define PG8_WAIT_V(n) asm volatile("s_waitcnt vmcnt(" #n ")" ::: "memory")
; #define PG8_WAIT_L(n) asm volatile("s_waitcnt lgkmcnt(" #n ")" ::: "memory")
; #define PG8_BAR __builtin_amdgcn_s_barrier()
; #define PG8_SCHED __builtin_amdgcn_sched_barrier(0)
; template <class Epi, class Sched, bool F8 = false>
; __device__ __forceinline__ void gemm_phase(LAS unsigned char* lds, const int lda, const int ldb, const Sched& S, const Epi& E) {
;     ...
;             const char* a1 = cA + (size_t)(t + 1) * kstep;
;             const char* a2 = last ? nA : cA + (size_t)(t + 2) * kstep; const char* b2 = last ? nB : cB + (size_t)(t + 2) * kstepB;
;             const char* a3 = a2 + kstep; const char* b3 = b2 + kstepB;
;     ...
;             PG8_LDB(B0, 0, 0); PG8_LDB(B1, 0, 1); PG8_SCHED; PG8_LDA(At, 0, 0); PG8_STAGE(PG8_SA(1, 1), a1 + hstepA, voffA);
;             PG8_WAIT_V(8); PG8_WAIT_L(0); PG8_BAR; PG8_MMA(0, 0, At, B0); PG8_MMA(0, 1, At, B1); PG8_BAR; PG8_SCHED;
;             PG8_LDA(At, 0, 1); PG8_STAGE(PG8_SB(0, 0), b2, voffB); PG8_STAGE(PG8_SB(0, 1), b2 + hstepB, voffB); PG8_STAGE(PG8_SA(0, 0), a2, voffA);
;             PG8_WAIT_V(8); PG8_WAIT_L(0); PG8_BAR; PG8_MMA(1, 0, At, B0); PG8_MMA(1, 1, At, B1); PG8_BAR; PG8_SCHED;
.LBB0_632:
	ds_read_b128 v[132:135], v142
	ds_read_b128 v[148:151], v142 offset:1024
	ds_read_b128 v[152:155], v142 offset:2048
	ds_read_b128 v[156:159], v142 offset:3072
	ds_read_b128 v[160:163], v143
	ds_read_b128 v[164:167], v143 offset:1024
	ds_read_b128 v[168:171], v143 offset:2048
	ds_read_b128 v[172:175], v143 offset:3072
	s_add_u32 s4, vcc_lo, 0xfff00080
	s_addc_u32 s5, vcc_hi, -1
	s_cmp_eq_u32 s64, 60
	s_cselect_b32 s40, s68, s4
	s_cselect_b32 s19, s69, s5
	s_cselect_b32 s18, s71, s67
	s_cselect_b32 s36, s70, s51
	s_add_u32 s16, s40, 0x80
	s_addc_u32 s17, s19, 0
	s_and_b32 s5, vcc_hi, 0xffff
	s_mov_b32 s4, vcc_lo
	s_mov_b32 m0, s92
	ds_read_b128 v[176:179], v144
	ds_read_b128 v[180:183], v144 offset:1024
	ds_read_b128 v[184:187], v144 offset:2048
	ds_read_b128 v[188:191], v144 offset:3072
	ds_read_b128 v[192:195], v144 offset:4096
	ds_read_b128 v[196:199], v144 offset:5120
	ds_read_b128 v[200:203], v144 offset:6144
	ds_read_b128 v[204:207], v144 offset:7168
	buffer_load_dwordx4 v138, s[4:7], 0 offen lds
	s_mov_b32 m0, s93
	s_nop 0
	buffer_load_dwordx4 v140, s[4:7], 0 offen lds
	s_waitcnt vmcnt(8)
	s_waitcnt lgkmcnt(0)
	s_barrier
	v_mfma_f32_16x16x32_bf16 v[124:127], v[132:135], v[176:179], v[124:127]
	v_mfma_f32_16x16x32_bf16 v[120:123], v[152:155], v[176:179], v[120:123]
	v_mfma_f32_16x16x32_bf16 v[108:111], v[132:135], v[184:187], v[108:111]
	v_mfma_f32_16x16x32_bf16 v[104:107], v[152:155], v[184:187], v[104:107]
	v_mfma_f32_16x16x32_bf16 v[92:95], v[132:135], v[192:195], v[92:95]
	v_mfma_f32_16x16x32_bf16 v[88:91], v[152:155], v[192:195], v[88:91]
	v_mfma_f32_16x16x32_bf16 v[76:79], v[132:135], v[200:203], v[76:79]
	v_mfma_f32_16x16x32_bf16 v[72:75], v[152:155], v[200:203], v[72:75]
	v_mfma_f32_16x16x32_bf16 v[124:127], v[148:151], v[180:183], v[124:127]
	v_mfma_f32_16x16x32_bf16 v[120:123], v[156:159], v[180:183], v[120:123]
	v_mfma_f32_16x16x32_bf16 v[108:111], v[148:151], v[188:191], v[108:111]
	v_mfma_f32_16x16x32_bf16 v[104:107], v[156:159], v[188:191], v[104:107]
	v_mfma_f32_16x16x32_bf16 v[92:95], v[148:151], v[196:199], v[92:95]
	v_mfma_f32_16x16x32_bf16 v[88:91], v[156:159], v[196:199], v[88:91]
	v_mfma_f32_16x16x32_bf16 v[76:79], v[148:151], v[204:207], v[76:79]
	v_mfma_f32_16x16x32_bf16 v[72:75], v[156:159], v[204:207], v[72:75]
	v_mfma_f32_16x16x32_bf16 v[116:119], v[160:163], v[176:179], v[116:119]
	v_mfma_f32_16x16x32_bf16 v[112:115], v[168:171], v[176:179], v[112:115]
	v_mfma_f32_16x16x32_bf16 v[100:103], v[160:163], v[184:187], v[100:103]
	v_mfma_f32_16x16x32_bf16 v[96:99], v[168:171], v[184:187], v[96:99]
	v_mfma_f32_16x16x32_bf16 v[84:87], v[160:163], v[192:195], v[84:87]
	v_mfma_f32_16x16x32_bf16 v[80:83], v[168:171], v[192:195], v[80:83]
	v_mfma_f32_16x16x32_bf16 v[68:71], v[160:163], v[200:203], v[68:71]
	v_mfma_f32_16x16x32_bf16 v[64:67], v[168:171], v[200:203], v[64:67]
	v_mfma_f32_16x16x32_bf16 v[116:119], v[164:167], v[180:183], v[116:119]
	v_mfma_f32_16x16x32_bf16 v[112:115], v[172:175], v[180:183], v[112:115]
	v_mfma_f32_16x16x32_bf16 v[100:103], v[164:167], v[188:191], v[100:103]
	v_mfma_f32_16x16x32_bf16 v[96:99], v[172:175], v[188:191], v[96:99]
	v_mfma_f32_16x16x32_bf16 v[84:87], v[164:167], v[196:199], v[84:87]
	v_mfma_f32_16x16x32_bf16 v[80:83], v[172:175], v[196:199], v[80:83]
	v_mfma_f32_16x16x32_bf16 v[68:71], v[164:167], v[204:207], v[68:71]
	v_mfma_f32_16x16x32_bf16 v[64:67], v[172:175], v[204:207], v[64:67]
	s_barrier
	s_and_b32 s37, s18, 0xffff
	s_mov_b32 m0, s73
	s_mov_b32 s38, s6
	s_mov_b32 s39, s7
	s_add_u32 s4, s36, 0x4000
	ds_read_b128 v[176:179], v144 offset:16384
	ds_read_b128 v[180:183], v144 offset:17408
	ds_read_b128 v[184:187], v144 offset:18432
	ds_read_b128 v[188:191], v144 offset:19456
	ds_read_b128 v[192:195], v144 offset:20480
	ds_read_b128 v[196:199], v144 offset:21504
	ds_read_b128 v[200:203], v144 offset:22528
	ds_read_b128 v[204:207], v144 offset:23552
	buffer_load_dwordx4 v139, s[36:39], 0 offen lds
	s_mov_b32 m0, s74
	s_addc_u32 s5, s18, 0
	buffer_load_dwordx4 v141, s[36:39], 0 offen lds
	s_and_b32 s5, s5, 0xffff
	s_mov_b32 m0, s75
	s_and_b32 s41, s19, 0xffff
	buffer_load_dwordx4 v139, s[4:7], 0 offen lds
	s_mov_b32 m0, s76
	s_mov_b32 s42, s6
	buffer_load_dwordx4 v141, s[4:7], 0 offen lds
	s_mov_b32 s43, s7
	s_mov_b32 m0, s61
	s_nop 0
	buffer_load_dwordx4 v138, s[40:43], 0 offen lds
	s_mov_b32 m0, s77
	s_nop 0
	buffer_load_dwordx4 v140, s[40:43], 0 offen lds
	s_waitcnt vmcnt(8)
	s_waitcnt lgkmcnt(0)
	s_barrier
	v_mfma_f32_16x16x32_bf16 v[60:63], v[132:135], v[176:179], v[60:63]
	v_mfma_f32_16x16x32_bf16 v[56:59], v[152:155], v[176:179], v[56:59]
	v_mfma_f32_16x16x32_bf16 v[44:47], v[132:135], v[184:187], v[44:47]
	v_mfma_f32_16x16x32_bf16 v[40:43], v[152:155], v[184:187], v[40:43]
	v_mfma_f32_16x16x32_bf16 v[28:31], v[132:135], v[192:195], v[28:31]
	v_mfma_f32_16x16x32_bf16 v[24:27], v[152:155], v[192:195], v[24:27]
	v_mfma_f32_16x16x32_bf16 v[12:15], v[132:135], v[200:203], v[12:15]
	v_mfma_f32_16x16x32_bf16 v[8:11], v[152:155], v[200:203], v[8:11]
	v_mfma_f32_16x16x32_bf16 v[60:63], v[148:151], v[180:183], v[60:63]
	v_mfma_f32_16x16x32_bf16 v[56:59], v[156:159], v[180:183], v[56:59]
	v_mfma_f32_16x16x32_bf16 v[44:47], v[148:151], v[188:191], v[44:47]
	v_mfma_f32_16x16x32_bf16 v[40:43], v[156:159], v[188:191], v[40:43]
	v_mfma_f32_16x16x32_bf16 v[28:31], v[148:151], v[196:199], v[28:31]
	v_mfma_f32_16x16x32_bf16 v[24:27], v[156:159], v[196:199], v[24:27]
	v_mfma_f32_16x16x32_bf16 v[12:15], v[148:151], v[204:207], v[12:15]
	v_mfma_f32_16x16x32_bf16 v[8:11], v[156:159], v[204:207], v[8:11]
	v_mfma_f32_16x16x32_bf16 v[52:55], v[160:163], v[176:179], v[52:55]
	v_mfma_f32_16x16x32_bf16 v[48:51], v[168:171], v[176:179], v[48:51]
	v_mfma_f32_16x16x32_bf16 v[36:39], v[160:163], v[184:187], v[36:39]
	v_mfma_f32_16x16x32_bf16 v[32:35], v[168:171], v[184:187], v[32:35]
	v_mfma_f32_16x16x32_bf16 v[20:23], v[160:163], v[192:195], v[20:23]
	v_mfma_f32_16x16x32_bf16 v[16:19], v[168:171], v[192:195], v[16:19]
	v_mfma_f32_16x16x32_bf16 v[4:7], v[160:163], v[200:203], v[4:7]
	v_mfma_f32_16x16x32_bf16 v[0:3], v[168:171], v[200:203], v[0:3]
	v_mfma_f32_16x16x32_bf16 v[52:55], v[164:167], v[180:183], v[52:55]
	v_mfma_f32_16x16x32_bf16 v[48:51], v[172:175], v[180:183], v[48:51]
	v_mfma_f32_16x16x32_bf16 v[36:39], v[164:167], v[188:191], v[36:39]
	v_mfma_f32_16x16x32_bf16 v[32:35], v[172:175], v[188:191], v[32:35]
	v_mfma_f32_16x16x32_bf16 v[20:23], v[164:167], v[196:199], v[20:23]
	v_mfma_f32_16x16x32_bf16 v[16:19], v[172:175], v[196:199], v[16:19]
	v_mfma_f32_16x16x32_bf16 v[4:7], v[164:167], v[204:207], v[4:7]
	v_mfma_f32_16x16x32_bf16 v[0:3], v[172:175], v[204:207], v[0:3]
	s_barrier
; #define PG8_STAGE(bufoff, gbase, voff) do { const __amdgpu_buffer_rsrc_t _rs = __builtin_amdgcn_make_buffer_rsrc((void*)(gbase), 0, 0x7fffffff, 0x00020000); _Pragma("unroll") for (int _i = 0; _i < 2; ++_i) \
;         __builtin_amdgcn_raw_ptr_buffer_load_lds(_rs, (LAS unsigned*)(lds + (bufoff) + ldsw + _i * 8192), 16, (int)(voff)[_i], 0, 0, 0); } while (0)
; #define PG8_WAIT_V(n) asm volatile("s_waitcnt vmcnt(" #n ")" ::: "memory")
; #define PG8_WAIT_L(n) asm volatile("s_waitcnt lgkmcnt(" #n ")" ::: "memory")
; #define PG8_BAR __builtin_amdgcn_s_barrier()
; #define PG8_SCHED __builtin_amdgcn_sched_barrier(0)
; template <class Epi, class Sched, bool F8 = false>
; __device__ __forceinline__ void gemm_phase(LAS unsigned char* lds, const int lda, const int ldb, const Sched& S, const Epi& E) {
;     ...
;             PG8_LDB(B0, 1, 0); PG8_LDB(B1, 1, 1); PG8_SCHED; PG8_LDA(At, 1, 0); PG8_STAGE(PG8_SA(0, 1), a2 + hstepA, voffA);
;             PG8_WAIT_V(8); PG8_WAIT_L(0); PG8_BAR; PG8_MMA(0, 0, At, B0); PG8_MMA(0, 1, At, B1); PG8_BAR; PG8_SCHED;
;             PG8_LDA(At, 1, 1); PG8_STAGE(PG8_SB(1, 0), b3, voffB); PG8_STAGE(PG8_SB(1, 1), b3 + hstepB, voffB); PG8_STAGE(PG8_SA(1, 0), a3, voffA);
;             PG8_WAIT_V(8); PG8_WAIT_L(0); PG8_BAR; PG8_MMA(1, 0, At, B0); PG8_MMA(1, 1, At, B1); PG8_BAR; PG8_SCHED;
	ds_read_b128 v[132:135], v145
	ds_read_b128 v[148:151], v145 offset:1024
	ds_read_b128 v[152:155], v145 offset:2048
	ds_read_b128 v[156:159], v145 offset:3072
	ds_read_b128 v[160:163], v146
	ds_read_b128 v[164:167], v146 offset:1024
	ds_read_b128 v[168:171], v146 offset:2048
	ds_read_b128 v[172:175], v146 offset:3072
	s_add_u32 s4, s40, 0x100000
	s_addc_u32 s5, s19, 0
	s_and_b32 s5, s5, 0xffff
	s_mov_b32 m0, s78
	ds_read_b128 v[176:179], v144 offset:32768
	ds_read_b128 v[180:183], v144 offset:33792
	ds_read_b128 v[184:187], v144 offset:34816
	ds_read_b128 v[188:191], v144 offset:35840
	ds_read_b128 v[192:195], v144 offset:36864
	ds_read_b128 v[196:199], v144 offset:37888
	ds_read_b128 v[200:203], v144 offset:38912
	ds_read_b128 v[204:207], v144 offset:39936
	buffer_load_dwordx4 v138, s[4:7], 0 offen lds
	s_mov_b32 m0, s79
	s_nop 0
	buffer_load_dwordx4 v140, s[4:7], 0 offen lds
	s_waitcnt vmcnt(8)
	s_waitcnt lgkmcnt(0)
	s_barrier
	v_mfma_f32_16x16x32_bf16 v[124:127], v[132:135], v[176:179], v[124:127]
	v_mfma_f32_16x16x32_bf16 v[120:123], v[152:155], v[176:179], v[120:123]
	v_mfma_f32_16x16x32_bf16 v[108:111], v[132:135], v[184:187], v[108:111]
	v_mfma_f32_16x16x32_bf16 v[104:107], v[152:155], v[184:187], v[104:107]
	v_mfma_f32_16x16x32_bf16 v[92:95], v[132:135], v[192:195], v[92:95]
	v_mfma_f32_16x16x32_bf16 v[88:91], v[152:155], v[192:195], v[88:91]
	v_mfma_f32_16x16x32_bf16 v[76:79], v[132:135], v[200:203], v[76:79]
	v_mfma_f32_16x16x32_bf16 v[72:75], v[152:155], v[200:203], v[72:75]
	v_mfma_f32_16x16x32_bf16 v[124:127], v[148:151], v[180:183], v[124:127]
	v_mfma_f32_16x16x32_bf16 v[120:123], v[156:159], v[180:183], v[120:123]
	v_mfma_f32_16x16x32_bf16 v[108:111], v[148:151], v[188:191], v[108:111]
	v_mfma_f32_16x16x32_bf16 v[104:107], v[156:159], v[188:191], v[104:107]
	v_mfma_f32_16x16x32_bf16 v[92:95], v[148:151], v[196:199], v[92:95]
	v_mfma_f32_16x16x32_bf16 v[88:91], v[156:159], v[196:199], v[88:91]
	v_mfma_f32_16x16x32_bf16 v[76:79], v[148:151], v[204:207], v[76:79]
	v_mfma_f32_16x16x32_bf16 v[72:75], v[156:159], v[204:207], v[72:75]
	v_mfma_f32_16x16x32_bf16 v[116:119], v[160:163], v[176:179], v[116:119]
	v_mfma_f32_16x16x32_bf16 v[112:115], v[168:171], v[176:179], v[112:115]
	v_mfma_f32_16x16x32_bf16 v[100:103], v[160:163], v[184:187], v[100:103]
	v_mfma_f32_16x16x32_bf16 v[96:99], v[168:171], v[184:187], v[96:99]
	v_mfma_f32_16x16x32_bf16 v[84:87], v[160:163], v[192:195], v[84:87]
	v_mfma_f32_16x16x32_bf16 v[80:83], v[168:171], v[192:195], v[80:83]
	v_mfma_f32_16x16x32_bf16 v[68:71], v[160:163], v[200:203], v[68:71]
	v_mfma_f32_16x16x32_bf16 v[64:67], v[168:171], v[200:203], v[64:67]
	v_mfma_f32_16x16x32_bf16 v[116:119], v[164:167], v[180:183], v[116:119]
	v_mfma_f32_16x16x32_bf16 v[112:115], v[172:175], v[180:183], v[112:115]
	v_mfma_f32_16x16x32_bf16 v[100:103], v[164:167], v[188:191], v[100:103]
	v_mfma_f32_16x16x32_bf16 v[96:99], v[172:175], v[188:191], v[96:99]
	v_mfma_f32_16x16x32_bf16 v[84:87], v[164:167], v[196:199], v[84:87]
	v_mfma_f32_16x16x32_bf16 v[80:83], v[172:175], v[196:199], v[80:83]
	v_mfma_f32_16x16x32_bf16 v[68:71], v[164:167], v[204:207], v[68:71]
	v_mfma_f32_16x16x32_bf16 v[64:67], v[172:175], v[204:207], v[64:67]
	s_barrier
	s_add_u32 s4, s36, 0x8000
	s_addc_u32 s5, s18, 0
	s_mov_b32 m0, s86
	s_and_b32 s5, s5, 0xffff
	ds_read_b128 v[176:179], v144 offset:49152
	ds_read_b128 v[180:183], v144 offset:50176
	ds_read_b128 v[184:187], v144 offset:51200
	ds_read_b128 v[188:191], v144 offset:52224
	ds_read_b128 v[192:195], v144 offset:53248
	ds_read_b128 v[196:199], v144 offset:54272
	ds_read_b128 v[200:203], v144 offset:55296
	ds_read_b128 v[204:207], v144 offset:56320
	buffer_load_dwordx4 v139, s[4:7], 0 offen lds
	s_mov_b32 m0, s87
	s_mov_b32 s19, s7
	buffer_load_dwordx4 v141, s[4:7], 0 offen lds
	s_add_u32 s4, s36, 0xc000
	s_addc_u32 s5, s18, 0
	s_and_b32 s5, s5, 0xffff
	s_mov_b32 m0, s90
	s_and_b32 s17, s17, 0xffff
	buffer_load_dwordx4 v139, s[4:7], 0 offen lds
	s_mov_b32 m0, s91
	s_mov_b32 s18, s6
	buffer_load_dwordx4 v141, s[4:7], 0 offen lds
	s_mov_b32 m0, s88
	s_nop 0
	buffer_load_dwordx4 v138, s[16:19], 0 offen lds
	s_mov_b32 m0, s89
	s_nop 0
	buffer_load_dwordx4 v140, s[16:19], 0 offen lds
	s_waitcnt vmcnt(8)
	s_waitcnt lgkmcnt(0)
	s_barrier
	v_mfma_f32_16x16x32_bf16 v[60:63], v[132:135], v[176:179], v[60:63]
	v_mfma_f32_16x16x32_bf16 v[56:59], v[152:155], v[176:179], v[56:59]
	v_mfma_f32_16x16x32_bf16 v[44:47], v[132:135], v[184:187], v[44:47]
	v_mfma_f32_16x16x32_bf16 v[40:43], v[152:155], v[184:187], v[40:43]
	v_mfma_f32_16x16x32_bf16 v[28:31], v[132:135], v[192:195], v[28:31]
	v_mfma_f32_16x16x32_bf16 v[24:27], v[152:155], v[192:195], v[24:27]
	v_mfma_f32_16x16x32_bf16 v[12:15], v[132:135], v[200:203], v[12:15]
	v_mfma_f32_16x16x32_bf16 v[8:11], v[152:155], v[200:203], v[8:11]
	v_mfma_f32_16x16x32_bf16 v[60:63], v[148:151], v[180:183], v[60:63]
	v_mfma_f32_16x16x32_bf16 v[56:59], v[156:159], v[180:183], v[56:59]
	v_mfma_f32_16x16x32_bf16 v[44:47], v[148:151], v[188:191], v[44:47]
	v_mfma_f32_16x16x32_bf16 v[40:43], v[156:159], v[188:191], v[40:43]
	v_mfma_f32_16x16x32_bf16 v[28:31], v[148:151], v[196:199], v[28:31]
	v_mfma_f32_16x16x32_bf16 v[24:27], v[156:159], v[196:199], v[24:27]
	v_mfma_f32_16x16x32_bf16 v[12:15], v[148:151], v[204:207], v[12:15]
	v_mfma_f32_16x16x32_bf16 v[8:11], v[156:159], v[204:207], v[8:11]
	v_mfma_f32_16x16x32_bf16 v[52:55], v[160:163], v[176:179], v[52:55]
	v_mfma_f32_16x16x32_bf16 v[48:51], v[168:171], v[176:179], v[48:51]
	v_mfma_f32_16x16x32_bf16 v[36:39], v[160:163], v[184:187], v[36:39]
	v_mfma_f32_16x16x32_bf16 v[32:35], v[168:171], v[184:187], v[32:35]
	v_mfma_f32_16x16x32_bf16 v[20:23], v[160:163], v[192:195], v[20:23]
	v_mfma_f32_16x16x32_bf16 v[16:19], v[168:171], v[192:195], v[16:19]
	v_mfma_f32_16x16x32_bf16 v[4:7], v[160:163], v[200:203], v[4:7]
	v_mfma_f32_16x16x32_bf16 v[0:3], v[168:171], v[200:203], v[0:3]
	v_mfma_f32_16x16x32_bf16 v[52:55], v[164:167], v[180:183], v[52:55]
	v_mfma_f32_16x16x32_bf16 v[48:51], v[172:175], v[180:183], v[48:51]
	v_mfma_f32_16x16x32_bf16 v[36:39], v[164:167], v[188:191], v[36:39]
	v_mfma_f32_16x16x32_bf16 v[32:35], v[172:175], v[188:191], v[32:35]
	v_mfma_f32_16x16x32_bf16 v[20:23], v[164:167], v[196:199], v[20:23]
	v_mfma_f32_16x16x32_bf16 v[16:19], v[172:175], v[196:199], v[16:19]
	v_mfma_f32_16x16x32_bf16 v[4:7], v[164:167], v[204:207], v[4:7]
	v_mfma_f32_16x16x32_bf16 v[0:3], v[172:175], v[204:207], v[0:3]
	s_barrier
	s_add_i32 s64, s64, 2
	s_add_u32 s51, s51, 0x10000
	s_addc_u32 s67, s67, 0
	s_add_u32 vcc_lo, vcc_lo, 0x100
	s_addc_u32 vcc_hi, vcc_hi, 0
	s_cmp_gt_u32 s64, 61
	s_cbranch_scc0 .LBB0_632
	s_and_b64 vcc, exec, s[26:27]
	s_cbranch_vccz .LBB0_635
	s_barrier

; #define PG8_STAGE(bufoff, gbase, voff) do { const __amdgpu_buffer_rsrc_t _rs = __builtin_amdgcn_make_buffer_rsrc((void*)(gbase), 0, 0x7fffffff, 0x00020000); _Pragma("unroll") for (int _i = 0; _i < 2; ++_i) \
;         __builtin_amdgcn_raw_ptr_buffer_load_lds(_rs, (LAS unsigned*)(lds + (bufoff) + ldsw + _i * 8192), 16, (int)(voff)[_i], 0, 0, 0); } while (0)
; #define PG8_BAR __builtin_amdgcn_s_barrier()
; template <class Epi, class Sched, bool F8 = false>
; __device__ __forceinline__ void gemm_phase(LAS unsigned char* lds, const int lda, const int ldb, const Sched& S, const Epi& E) {
;     ...
;     for (int i = 0; i < 2; ++i) { int R, C; stage_rc(tid * 16 + i * 8192, R, C); const int Rb = Epi::PERM ? ((R & ~31) + perm32(R & 31)) : R;
;         voffA[i] = (unsigned)(R * lda + C * 2); voffB[i] = (unsigned)(Rb * 128 + C * 2); }
;     ...
;     PG8_STAGE(PG8_SB(0, 0), cB, voffB); PG8_STAGE(PG8_SB(0, 1), cB + hstepB, voffB); PG8_STAGE(PG8_SA(0, 0), cA, voffA); PG8_STAGE(PG8_SA(0, 1), cA + hstepA, voffA);
;     if (wr == 1) PG8_BAR;
.LBB0_770:
	v_bfe_i32 v3, v0, 27, 1
	v_lshlrev_b32_e32 v1, 4, v0
	v_lshrrev_b32_e32 v3, 22, v3
	v_add_u32_e32 v3, v1, v3
	v_and_b32_e32 v3, 0xfffffc00, v3
	v_sub_u32_e32 v3, v1, v3
	v_ashrrev_i32_e32 v2, 31, v0
	v_lshrrev_b32_e32 v4, 4, v3
	v_lshrrev_b32_e32 v2, 26, v2
	v_bitop3_b32 v3, v4, v3, 32 bitop3:0x6c
	v_add_u32_e32 v2, v0, v2
	v_ashrrev_i32_e32 v5, 31, v3
	v_ashrrev_i32_e32 v2, 6, v2
	v_lshrrev_b32_e32 v5, 26, v5
	v_lshlrev_b32_e32 v4, 3, v2
	v_add_u32_e32 v5, v3, v5
	v_and_b32_e32 v4, -16, v4
	v_ashrrev_i32_e32 v6, 6, v5
	v_and_b32_e32 v5, 0xc0, v5
	v_add_u32_e32 v4, v6, v4
	v_sub_u32_e32 v3, v3, v5
	v_mov_b32_e32 v5, 1
	v_lshlrev_b32_e32 v2, 5, v2
	v_ashrrev_i16_sdwa v3, v5, sext(v3) dst_sel:DWORD dst_unused:UNUSED_PAD src0_sel:DWORD src1_sel:BYTE_0
	v_lshlrev_b32_e32 v7, 1, v4
	v_lshrrev_b32_e32 v8, 2, v4
	v_and_b32_e32 v6, 3, v6
	s_mov_b32 s1, 0x1ffffe0
	v_and_b32_e32 v2, 32, v2
	v_bfe_i32 v3, v3, 0, 16
	v_and_b32_e32 v7, 24, v7
	v_and_b32_e32 v8, 4, v8
	v_and_or_b32 v6, v4, s1, v6
	v_or3_b32 v6, v6, v8, v7
	v_add_lshl_u32 v2, v2, v3, 1
	v_add_u32_e32 v1, 0x2000, v1
	v_lshl_add_u32 v175, v4, 13, v2
	v_lshl_add_u32 v177, v6, 7, v2
	v_ashrrev_i32_e32 v2, 31, v1
	v_lshrrev_b32_e32 v2, 22, v2
	v_add_u32_e32 v2, v1, v2
	v_ashrrev_i32_e32 v2, 10, v2
	v_mul_i32_i24_e32 v3, 0x400, v2
	v_sub_u32_e32 v1, v1, v3
	v_lshrrev_b32_e32 v3, 4, v1
	v_bitop3_b32 v1, v3, v1, 32 bitop3:0x6c
	v_ashrrev_i32_e32 v4, 31, v1
	v_lshrrev_b32_e32 v4, 26, v4
	v_lshlrev_b32_e32 v3, 3, v2
	v_add_u32_e32 v4, v1, v4
	s_ashr_i32 s0, s8, 6
	v_and_b32_e32 v3, -16, v3
	v_ashrrev_i32_e32 v6, 6, v4
	v_and_b32_e32 v4, 0xc0, v4
	v_add_u32_e32 v3, v6, v3
	v_sub_u32_e32 v1, v1, v4
	s_lshl_b32 s9, s0, 10
	v_lshlrev_b32_e32 v2, 5, v2
	v_ashrrev_i16_sdwa v1, v5, sext(v1) dst_sel:DWORD dst_unused:UNUSED_PAD src0_sel:DWORD src1_sel:BYTE_0
	v_lshlrev_b32_e32 v4, 1, v3
	v_lshrrev_b32_e32 v5, 2, v3
	v_and_b32_e32 v6, 3, v6
	s_add_i32 s51, s9, 0
	v_and_b32_e32 v2, 32, v2
	v_bfe_i32 v1, v1, 0, 16
	v_and_b32_e32 v4, 24, v4
	v_and_b32_e32 v5, 4, v5
	v_and_or_b32 v6, v3, s1, v6
	s_add_i32 s68, s51, 0x10000
	v_or3_b32 v4, v6, v5, v4
	v_add_lshl_u32 v1, v2, v1, 1
	s_and_b32 s13, s7, 0xffff
	s_mov_b32 s15, 0x20000
	s_brev_b32 s14, -2
	s_mov_b32 s12, s6
	s_mov_b32 m0, s68
	s_add_i32 s69, s51, 0x12000
	v_lshl_add_u32 v193, v4, 7, v1
	s_ashr_i32 s1, s8, 8
	buffer_load_dwordx4 v177, s[12:15], 0 offen lds
	s_mov_b32 m0, s69
	v_lshl_add_u32 v179, v3, 13, v1
	buffer_load_dwordx4 v193, s[12:15], 0 offen lds
	s_add_u32 s12, s6, 0x4000
	s_addc_u32 s9, s7, 0
	s_add_i32 s70, s51, 0x14000
	s_and_b32 s13, s9, 0xffff
	s_mov_b32 m0, s70
	s_add_i32 s71, s51, 0x16000
	buffer_load_dwordx4 v177, s[12:15], 0 offen lds
	s_mov_b32 m0, s71
	s_add_i32 s72, s51, 0x2000
	buffer_load_dwordx4 v193, s[12:15], 0 offen lds
	s_and_b32 s13, s5, 0xffff
	s_mov_b32 s12, s4
	s_mov_b32 m0, s51
	s_mov_b32 s75, 0
	buffer_load_dwordx4 v175, s[12:15], 0 offen lds
	s_mov_b32 m0, s72
	s_nop 0
	buffer_load_dwordx4 v179, s[12:15], 0 offen lds
	s_add_u32 s12, s4, 0x100000
	s_addc_u32 s9, s5, 0
	s_add_i32 s73, s51, 0x4000
	s_and_b32 s13, s9, 0xffff
	s_mov_b32 m0, s73
	s_add_i32 s74, s51, 0x6000
	buffer_load_dwordx4 v175, s[12:15], 0 offen lds
	s_mov_b32 m0, s74
	s_cmp_eq_u32 s1, 1
	buffer_load_dwordx4 v179, s[12:15], 0 offen lds
	s_mov_b32 s9, 4
	s_cselect_b64 s[26:27], -1, 0
	s_cmp_lg_u32 s1, 1
	s_cbranch_scc1 .LBB0_772
	s_mov_b32 s9, 8
	s_setprio 1
	s_barrier

; #define PG8_STAGE(bufoff, gbase, voff) do { const __amdgpu_buffer_rsrc_t _rs = __builtin_amdgcn_make_buffer_rsrc((void*)(gbase), 0, 0x7fffffff, 0x00020000); _Pragma("unroll") for (int _i = 0; _i < 2; ++_i) \
;         __builtin_amdgcn_raw_ptr_buffer_load_lds(_rs, (LAS unsigned*)(lds + (bufoff) + ldsw + _i * 8192), 16, (int)(voff)[_i], 0, 0, 0); } while (0)
; #define PG8_WAIT_V(n) asm volatile("s_waitcnt vmcnt(" #n ")" ::: "memory")
; #define PG8_WAIT_L(n) asm volatile("s_waitcnt lgkmcnt(" #n ")" ::: "memory")
; #define PG8_BAR __builtin_amdgcn_s_barrier()
; #define PG8_SCHED __builtin_amdgcn_sched_barrier(0)
; template <class Epi, class Sched, bool F8 = false>
; __device__ __forceinline__ void gemm_phase(LAS unsigned char* lds, const int lda, const int ldb, const Sched& S, const Epi& E) {
;     ...
;             const char* a1 = cA + (size_t)(t + 1) * kstep;
;             const char* a2 = last ? nA : cA + (size_t)(t + 2) * kstep; const char* b2 = last ? nB : cB + (size_t)(t + 2) * kstepB;
;             const char* a3 = a2 + kstep; const char* b3 = b2 + kstepB;
;     ...
;             PG8_LDB(B0, 0, 0); PG8_LDB(B1, 0, 1); PG8_SCHED; PG8_LDA(At, 0, 0); PG8_STAGE(PG8_SA(1, 1), a1 + hstepA, voffA);
;             PG8_WAIT_V(8); PG8_WAIT_L(0); PG8_BAR; PG8_MMA(0, 0, At, B0); PG8_MMA(0, 1, At, B1); PG8_BAR; PG8_SCHED;
;             PG8_LDA(At, 0, 1); PG8_STAGE(PG8_SB(0, 0), b2, voffB); PG8_STAGE(PG8_SB(0, 1), b2 + hstepB, voffB); PG8_STAGE(PG8_SA(0, 0), a2, voffA);
;             PG8_WAIT_V(8); PG8_WAIT_L(0); PG8_BAR; PG8_MMA(1, 0, At, B0); PG8_MMA(1, 1, At, B1); PG8_BAR; PG8_SCHED;
.LBB0_778:
	ds_read_b128 v[118:121], v194
	ds_read_b128 v[122:125], v194 offset:1024
	ds_read_b128 v[130:133], v194 offset:2048
	ds_read_b128 v[134:137], v194 offset:3072
	ds_read_b128 v[138:141], v195
	ds_read_b128 v[142:145], v195 offset:1024
	ds_read_b128 v[146:149], v195 offset:2048
	ds_read_b128 v[150:153], v195 offset:3072
	s_add_u32 s4, s33, 0xfff00080
	s_addc_u32 s5, s43, -1
	s_cmp_eq_u32 s45, 60
	s_cselect_b32 s20, s46, s4
	s_cselect_b32 s7, s47, s5
	s_cselect_b32 s6, s49, s9
	s_cselect_b32 s16, s48, s8
	s_add_u32 s4, s20, 0x80
	s_addc_u32 s5, s7, 0
	s_and_b32 s13, s43, 0xffff
	s_mov_b32 s12, s33
	s_mov_b32 m0, s84
	ds_read_b128 v[162:165], v196
	ds_read_b128 v[166:169], v196 offset:1024
	ds_read_b128 v[170:173], v196 offset:2048
	ds_read_b128 v[186:189], v196 offset:3072
	ds_read_b128 v[200:203], v196 offset:4096
	ds_read_b128 v[204:207], v196 offset:5120
	ds_read_b128 v[208:211], v196 offset:6144
	ds_read_b128 v[212:215], v196 offset:7168
	buffer_load_dwordx4 v175, s[12:15], 0 offen lds
	s_mov_b32 m0, s86
	s_nop 0
	buffer_load_dwordx4 v179, s[12:15], 0 offen lds
	s_waitcnt vmcnt(8)
	s_waitcnt lgkmcnt(0)
	s_barrier
	v_mfma_f32_16x16x32_bf16 v[158:161], v[118:121], v[162:165], v[158:161]
	v_mfma_f32_16x16x32_bf16 v[60:63], v[130:133], v[162:165], v[60:63]
	v_mfma_f32_16x16x32_bf16 v[154:157], v[118:121], v[170:173], v[154:157]
	v_mfma_f32_16x16x32_bf16 v[52:55], v[130:133], v[170:173], v[52:55]
	v_mfma_f32_16x16x32_bf16 v[114:117], v[118:121], v[200:203], v[114:117]
	v_mfma_f32_16x16x32_bf16 v[44:47], v[130:133], v[200:203], v[44:47]
	v_mfma_f32_16x16x32_bf16 v[108:111], v[118:121], v[208:211], v[110:113]
	v_mfma_f32_16x16x32_bf16 v[36:39], v[130:133], v[208:211], v[36:39]
	v_mfma_f32_16x16x32_bf16 v[158:161], v[122:125], v[166:169], v[158:161]
	v_mfma_f32_16x16x32_bf16 v[60:63], v[134:137], v[166:169], v[60:63]
	v_mfma_f32_16x16x32_bf16 v[154:157], v[122:125], v[186:189], v[154:157]
	v_mfma_f32_16x16x32_bf16 v[52:55], v[134:137], v[186:189], v[52:55]
	v_mfma_f32_16x16x32_bf16 v[114:117], v[122:125], v[204:207], v[114:117]
	v_mfma_f32_16x16x32_bf16 v[44:47], v[134:137], v[204:207], v[44:47]
	v_mfma_f32_16x16x32_bf16 v[108:111], v[122:125], v[212:215], v[108:111]
	v_mfma_f32_16x16x32_bf16 v[36:39], v[134:137], v[212:215], v[36:39]
	v_mfma_f32_16x16x32_bf16 v[104:107], v[138:141], v[162:165], v[104:107]
	v_mfma_f32_16x16x32_bf16 v[56:59], v[146:149], v[162:165], v[56:59]
	v_mfma_f32_16x16x32_bf16 v[126:129], v[138:141], v[170:173], v[126:129]
	v_mfma_f32_16x16x32_bf16 v[48:51], v[146:149], v[170:173], v[48:51]
	v_mfma_f32_16x16x32_bf16 v[100:103], v[138:141], v[200:203], v[100:103]
	v_mfma_f32_16x16x32_bf16 v[40:43], v[146:149], v[200:203], v[40:43]
	v_mfma_f32_16x16x32_bf16 v[96:99], v[138:141], v[208:211], v[96:99]
	v_mfma_f32_16x16x32_bf16 v[32:35], v[146:149], v[208:211], v[32:35]
	v_mfma_f32_16x16x32_bf16 v[104:107], v[142:145], v[166:169], v[104:107]
	v_mfma_f32_16x16x32_bf16 v[56:59], v[150:153], v[166:169], v[56:59]
	v_mfma_f32_16x16x32_bf16 v[126:129], v[142:145], v[186:189], v[126:129]
	v_mfma_f32_16x16x32_bf16 v[48:51], v[150:153], v[186:189], v[48:51]
	v_mfma_f32_16x16x32_bf16 v[100:103], v[142:145], v[204:207], v[100:103]
	v_mfma_f32_16x16x32_bf16 v[40:43], v[150:153], v[204:207], v[40:43]
	v_mfma_f32_16x16x32_bf16 v[96:99], v[142:145], v[212:215], v[96:99]
	v_mfma_f32_16x16x32_bf16 v[32:35], v[150:153], v[212:215], v[32:35]
	s_barrier
	s_and_b32 s17, s6, 0xffff
	s_mov_b32 m0, s68
	s_mov_b32 s18, s14
	s_mov_b32 s19, s15
	s_add_u32 s12, s16, 0x4000
	ds_read_b128 v[162:165], v196 offset:16384
	ds_read_b128 v[166:169], v196 offset:17408
	ds_read_b128 v[170:173], v196 offset:18432
	ds_read_b128 v[186:189], v196 offset:19456
	ds_read_b128 v[200:203], v196 offset:20480
	ds_read_b128 v[204:207], v196 offset:21504
	ds_read_b128 v[208:211], v196 offset:22528
	ds_read_b128 v[212:215], v196 offset:23552
	buffer_load_dwordx4 v177, s[16:19], 0 offen lds
	s_mov_b32 m0, s69
	s_addc_u32 s13, s6, 0
	buffer_load_dwordx4 v193, s[16:19], 0 offen lds
	s_and_b32 s13, s13, 0xffff
	s_mov_b32 m0, s70
	s_and_b32 s21, s7, 0xffff
	buffer_load_dwordx4 v177, s[12:15], 0 offen lds
	s_mov_b32 m0, s71
	s_mov_b32 s22, s14
	buffer_load_dwordx4 v193, s[12:15], 0 offen lds
	s_mov_b32 s23, s15
	s_mov_b32 m0, s51
	s_nop 0
	buffer_load_dwordx4 v175, s[20:23], 0 offen lds
	s_mov_b32 m0, s72
	s_nop 0
	buffer_load_dwordx4 v179, s[20:23], 0 offen lds
	s_waitcnt vmcnt(8)
	s_waitcnt lgkmcnt(0)
	s_barrier
	v_mfma_f32_16x16x32_bf16 v[92:95], v[118:121], v[162:165], v[92:95]
	v_mfma_f32_16x16x32_bf16 v[28:31], v[130:133], v[162:165], v[28:31]
	v_mfma_f32_16x16x32_bf16 v[84:87], v[118:121], v[170:173], v[84:87]
	v_mfma_f32_16x16x32_bf16 v[20:23], v[130:133], v[170:173], v[20:23]
	v_mfma_f32_16x16x32_bf16 v[76:79], v[118:121], v[200:203], v[76:79]
	v_mfma_f32_16x16x32_bf16 v[12:15], v[130:133], v[200:203], v[12:15]
	v_mfma_f32_16x16x32_bf16 v[72:75], v[118:121], v[208:211], v[72:75]
	v_mfma_f32_16x16x32_bf16 v[4:7], v[130:133], v[208:211], v[4:7]
	v_mfma_f32_16x16x32_bf16 v[92:95], v[122:125], v[166:169], v[92:95]
	v_mfma_f32_16x16x32_bf16 v[28:31], v[134:137], v[166:169], v[28:31]
	v_mfma_f32_16x16x32_bf16 v[84:87], v[122:125], v[186:189], v[84:87]
	v_mfma_f32_16x16x32_bf16 v[20:23], v[134:137], v[186:189], v[20:23]
	v_mfma_f32_16x16x32_bf16 v[76:79], v[122:125], v[204:207], v[76:79]
	v_mfma_f32_16x16x32_bf16 v[12:15], v[134:137], v[204:207], v[12:15]
	v_mfma_f32_16x16x32_bf16 v[72:75], v[122:125], v[212:215], v[72:75]
	v_mfma_f32_16x16x32_bf16 v[4:7], v[134:137], v[212:215], v[4:7]
	v_mfma_f32_16x16x32_bf16 v[88:91], v[138:141], v[162:165], v[88:91]
	v_mfma_f32_16x16x32_bf16 v[24:27], v[146:149], v[162:165], v[24:27]
	v_mfma_f32_16x16x32_bf16 v[80:83], v[138:141], v[170:173], v[80:83]
	v_mfma_f32_16x16x32_bf16 v[16:19], v[146:149], v[170:173], v[16:19]
	v_mfma_f32_16x16x32_bf16 v[68:71], v[138:141], v[200:203], v[68:71]
	v_mfma_f32_16x16x32_bf16 v[8:11], v[146:149], v[200:203], v[8:11]
	v_mfma_f32_16x16x32_bf16 v[64:67], v[138:141], v[208:211], v[64:67]
	v_mfma_f32_16x16x32_bf16 v[0:3], v[146:149], v[208:211], v[0:3]
	v_mfma_f32_16x16x32_bf16 v[88:91], v[142:145], v[166:169], v[88:91]
	v_mfma_f32_16x16x32_bf16 v[24:27], v[150:153], v[166:169], v[24:27]
	v_mfma_f32_16x16x32_bf16 v[80:83], v[142:145], v[186:189], v[80:83]
	v_mfma_f32_16x16x32_bf16 v[16:19], v[150:153], v[186:189], v[16:19]
	v_mfma_f32_16x16x32_bf16 v[68:71], v[142:145], v[204:207], v[68:71]
	v_mfma_f32_16x16x32_bf16 v[8:11], v[150:153], v[204:207], v[8:11]
	v_mfma_f32_16x16x32_bf16 v[64:67], v[142:145], v[212:215], v[64:67]
	v_mfma_f32_16x16x32_bf16 v[0:3], v[150:153], v[212:215], v[0:3]
	s_barrier
; #define PG8_STAGE(bufoff, gbase, voff) do { const __amdgpu_buffer_rsrc_t _rs = __builtin_amdgcn_make_buffer_rsrc((void*)(gbase), 0, 0x7fffffff, 0x00020000); _Pragma("unroll") for (int _i = 0; _i < 2; ++_i) \
;         __builtin_amdgcn_raw_ptr_buffer_load_lds(_rs, (LAS unsigned*)(lds + (bufoff) + ldsw + _i * 8192), 16, (int)(voff)[_i], 0, 0, 0); } while (0)
; #define PG8_WAIT_V(n) asm volatile("s_waitcnt vmcnt(" #n ")" ::: "memory")
; #define PG8_WAIT_L(n) asm volatile("s_waitcnt lgkmcnt(" #n ")" ::: "memory")
; #define PG8_BAR __builtin_amdgcn_s_barrier()
; #define PG8_SCHED __builtin_amdgcn_sched_barrier(0)
; template <class Epi, class Sched, bool F8 = false>
; __device__ __forceinline__ void gemm_phase(LAS unsigned char* lds, const int lda, const int ldb, const Sched& S, const Epi& E) {
;     ...
;             PG8_LDB(B0, 1, 0); PG8_LDB(B1, 1, 1); PG8_SCHED; PG8_LDA(At, 1, 0); PG8_STAGE(PG8_SA(0, 1), a2 + hstepA, voffA);
;             PG8_WAIT_V(8); PG8_WAIT_L(0); PG8_BAR; PG8_MMA(0, 0, At, B0); PG8_MMA(0, 1, At, B1); PG8_BAR; PG8_SCHED;
;             PG8_LDA(At, 1, 1); PG8_STAGE(PG8_SB(1, 0), b3, voffB); PG8_STAGE(PG8_SB(1, 1), b3 + hstepB, voffB); PG8_STAGE(PG8_SA(1, 0), a3, voffA);
;             PG8_WAIT_V(8); PG8_WAIT_L(0); PG8_BAR; PG8_MMA(1, 0, At, B0); PG8_MMA(1, 1, At, B1); PG8_BAR; PG8_SCHED;
	ds_read_b128 v[118:121], v197
	ds_read_b128 v[122:125], v197 offset:1024
	ds_read_b128 v[130:133], v197 offset:2048
	ds_read_b128 v[134:137], v197 offset:3072
	ds_read_b128 v[138:141], v198
	ds_read_b128 v[142:145], v198 offset:1024
	ds_read_b128 v[146:149], v198 offset:2048
	ds_read_b128 v[150:153], v198 offset:3072
	s_add_u32 s12, s20, 0x100000
	s_addc_u32 s7, s7, 0
	s_and_b32 s13, s7, 0xffff
	s_mov_b32 m0, s73
	ds_read_b128 v[162:165], v196 offset:32768
	ds_read_b128 v[166:169], v196 offset:33792
	ds_read_b128 v[170:173], v196 offset:34816
	ds_read_b128 v[186:189], v196 offset:35840
	ds_read_b128 v[200:203], v196 offset:36864
	ds_read_b128 v[204:207], v196 offset:37888
	ds_read_b128 v[208:211], v196 offset:38912
	ds_read_b128 v[212:215], v196 offset:39936
	buffer_load_dwordx4 v175, s[12:15], 0 offen lds
	s_mov_b32 m0, s74
	s_nop 0
	buffer_load_dwordx4 v179, s[12:15], 0 offen lds
	s_waitcnt vmcnt(8)
	s_waitcnt lgkmcnt(0)
	s_barrier
	v_mfma_f32_16x16x32_bf16 v[158:161], v[118:121], v[162:165], v[158:161]
	v_mfma_f32_16x16x32_bf16 v[60:63], v[130:133], v[162:165], v[60:63]
	v_mfma_f32_16x16x32_bf16 v[154:157], v[118:121], v[170:173], v[154:157]
	v_mfma_f32_16x16x32_bf16 v[52:55], v[130:133], v[170:173], v[52:55]
	v_mfma_f32_16x16x32_bf16 v[112:115], v[118:121], v[200:203], v[114:117]
	v_mfma_f32_16x16x32_bf16 v[44:47], v[130:133], v[200:203], v[44:47]
	v_mfma_f32_16x16x32_bf16 v[108:111], v[118:121], v[208:211], v[108:111]
	v_mfma_f32_16x16x32_bf16 v[36:39], v[130:133], v[208:211], v[36:39]
	v_mfma_f32_16x16x32_bf16 v[158:161], v[122:125], v[166:169], v[158:161]
	v_mfma_f32_16x16x32_bf16 v[60:63], v[134:137], v[166:169], v[60:63]
	v_mfma_f32_16x16x32_bf16 v[154:157], v[122:125], v[186:189], v[154:157]
	v_mfma_f32_16x16x32_bf16 v[52:55], v[134:137], v[186:189], v[52:55]
	v_mfma_f32_16x16x32_bf16 v[114:117], v[122:125], v[204:207], v[112:115]
	v_mfma_f32_16x16x32_bf16 v[44:47], v[134:137], v[204:207], v[44:47]
	v_mfma_f32_16x16x32_bf16 v[110:113], v[122:125], v[212:215], v[108:111]
	v_mfma_f32_16x16x32_bf16 v[36:39], v[134:137], v[212:215], v[36:39]
	v_mfma_f32_16x16x32_bf16 v[104:107], v[138:141], v[162:165], v[104:107]
	v_mfma_f32_16x16x32_bf16 v[56:59], v[146:149], v[162:165], v[56:59]
	v_mfma_f32_16x16x32_bf16 v[126:129], v[138:141], v[170:173], v[126:129]
	v_mfma_f32_16x16x32_bf16 v[48:51], v[146:149], v[170:173], v[48:51]
	v_mfma_f32_16x16x32_bf16 v[100:103], v[138:141], v[200:203], v[100:103]
	v_mfma_f32_16x16x32_bf16 v[40:43], v[146:149], v[200:203], v[40:43]
	v_mfma_f32_16x16x32_bf16 v[96:99], v[138:141], v[208:211], v[96:99]
	v_mfma_f32_16x16x32_bf16 v[32:35], v[146:149], v[208:211], v[32:35]
	v_mfma_f32_16x16x32_bf16 v[104:107], v[142:145], v[166:169], v[104:107]
	v_mfma_f32_16x16x32_bf16 v[56:59], v[150:153], v[166:169], v[56:59]
	v_mfma_f32_16x16x32_bf16 v[126:129], v[142:145], v[186:189], v[126:129]
	v_mfma_f32_16x16x32_bf16 v[48:51], v[150:153], v[186:189], v[48:51]
	v_mfma_f32_16x16x32_bf16 v[100:103], v[142:145], v[204:207], v[100:103]
	v_mfma_f32_16x16x32_bf16 v[40:43], v[150:153], v[204:207], v[40:43]
	v_mfma_f32_16x16x32_bf16 v[96:99], v[142:145], v[212:215], v[96:99]
	v_mfma_f32_16x16x32_bf16 v[32:35], v[150:153], v[212:215], v[32:35]
	s_barrier
	s_add_u32 s12, s16, 0x8000
	s_addc_u32 s7, s6, 0
	s_mov_b32 m0, s78
	s_and_b32 s13, s7, 0xffff
	ds_read_b128 v[162:165], v196 offset:49152
	ds_read_b128 v[166:169], v196 offset:50176
	ds_read_b128 v[170:173], v196 offset:51200
	ds_read_b128 v[186:189], v196 offset:52224
	ds_read_b128 v[200:203], v196 offset:53248
	ds_read_b128 v[204:207], v196 offset:54272
	ds_read_b128 v[208:211], v196 offset:55296
	ds_read_b128 v[212:215], v196 offset:56320
	buffer_load_dwordx4 v177, s[12:15], 0 offen lds
	s_mov_b32 m0, s79
	s_mov_b32 s7, s15
	buffer_load_dwordx4 v193, s[12:15], 0 offen lds
	s_add_u32 s12, s16, 0xc000
	s_addc_u32 s6, s6, 0
	s_and_b32 s13, s6, 0xffff
	s_mov_b32 m0, s82
	s_and_b32 s5, s5, 0xffff
	buffer_load_dwordx4 v177, s[12:15], 0 offen lds
	s_mov_b32 m0, s83
	s_mov_b32 s6, s14
	buffer_load_dwordx4 v193, s[12:15], 0 offen lds
	s_mov_b32 m0, s80
	s_nop 0
	buffer_load_dwordx4 v175, s[4:7], 0 offen lds
	s_mov_b32 m0, s81
	s_nop 0
	buffer_load_dwordx4 v179, s[4:7], 0 offen lds
	s_waitcnt vmcnt(8)
	s_waitcnt lgkmcnt(0)
	s_barrier
	v_mfma_f32_16x16x32_bf16 v[92:95], v[118:121], v[162:165], v[92:95]
	v_mfma_f32_16x16x32_bf16 v[28:31], v[130:133], v[162:165], v[28:31]
	v_mfma_f32_16x16x32_bf16 v[84:87], v[118:121], v[170:173], v[84:87]
	v_mfma_f32_16x16x32_bf16 v[20:23], v[130:133], v[170:173], v[20:23]
	v_mfma_f32_16x16x32_bf16 v[76:79], v[118:121], v[200:203], v[76:79]
	v_mfma_f32_16x16x32_bf16 v[12:15], v[130:133], v[200:203], v[12:15]
	v_mfma_f32_16x16x32_bf16 v[72:75], v[118:121], v[208:211], v[72:75]
	v_mfma_f32_16x16x32_bf16 v[4:7], v[130:133], v[208:211], v[4:7]
	v_mfma_f32_16x16x32_bf16 v[92:95], v[122:125], v[166:169], v[92:95]
	v_mfma_f32_16x16x32_bf16 v[28:31], v[134:137], v[166:169], v[28:31]
	v_mfma_f32_16x16x32_bf16 v[84:87], v[122:125], v[186:189], v[84:87]
	v_mfma_f32_16x16x32_bf16 v[20:23], v[134:137], v[186:189], v[20:23]
	v_mfma_f32_16x16x32_bf16 v[76:79], v[122:125], v[204:207], v[76:79]
	v_mfma_f32_16x16x32_bf16 v[12:15], v[134:137], v[204:207], v[12:15]
	v_mfma_f32_16x16x32_bf16 v[72:75], v[122:125], v[212:215], v[72:75]
	v_mfma_f32_16x16x32_bf16 v[4:7], v[134:137], v[212:215], v[4:7]
	v_mfma_f32_16x16x32_bf16 v[88:91], v[138:141], v[162:165], v[88:91]
	v_mfma_f32_16x16x32_bf16 v[24:27], v[146:149], v[162:165], v[24:27]
	v_mfma_f32_16x16x32_bf16 v[80:83], v[138:141], v[170:173], v[80:83]
	v_mfma_f32_16x16x32_bf16 v[16:19], v[146:149], v[170:173], v[16:19]
	v_mfma_f32_16x16x32_bf16 v[68:71], v[138:141], v[200:203], v[68:71]
	v_mfma_f32_16x16x32_bf16 v[8:11], v[146:149], v[200:203], v[8:11]
	v_mfma_f32_16x16x32_bf16 v[64:67], v[138:141], v[208:211], v[64:67]
	v_mfma_f32_16x16x32_bf16 v[0:3], v[146:149], v[208:211], v[0:3]
	v_mfma_f32_16x16x32_bf16 v[88:91], v[142:145], v[166:169], v[88:91]
	v_mfma_f32_16x16x32_bf16 v[24:27], v[150:153], v[166:169], v[24:27]
	v_mfma_f32_16x16x32_bf16 v[80:83], v[142:145], v[186:189], v[80:83]
	v_mfma_f32_16x16x32_bf16 v[16:19], v[150:153], v[186:189], v[16:19]
	v_mfma_f32_16x16x32_bf16 v[68:71], v[142:145], v[204:207], v[68:71]
	v_mfma_f32_16x16x32_bf16 v[8:11], v[150:153], v[204:207], v[8:11]
	v_mfma_f32_16x16x32_bf16 v[64:67], v[142:145], v[212:215], v[64:67]
	v_mfma_f32_16x16x32_bf16 v[0:3], v[150:153], v[212:215], v[0:3]
	s_barrier
	s_add_i32 s45, s45, 2
	s_add_u32 s8, s8, 0x10000
	s_addc_u32 s9, s9, 0
	s_add_u32 s33, s33, 0x100
	s_addc_u32 s43, s43, 0
	s_cmp_gt_u32 s45, 61
	s_cbranch_scc0 .LBB0_778
	s_and_b64 vcc, exec, s[40:41]
	s_cbranch_vccz .LBB0_781
	s_barrier

; #define PG8_WAIT_V(n) asm volatile("s_waitcnt vmcnt(" #n ")" ::: "memory")
; #define PG8_BAR __builtin_amdgcn_s_barrier()
; template <class Epi, class Sched, bool F8 = false>
; __device__ __forceinline__ void gemm_phase(LAS unsigned char* lds, const int lda, const int ldb, const Sched& S, const Epi& E) {
;     ...
;     PG8_WAIT_V(0);
;     PG8_BAR;
.LBB0_797:
	s_waitcnt vmcnt(0)
	v_readlane_b32 s88, v255, 7
	v_readlane_b32 s89, v255, 8
	s_setprio 0
	s_barrier

; #define PG8_STAGE(bufoff, gbase, voff) do { const __amdgpu_buffer_rsrc_t _rs = __builtin_amdgcn_make_buffer_rsrc((void*)(gbase), 0, 0x7fffffff, 0x00020000); _Pragma("unroll") for (int _i = 0; _i < 2; ++_i) \
;         __builtin_amdgcn_raw_ptr_buffer_load_lds(_rs, (LAS unsigned*)(lds + (bufoff) + ldsw + _i * 8192), 16, (int)(voff)[_i], 0, 0, 0); } while (0)
; #define PG8_BAR __builtin_amdgcn_s_barrier()
; template <class Epi, class Sched, bool F8 = false>
; __device__ __forceinline__ void gemm_phase(LAS unsigned char* lds, const int lda, const int ldb, const Sched& S, const Epi& E) {
;     ...
;     for (int i = 0; i < 2; ++i) { int R, C; stage_rc(tid * 16 + i * 8192, R, C); const int Rb = Epi::PERM ? ((R & ~31) + perm32(R & 31)) : R;
;         voffA[i] = (unsigned)(R * lda + C * 2); voffB[i] = (unsigned)(Rb * 128 + C * 2); }
;     ...
;     PG8_STAGE(PG8_SB(0, 0), cB, voffB); PG8_STAGE(PG8_SB(0, 1), cB + hstepB, voffB); PG8_STAGE(PG8_SA(0, 0), cA, voffA); PG8_STAGE(PG8_SA(0, 1), cA + hstepA, voffA);
;     if (wr == 1) PG8_BAR;
.LBB0_923:
	v_bfe_i32 v3, v0, 27, 1
	v_lshlrev_b32_e32 v1, 4, v0
	v_lshrrev_b32_e32 v3, 22, v3
	v_add_u32_e32 v3, v1, v3
	v_and_b32_e32 v3, 0xfffffc00, v3
	v_sub_u32_e32 v3, v1, v3
	v_lshrrev_b32_e32 v4, 4, v3
	v_ashrrev_i32_e32 v2, 31, v0
	v_bitop3_b32 v3, v4, v3, 32 bitop3:0x6c
	v_lshrrev_b32_e32 v2, 26, v2
	v_ashrrev_i32_e32 v5, 31, v3
	v_add_u32_e32 v2, v0, v2
	v_lshrrev_b32_e32 v5, 26, v5
	v_ashrrev_i32_e32 v2, 6, v2
	v_add_u32_e32 v5, v3, v5
	v_lshlrev_b32_e32 v4, 3, v2
	v_ashrrev_i32_e32 v6, 6, v5
	v_and_b32_e32 v5, 0xc0, v5
	v_and_b32_e32 v4, -16, v4
	v_sub_u32_e32 v3, v3, v5
	v_mov_b32_e32 v5, 1
	v_add_u32_e32 v4, v6, v4
	v_lshlrev_b32_e32 v2, 5, v2
	v_ashrrev_i16_sdwa v3, v5, sext(v3) dst_sel:DWORD dst_unused:UNUSED_PAD src0_sel:DWORD src1_sel:BYTE_0
	v_and_b32_e32 v2, 32, v2
	v_bfe_i32 v3, v3, 0, 16
	v_lshlrev_b32_e32 v7, 1, v4
	v_lshrrev_b32_e32 v8, 2, v4
	v_and_b32_e32 v6, 3, v6
	s_mov_b32 s1, 0x1ffffe0
	v_and_b32_e32 v7, 24, v7
	v_and_b32_e32 v8, 4, v8
	v_and_or_b32 v6, v4, s1, v6
	v_add_lshl_u32 v2, v2, v3, 1
	s_movk_i32 s6, 0x5600
	v_or3_b32 v6, v6, v8, v7
	v_mad_u64_u32 v[128:129], s[4:5], v4, s6, v[2:3]
	v_add_u32_e32 v1, 0x2000, v1
	v_lshl_add_u32 v129, v6, 7, v2
	v_ashrrev_i32_e32 v2, 31, v1
	v_lshrrev_b32_e32 v2, 22, v2
	v_add_u32_e32 v2, v1, v2
	v_ashrrev_i32_e32 v2, 10, v2
	v_mul_i32_i24_e32 v3, 0x400, v2
	v_sub_u32_e32 v1, v1, v3
	v_lshrrev_b32_e32 v3, 4, v1
	v_bitop3_b32 v1, v3, v1, 32 bitop3:0x6c
	v_ashrrev_i32_e32 v4, 31, v1
	v_lshrrev_b32_e32 v4, 26, v4
	v_add_u32_e32 v4, v1, v4
	v_ashrrev_i32_e32 v6, 6, v4
	v_and_b32_e32 v4, 0xc0, v4
	v_lshlrev_b32_e32 v3, 3, v2
	v_sub_u32_e32 v1, v1, v4
	s_ashr_i32 s0, s16, 6
	v_and_b32_e32 v3, -16, v3
	v_lshlrev_b32_e32 v2, 5, v2
	v_ashrrev_i16_sdwa v1, v5, sext(v1) dst_sel:DWORD dst_unused:UNUSED_PAD src0_sel:DWORD src1_sel:BYTE_0
	v_add_u32_e32 v3, v6, v3
	v_and_b32_e32 v2, 32, v2
	v_bfe_i32 v1, v1, 0, 16
	s_lshl_b32 s17, s0, 10
	v_lshlrev_b32_e32 v4, 1, v3
	v_lshrrev_b32_e32 v5, 2, v3
	v_and_b32_e32 v6, 3, v6
	v_add_lshl_u32 v2, v2, v1, 1
	s_add_i32 s48, s17, 0
	v_and_b32_e32 v4, 24, v4
	v_and_b32_e32 v5, 4, v5
	v_and_or_b32 v6, v3, s1, v6
	v_mad_u64_u32 v[130:131], s[4:5], v3, s6, v[2:3]
	s_add_i32 s49, s48, 0x10000
	v_or3_b32 v4, v6, v5, v4
	s_and_b32 s5, s15, 0xffff
	s_mov_b32 s7, 0x20000
	s_brev_b32 s6, -2
	s_mov_b32 s4, s14
	s_mov_b32 m0, s49
	s_add_i32 s50, s48, 0x12000
	v_lshl_add_u32 v131, v4, 7, v2
	s_ashr_i32 s1, s16, 8
	buffer_load_dwordx4 v129, s[4:7], 0 offen lds
	s_mov_b32 m0, s50
	s_mov_b32 s67, 0
	buffer_load_dwordx4 v131, s[4:7], 0 offen lds
	s_add_u32 s4, s14, 0x4000
	s_addc_u32 s5, s15, 0
	s_add_i32 s51, s48, 0x14000
	s_and_b32 s5, s5, 0xffff
	s_mov_b32 m0, s51
	s_add_i32 s52, s48, 0x16000
	buffer_load_dwordx4 v129, s[4:7], 0 offen lds
	s_mov_b32 m0, s52
	s_add_i32 s53, s48, 0x2000
	buffer_load_dwordx4 v131, s[4:7], 0 offen lds
	s_and_b32 s5, s13, 0xffff
	s_mov_b32 s4, s12
	s_mov_b32 m0, s48
	s_nop 0
	buffer_load_dwordx4 v128, s[4:7], 0 offen lds
	s_mov_b32 m0, s53
	s_nop 0
	buffer_load_dwordx4 v130, s[4:7], 0 offen lds
	s_add_u32 s4, s12, 0x2b0000
	s_addc_u32 s5, s13, 0
	s_add_i32 s61, s48, 0x4000
	s_and_b32 s5, s5, 0xffff
	s_mov_b32 m0, s61
	s_add_i32 s66, s48, 0x6000
	buffer_load_dwordx4 v128, s[4:7], 0 offen lds
	s_mov_b32 m0, s66
	s_cmp_eq_u32 s1, 1
	buffer_load_dwordx4 v130, s[4:7], 0 offen lds
	s_cselect_b64 s[26:27], -1, 0
	s_cmp_lg_u32 s1, 1
	s_cbranch_scc1 .LBB0_925
	s_setprio 1
	s_barrier

; #define PG8_STAGE(bufoff, gbase, voff) do { const __amdgpu_buffer_rsrc_t _rs = __builtin_amdgcn_make_buffer_rsrc((void*)(gbase), 0, 0x7fffffff, 0x00020000); _Pragma("unroll") for (int _i = 0; _i < 2; ++_i) \
;         __builtin_amdgcn_raw_ptr_buffer_load_lds(_rs, (LAS unsigned*)(lds + (bufoff) + ldsw + _i * 8192), 16, (int)(voff)[_i], 0, 0, 0); } while (0)
; #define PG8_WAIT_V(n) asm volatile("s_waitcnt vmcnt(" #n ")" ::: "memory")
; #define PG8_WAIT_L(n) asm volatile("s_waitcnt lgkmcnt(" #n ")" ::: "memory")
; #define PG8_BAR __builtin_amdgcn_s_barrier()
; #define PG8_SCHED __builtin_amdgcn_sched_barrier(0)
; template <class Epi, class Sched, bool F8 = false>
; __device__ __forceinline__ void gemm_phase(LAS unsigned char* lds, const int lda, const int ldb, const Sched& S, const Epi& E) {
;     ...
;             const char* a1 = cA + (size_t)(t + 1) * kstep;
;             const char* a2 = last ? nA : cA + (size_t)(t + 2) * kstep; const char* b2 = last ? nB : cB + (size_t)(t + 2) * kstepB;
;             const char* a3 = a2 + kstep; const char* b3 = b2 + kstepB;
;     ...
;             PG8_LDB(B0, 0, 0); PG8_LDB(B1, 0, 1); PG8_SCHED; PG8_LDA(At, 0, 0); PG8_STAGE(PG8_SA(1, 1), a1 + hstepA, voffA);
;             PG8_WAIT_V(8); PG8_WAIT_L(0); PG8_BAR; PG8_MMA(0, 0, At, B0); PG8_MMA(0, 1, At, B1); PG8_BAR; PG8_SCHED;
;             PG8_LDA(At, 0, 1); PG8_STAGE(PG8_SB(0, 0), b2, voffB); PG8_STAGE(PG8_SB(0, 1), b2 + hstepB, voffB); PG8_STAGE(PG8_SA(0, 0), a2, voffA);
;             PG8_WAIT_V(8); PG8_WAIT_L(0); PG8_BAR; PG8_MMA(1, 0, At, B0); PG8_MMA(1, 1, At, B1); PG8_BAR; PG8_SCHED;
.LBB0_935:
	ds_read_b128 v[136:139], v142
	ds_read_b128 v[148:151], v142 offset:1024
	ds_read_b128 v[152:155], v142 offset:2048
	ds_read_b128 v[156:159], v142 offset:3072
	ds_read_b128 v[160:163], v143
	ds_read_b128 v[164:167], v143 offset:1024
	ds_read_b128 v[168:171], v143 offset:2048
	ds_read_b128 v[180:183], v143 offset:3072
	s_add_u32 s4, s91, 0xffd50080
	s_addc_u32 s5, s92, -1
	s_cmpk_eq_i32 s64, 0xa8
	s_cselect_b32 s20, s44, s4
	s_cselect_b32 s15, s45, s5
	s_cselect_b32 s14, s47, s90
	s_cselect_b32 s16, s46, s89
	s_add_u32 s12, s20, 0x80
	s_addc_u32 s13, s15, 0
	s_and_b32 s5, s92, 0xffff
	s_mov_b32 s4, s91
	s_mov_b32 m0, s79
	ds_read_b128 v[184:187], v144
	ds_read_b128 v[188:191], v144 offset:1024
	ds_read_b128 v[194:197], v144 offset:2048
	ds_read_b128 v[198:201], v144 offset:3072
	ds_read_b128 v[202:205], v144 offset:4096
	ds_read_b128 v[206:209], v144 offset:5120
	ds_read_b128 v[210:213], v144 offset:6144
	ds_read_b128 v[214:217], v144 offset:7168
	buffer_load_dwordx4 v128, s[4:7], 0 offen lds
	s_mov_b32 m0, s80
	s_nop 0
	buffer_load_dwordx4 v130, s[4:7], 0 offen lds
	s_waitcnt vmcnt(8)
	s_waitcnt lgkmcnt(0)
	s_barrier
	v_mfma_f32_16x16x32_bf16 v[124:127], v[136:139], v[184:187], v[124:127]
	v_mfma_f32_16x16x32_bf16 v[120:123], v[152:155], v[184:187], v[120:123]
	v_mfma_f32_16x16x32_bf16 v[108:111], v[136:139], v[194:197], v[108:111]
	v_mfma_f32_16x16x32_bf16 v[104:107], v[152:155], v[194:197], v[104:107]
	v_mfma_f32_16x16x32_bf16 v[92:95], v[136:139], v[202:205], v[92:95]
	v_mfma_f32_16x16x32_bf16 v[88:91], v[152:155], v[202:205], v[88:91]
	v_mfma_f32_16x16x32_bf16 v[76:79], v[136:139], v[210:213], v[76:79]
	v_mfma_f32_16x16x32_bf16 v[72:75], v[152:155], v[210:213], v[72:75]
	v_mfma_f32_16x16x32_bf16 v[124:127], v[148:151], v[188:191], v[124:127]
	v_mfma_f32_16x16x32_bf16 v[120:123], v[156:159], v[188:191], v[120:123]
	v_mfma_f32_16x16x32_bf16 v[108:111], v[148:151], v[198:201], v[108:111]
	v_mfma_f32_16x16x32_bf16 v[104:107], v[156:159], v[198:201], v[104:107]
	v_mfma_f32_16x16x32_bf16 v[92:95], v[148:151], v[206:209], v[92:95]
	v_mfma_f32_16x16x32_bf16 v[88:91], v[156:159], v[206:209], v[88:91]
	v_mfma_f32_16x16x32_bf16 v[76:79], v[148:151], v[214:217], v[76:79]
	v_mfma_f32_16x16x32_bf16 v[72:75], v[156:159], v[214:217], v[72:75]
	v_mfma_f32_16x16x32_bf16 v[116:119], v[160:163], v[184:187], v[116:119]
	v_mfma_f32_16x16x32_bf16 v[112:115], v[168:171], v[184:187], v[112:115]
	v_mfma_f32_16x16x32_bf16 v[100:103], v[160:163], v[194:197], v[100:103]
	v_mfma_f32_16x16x32_bf16 v[96:99], v[168:171], v[194:197], v[96:99]
	v_mfma_f32_16x16x32_bf16 v[84:87], v[160:163], v[202:205], v[84:87]
	v_mfma_f32_16x16x32_bf16 v[80:83], v[168:171], v[202:205], v[80:83]
	v_mfma_f32_16x16x32_bf16 v[68:71], v[160:163], v[210:213], v[68:71]
	v_mfma_f32_16x16x32_bf16 v[64:67], v[168:171], v[210:213], v[64:67]
	v_mfma_f32_16x16x32_bf16 v[116:119], v[164:167], v[188:191], v[116:119]
	v_mfma_f32_16x16x32_bf16 v[112:115], v[180:183], v[188:191], v[112:115]
	v_mfma_f32_16x16x32_bf16 v[100:103], v[164:167], v[198:201], v[100:103]
	v_mfma_f32_16x16x32_bf16 v[96:99], v[180:183], v[198:201], v[96:99]
	v_mfma_f32_16x16x32_bf16 v[84:87], v[164:167], v[206:209], v[84:87]
	v_mfma_f32_16x16x32_bf16 v[80:83], v[180:183], v[206:209], v[80:83]
	v_mfma_f32_16x16x32_bf16 v[68:71], v[164:167], v[214:217], v[68:71]
	v_mfma_f32_16x16x32_bf16 v[64:67], v[180:183], v[214:217], v[64:67]
	s_barrier
	s_and_b32 s17, s14, 0xffff
	s_mov_b32 m0, s49
	s_mov_b32 s18, s6
	s_mov_b32 s19, s7
	s_add_u32 s4, s16, 0x4000
	ds_read_b128 v[184:187], v144 offset:16384
	ds_read_b128 v[188:191], v144 offset:17408
	ds_read_b128 v[194:197], v144 offset:18432
	ds_read_b128 v[198:201], v144 offset:19456
	ds_read_b128 v[202:205], v144 offset:20480
	ds_read_b128 v[206:209], v144 offset:21504
	ds_read_b128 v[210:213], v144 offset:22528
	ds_read_b128 v[214:217], v144 offset:23552
	buffer_load_dwordx4 v129, s[16:19], 0 offen lds
	s_mov_b32 m0, s50
	s_addc_u32 s5, s14, 0
	buffer_load_dwordx4 v131, s[16:19], 0 offen lds
	s_and_b32 s5, s5, 0xffff
	s_mov_b32 m0, s51
	s_and_b32 s21, s15, 0xffff
	buffer_load_dwordx4 v129, s[4:7], 0 offen lds
	s_mov_b32 m0, s52
	s_mov_b32 s22, s6
	buffer_load_dwordx4 v131, s[4:7], 0 offen lds
	s_mov_b32 s23, s7
	s_mov_b32 m0, s48
	s_nop 0
	buffer_load_dwordx4 v128, s[20:23], 0 offen lds
	s_mov_b32 m0, s53
	s_nop 0
	buffer_load_dwordx4 v130, s[20:23], 0 offen lds
	s_waitcnt vmcnt(8)
	s_waitcnt lgkmcnt(0)
	s_barrier
	v_mfma_f32_16x16x32_bf16 v[60:63], v[136:139], v[184:187], v[60:63]
	v_mfma_f32_16x16x32_bf16 v[56:59], v[152:155], v[184:187], v[56:59]
	v_mfma_f32_16x16x32_bf16 v[44:47], v[136:139], v[194:197], v[44:47]
	v_mfma_f32_16x16x32_bf16 v[40:43], v[152:155], v[194:197], v[40:43]
	v_mfma_f32_16x16x32_bf16 v[28:31], v[136:139], v[202:205], v[28:31]
	v_mfma_f32_16x16x32_bf16 v[24:27], v[152:155], v[202:205], v[24:27]
	v_mfma_f32_16x16x32_bf16 v[12:15], v[136:139], v[210:213], v[12:15]
	v_mfma_f32_16x16x32_bf16 v[8:11], v[152:155], v[210:213], v[8:11]
	v_mfma_f32_16x16x32_bf16 v[60:63], v[148:151], v[188:191], v[60:63]
	v_mfma_f32_16x16x32_bf16 v[56:59], v[156:159], v[188:191], v[56:59]
	v_mfma_f32_16x16x32_bf16 v[44:47], v[148:151], v[198:201], v[44:47]
	v_mfma_f32_16x16x32_bf16 v[40:43], v[156:159], v[198:201], v[40:43]
	v_mfma_f32_16x16x32_bf16 v[28:31], v[148:151], v[206:209], v[28:31]
	v_mfma_f32_16x16x32_bf16 v[24:27], v[156:159], v[206:209], v[24:27]
	v_mfma_f32_16x16x32_bf16 v[12:15], v[148:151], v[214:217], v[12:15]
	v_mfma_f32_16x16x32_bf16 v[8:11], v[156:159], v[214:217], v[8:11]
	v_mfma_f32_16x16x32_bf16 v[52:55], v[160:163], v[184:187], v[52:55]
	v_mfma_f32_16x16x32_bf16 v[48:51], v[168:171], v[184:187], v[48:51]
	v_mfma_f32_16x16x32_bf16 v[36:39], v[160:163], v[194:197], v[36:39]
	v_mfma_f32_16x16x32_bf16 v[32:35], v[168:171], v[194:197], v[32:35]
	v_mfma_f32_16x16x32_bf16 v[20:23], v[160:163], v[202:205], v[20:23]
	v_mfma_f32_16x16x32_bf16 v[16:19], v[168:171], v[202:205], v[16:19]
	v_mfma_f32_16x16x32_bf16 v[4:7], v[160:163], v[210:213], v[4:7]
	v_mfma_f32_16x16x32_bf16 v[0:3], v[168:171], v[210:213], v[0:3]
	v_mfma_f32_16x16x32_bf16 v[52:55], v[164:167], v[188:191], v[52:55]
	v_mfma_f32_16x16x32_bf16 v[48:51], v[180:183], v[188:191], v[48:51]
	v_mfma_f32_16x16x32_bf16 v[36:39], v[164:167], v[198:201], v[36:39]
	v_mfma_f32_16x16x32_bf16 v[32:35], v[180:183], v[198:201], v[32:35]
	v_mfma_f32_16x16x32_bf16 v[20:23], v[164:167], v[206:209], v[20:23]
	v_mfma_f32_16x16x32_bf16 v[16:19], v[180:183], v[206:209], v[16:19]
	v_mfma_f32_16x16x32_bf16 v[4:7], v[164:167], v[214:217], v[4:7]
	v_mfma_f32_16x16x32_bf16 v[0:3], v[180:183], v[214:217], v[0:3]
	s_barrier
; #define PG8_STAGE(bufoff, gbase, voff) do { const __amdgpu_buffer_rsrc_t _rs = __builtin_amdgcn_make_buffer_rsrc((void*)(gbase), 0, 0x7fffffff, 0x00020000); _Pragma("unroll") for (int _i = 0; _i < 2; ++_i) \
;         __builtin_amdgcn_raw_ptr_buffer_load_lds(_rs, (LAS unsigned*)(lds + (bufoff) + ldsw + _i * 8192), 16, (int)(voff)[_i], 0, 0, 0); } while (0)
; #define PG8_WAIT_V(n) asm volatile("s_waitcnt vmcnt(" #n ")" ::: "memory")
; #define PG8_WAIT_L(n) asm volatile("s_waitcnt lgkmcnt(" #n ")" ::: "memory")
; #define PG8_BAR __builtin_amdgcn_s_barrier()
; #define PG8_SCHED __builtin_amdgcn_sched_barrier(0)
; template <class Epi, class Sched, bool F8 = false>
; __device__ __forceinline__ void gemm_phase(LAS unsigned char* lds, const int lda, const int ldb, const Sched& S, const Epi& E) {
;     ...
;             PG8_LDB(B0, 1, 0); PG8_LDB(B1, 1, 1); PG8_SCHED; PG8_LDA(At, 1, 0); PG8_STAGE(PG8_SA(0, 1), a2 + hstepA, voffA);
;             PG8_WAIT_V(8); PG8_WAIT_L(0); PG8_BAR; PG8_MMA(0, 0, At, B0); PG8_MMA(0, 1, At, B1); PG8_BAR; PG8_SCHED;
;             PG8_LDA(At, 1, 1); PG8_STAGE(PG8_SB(1, 0), b3, voffB); PG8_STAGE(PG8_SB(1, 1), b3 + hstepB, voffB); PG8_STAGE(PG8_SA(1, 0), a3, voffA);
;             PG8_WAIT_V(8); PG8_WAIT_L(0); PG8_BAR; PG8_MMA(1, 0, At, B0); PG8_MMA(1, 1, At, B1); PG8_BAR; PG8_SCHED;
	ds_read_b128 v[136:139], v145
	ds_read_b128 v[148:151], v145 offset:1024
	ds_read_b128 v[152:155], v145 offset:2048
	ds_read_b128 v[156:159], v145 offset:3072
	ds_read_b128 v[160:163], v146
	ds_read_b128 v[164:167], v146 offset:1024
	ds_read_b128 v[168:171], v146 offset:2048
	ds_read_b128 v[180:183], v146 offset:3072
	s_add_u32 s4, s20, 0x2b0000
	s_addc_u32 s5, s15, 0
	s_and_b32 s5, s5, 0xffff
	s_mov_b32 m0, s61
	ds_read_b128 v[184:187], v144 offset:32768
	ds_read_b128 v[188:191], v144 offset:33792
	ds_read_b128 v[194:197], v144 offset:34816
	ds_read_b128 v[198:201], v144 offset:35840
	ds_read_b128 v[202:205], v144 offset:36864
	ds_read_b128 v[206:209], v144 offset:37888
	ds_read_b128 v[210:213], v144 offset:38912
	ds_read_b128 v[214:217], v144 offset:39936
	buffer_load_dwordx4 v128, s[4:7], 0 offen lds
	s_mov_b32 m0, s66
	s_nop 0
	buffer_load_dwordx4 v130, s[4:7], 0 offen lds
	s_waitcnt vmcnt(8)
	s_waitcnt lgkmcnt(0)
	s_barrier
	v_mfma_f32_16x16x32_bf16 v[124:127], v[136:139], v[184:187], v[124:127]
	v_mfma_f32_16x16x32_bf16 v[120:123], v[152:155], v[184:187], v[120:123]
	v_mfma_f32_16x16x32_bf16 v[108:111], v[136:139], v[194:197], v[108:111]
	v_mfma_f32_16x16x32_bf16 v[104:107], v[152:155], v[194:197], v[104:107]
	v_mfma_f32_16x16x32_bf16 v[92:95], v[136:139], v[202:205], v[92:95]
	v_mfma_f32_16x16x32_bf16 v[88:91], v[152:155], v[202:205], v[88:91]
	v_mfma_f32_16x16x32_bf16 v[76:79], v[136:139], v[210:213], v[76:79]
	v_mfma_f32_16x16x32_bf16 v[72:75], v[152:155], v[210:213], v[72:75]
	v_mfma_f32_16x16x32_bf16 v[124:127], v[148:151], v[188:191], v[124:127]
	v_mfma_f32_16x16x32_bf16 v[120:123], v[156:159], v[188:191], v[120:123]
	v_mfma_f32_16x16x32_bf16 v[108:111], v[148:151], v[198:201], v[108:111]
	v_mfma_f32_16x16x32_bf16 v[104:107], v[156:159], v[198:201], v[104:107]
	v_mfma_f32_16x16x32_bf16 v[92:95], v[148:151], v[206:209], v[92:95]
	v_mfma_f32_16x16x32_bf16 v[88:91], v[156:159], v[206:209], v[88:91]
	v_mfma_f32_16x16x32_bf16 v[76:79], v[148:151], v[214:217], v[76:79]
	v_mfma_f32_16x16x32_bf16 v[72:75], v[156:159], v[214:217], v[72:75]
	v_mfma_f32_16x16x32_bf16 v[116:119], v[160:163], v[184:187], v[116:119]
	v_mfma_f32_16x16x32_bf16 v[112:115], v[168:171], v[184:187], v[112:115]
	v_mfma_f32_16x16x32_bf16 v[100:103], v[160:163], v[194:197], v[100:103]
	v_mfma_f32_16x16x32_bf16 v[96:99], v[168:171], v[194:197], v[96:99]
	v_mfma_f32_16x16x32_bf16 v[84:87], v[160:163], v[202:205], v[84:87]
	v_mfma_f32_16x16x32_bf16 v[80:83], v[168:171], v[202:205], v[80:83]
	v_mfma_f32_16x16x32_bf16 v[68:71], v[160:163], v[210:213], v[68:71]
	v_mfma_f32_16x16x32_bf16 v[64:67], v[168:171], v[210:213], v[64:67]
	v_mfma_f32_16x16x32_bf16 v[116:119], v[164:167], v[188:191], v[116:119]
	v_mfma_f32_16x16x32_bf16 v[112:115], v[180:183], v[188:191], v[112:115]
	v_mfma_f32_16x16x32_bf16 v[100:103], v[164:167], v[198:201], v[100:103]
	v_mfma_f32_16x16x32_bf16 v[96:99], v[180:183], v[198:201], v[96:99]
	v_mfma_f32_16x16x32_bf16 v[84:87], v[164:167], v[206:209], v[84:87]
	v_mfma_f32_16x16x32_bf16 v[80:83], v[180:183], v[206:209], v[80:83]
	v_mfma_f32_16x16x32_bf16 v[68:71], v[164:167], v[214:217], v[68:71]
	v_mfma_f32_16x16x32_bf16 v[64:67], v[180:183], v[214:217], v[64:67]
	s_barrier
	s_add_u32 s4, s16, 0x8000
	s_addc_u32 s5, s14, 0
	s_mov_b32 m0, s73
	s_and_b32 s5, s5, 0xffff
	ds_read_b128 v[184:187], v144 offset:49152
	ds_read_b128 v[188:191], v144 offset:50176
	ds_read_b128 v[194:197], v144 offset:51200
	ds_read_b128 v[198:201], v144 offset:52224
	ds_read_b128 v[202:205], v144 offset:53248
	ds_read_b128 v[206:209], v144 offset:54272
	ds_read_b128 v[210:213], v144 offset:55296
	ds_read_b128 v[214:217], v144 offset:56320
	buffer_load_dwordx4 v129, s[4:7], 0 offen lds
	s_mov_b32 m0, s74
	s_mov_b32 s15, s7
	buffer_load_dwordx4 v131, s[4:7], 0 offen lds
	s_add_u32 s4, s16, 0xc000
	s_addc_u32 s5, s14, 0
	s_and_b32 s5, s5, 0xffff
	s_mov_b32 m0, s77
	s_and_b32 s13, s13, 0xffff
	buffer_load_dwordx4 v129, s[4:7], 0 offen lds
	s_mov_b32 m0, s78
	s_mov_b32 s14, s6
	buffer_load_dwordx4 v131, s[4:7], 0 offen lds
	s_mov_b32 m0, s75
	s_nop 0
	buffer_load_dwordx4 v128, s[12:15], 0 offen lds
	s_mov_b32 m0, s76
	s_nop 0
	buffer_load_dwordx4 v130, s[12:15], 0 offen lds
	s_waitcnt vmcnt(8)
	s_waitcnt lgkmcnt(0)
	s_barrier
	v_mfma_f32_16x16x32_bf16 v[60:63], v[136:139], v[184:187], v[60:63]
	v_mfma_f32_16x16x32_bf16 v[56:59], v[152:155], v[184:187], v[56:59]
	v_mfma_f32_16x16x32_bf16 v[44:47], v[136:139], v[194:197], v[44:47]
	v_mfma_f32_16x16x32_bf16 v[40:43], v[152:155], v[194:197], v[40:43]
	v_mfma_f32_16x16x32_bf16 v[28:31], v[136:139], v[202:205], v[28:31]
	v_mfma_f32_16x16x32_bf16 v[24:27], v[152:155], v[202:205], v[24:27]
	v_mfma_f32_16x16x32_bf16 v[12:15], v[136:139], v[210:213], v[12:15]
	v_mfma_f32_16x16x32_bf16 v[8:11], v[152:155], v[210:213], v[8:11]
	v_mfma_f32_16x16x32_bf16 v[60:63], v[148:151], v[188:191], v[60:63]
	v_mfma_f32_16x16x32_bf16 v[56:59], v[156:159], v[188:191], v[56:59]
	v_mfma_f32_16x16x32_bf16 v[44:47], v[148:151], v[198:201], v[44:47]
	v_mfma_f32_16x16x32_bf16 v[40:43], v[156:159], v[198:201], v[40:43]
	v_mfma_f32_16x16x32_bf16 v[28:31], v[148:151], v[206:209], v[28:31]
	v_mfma_f32_16x16x32_bf16 v[24:27], v[156:159], v[206:209], v[24:27]
	v_mfma_f32_16x16x32_bf16 v[12:15], v[148:151], v[214:217], v[12:15]
	v_mfma_f32_16x16x32_bf16 v[8:11], v[156:159], v[214:217], v[8:11]
	v_mfma_f32_16x16x32_bf16 v[52:55], v[160:163], v[184:187], v[52:55]
	v_mfma_f32_16x16x32_bf16 v[48:51], v[168:171], v[184:187], v[48:51]
	v_mfma_f32_16x16x32_bf16 v[36:39], v[160:163], v[194:197], v[36:39]
	v_mfma_f32_16x16x32_bf16 v[32:35], v[168:171], v[194:197], v[32:35]
	v_mfma_f32_16x16x32_bf16 v[20:23], v[160:163], v[202:205], v[20:23]
	v_mfma_f32_16x16x32_bf16 v[16:19], v[168:171], v[202:205], v[16:19]
	v_mfma_f32_16x16x32_bf16 v[4:7], v[160:163], v[210:213], v[4:7]
	v_mfma_f32_16x16x32_bf16 v[0:3], v[168:171], v[210:213], v[0:3]
	v_mfma_f32_16x16x32_bf16 v[52:55], v[164:167], v[188:191], v[52:55]
	v_mfma_f32_16x16x32_bf16 v[48:51], v[180:183], v[188:191], v[48:51]
	v_mfma_f32_16x16x32_bf16 v[36:39], v[164:167], v[198:201], v[36:39]
	v_mfma_f32_16x16x32_bf16 v[32:35], v[180:183], v[198:201], v[32:35]
	v_mfma_f32_16x16x32_bf16 v[20:23], v[164:167], v[206:209], v[20:23]
	v_mfma_f32_16x16x32_bf16 v[16:19], v[180:183], v[206:209], v[16:19]
	v_mfma_f32_16x16x32_bf16 v[4:7], v[164:167], v[214:217], v[4:7]
	v_mfma_f32_16x16x32_bf16 v[0:3], v[180:183], v[214:217], v[0:3]
	s_barrier
	s_add_i32 s64, s64, 2
	s_add_u32 s89, s89, 0x10000
	s_addc_u32 s90, s90, 0
	s_add_u32 s91, s91, 0x100
	s_addc_u32 s92, s92, 0
	s_cmpk_gt_u32 s64, 0xa9
	s_cbranch_scc0 .LBB0_935
	s_and_b64 vcc, exec, s[30:31]
	s_cbranch_vccz .LBB0_938
	s_barrier

; #define PG8_WAIT_V(n) asm volatile("s_waitcnt vmcnt(" #n ")" ::: "memory")
; #define PG8_BAR __builtin_amdgcn_s_barrier()
; template <class Epi, class Sched, bool F8 = false>
; __device__ __forceinline__ void gemm_phase(LAS unsigned char* lds, const int lda, const int ldb, const Sched& S, const Epi& E) {
;     ...
;     PG8_WAIT_V(0);
;     PG8_BAR;
.LBB0_957:
	s_waitcnt vmcnt(0)
	s_setprio 0
	s_barrier
